# k=3 OpDec/OpAA epilogues: bias quads loaded once per tile instead of per row group, per-group vmcnt(0) drains removed
# speedup vs baseline: 1.0163x; 1.0114x over previous
; __device__ __forceinline__ u32x4 pack8(f32x4 v0, f32x4 v1) { u32x4 o; o.x = pkbf(v0.x, v0.y); o.y = pkbf(v0.z, v0.w); o.z = pkbf(v1.x, v1.y); o.w = pkbf(v1.z, v1.w); return o; }
;     __device__ __forceinline__ void operator()(int row, int col, f32x4 v0, f32x4 v1) const { *(u32x4*)(G + (size_t)row * 1024 + col) = pack8(v0, v1); }
;     __device__ __forceinline__ void operator()(int row, int col, f32x4 v0, f32x4 v1) const {
;         f32x4 g0, g1; unpack8(*(const u32x4*)(GT + (size_t)row * 3072 + KB * 1024 + col), g0, g1);
;         float* mf = MF + (size_t)row * 1024 + col;
;         f32x4 r0 = g0 * v0, r1 = g1 * v1;
;         if (KB > 0) { r0 += *(const f32x4*)mf; r1 += *(const f32x4*)(mf + 4); }
;         if (KB < 2) { *(f32x4*)mf = r0; *(f32x4*)(mf + 4) = r1; }
;         else *(u32x4*)(MB + (size_t)row * 1024 + col) = pack8(r0, r1);
.LBB0_180:
	v_lshl_or_b32 v140, s94, 8, v163
	v_lshl_add_u32 v142, s95, 8, v161
	v_mov_b64_e32 v[144:145], s[48:49]
	v_ashrrev_i32_e32 v141, 31, v140
	v_mad_i64_i32 v[166:167], s[4:5], v142, s21, v[144:145]
	v_lshlrev_b64 v[146:147], 1, v[140:141]
	v_lshl_add_u64 v[170:171], v[166:167], 0, v[146:147]
	global_load_dwordx4 v[166:169], v[170:171], off
	v_ashrrev_i32_e32 v143, 31, v142
	v_lshlrev_b64 v[174:175], 12, v[142:143]
	v_lshlrev_b64 v[140:141], 2, v[140:141]
	v_lshl_add_u64 v[174:175], s[50:51], 0, v[174:175]
	v_lshl_add_u64 v[174:175], v[174:175], 0, v[140:141]
	s_and_b64 vcc, exec, s[40:41]
	s_waitcnt vmcnt(0)
	v_lshlrev_b32_e32 v176, 16, v166
	v_and_b32_e32 v177, 0xffff0000, v166
	v_lshlrev_b32_e32 v166, 16, v167
	v_and_b32_e32 v167, 0xffff0000, v167
	v_lshlrev_b32_e32 v182, 16, v168
	v_and_b32_e32 v183, 0xffff0000, v168
	v_lshlrev_b32_e32 v168, 16, v169
	v_and_b32_e32 v169, 0xffff0000, v169
	v_pk_mul_f32 v[128:129], v[128:129], v[166:167]
	v_pk_mul_f32 v[126:127], v[126:127], v[176:177]
	v_pk_mul_f32 v[124:125], v[124:125], v[168:169]
	v_pk_mul_f32 v[122:123], v[122:123], v[182:183]
	global_store_dwordx4 v[174:175], v[126:129], off
	global_store_dwordx4 v[174:175], v[122:125], off offset:16
	s_nop 1
	global_load_dwordx4 v[122:125], v[170:171], off offset:256
	v_or_b32_e32 v126, 16, v142
	v_mad_i64_i32 v[128:129], s[4:5], v126, s21, v[144:145]
	v_lshl_add_u64 v[128:129], v[128:129], 0, v[146:147]
	v_ashrrev_i32_e32 v127, 31, v126
	s_waitcnt vmcnt(0)
	v_lshlrev_b32_e32 v166, 16, v122
	v_and_b32_e32 v167, 0xffff0000, v122
	v_lshlrev_b32_e32 v122, 16, v123
	v_and_b32_e32 v123, 0xffff0000, v123
	v_lshlrev_b32_e32 v168, 16, v124
	v_and_b32_e32 v169, 0xffff0000, v124
	v_lshlrev_b32_e32 v124, 16, v125
	v_and_b32_e32 v125, 0xffff0000, v125
	v_pk_mul_f32 v[120:121], v[120:121], v[122:123]
	v_pk_mul_f32 v[118:119], v[118:119], v[166:167]
	v_pk_mul_f32 v[116:117], v[116:117], v[124:125]
	v_pk_mul_f32 v[114:115], v[114:115], v[168:169]
	global_store_dwordx4 v[174:175], v[118:121], off offset:512
	global_store_dwordx4 v[174:175], v[114:117], off offset:528
	s_nop 1
	global_load_dwordx4 v[114:117], v[128:129], off
	v_lshlrev_b64 v[118:119], 12, v[126:127]
	v_lshl_add_u64 v[118:119], s[50:51], 0, v[118:119]
	v_lshl_add_u64 v[118:119], v[118:119], 0, v[140:141]
	s_waitcnt vmcnt(0)
	v_lshlrev_b32_e32 v120, 16, v114
	v_and_b32_e32 v121, 0xffff0000, v114
	v_lshlrev_b32_e32 v114, 16, v115
	v_and_b32_e32 v115, 0xffff0000, v115
	v_lshlrev_b32_e32 v122, 16, v116
	v_and_b32_e32 v123, 0xffff0000, v116
	v_lshlrev_b32_e32 v116, 16, v117
	v_and_b32_e32 v117, 0xffff0000, v117
	v_pk_mul_f32 v[112:113], v[112:113], v[114:115]
	v_pk_mul_f32 v[110:111], v[110:111], v[120:121]
	v_pk_mul_f32 v[108:109], v[108:109], v[116:117]
	v_pk_mul_f32 v[106:107], v[106:107], v[122:123]
	global_store_dwordx4 v[118:119], v[110:113], off
	global_store_dwordx4 v[118:119], v[106:109], off offset:16
	s_nop 1
	global_load_dwordx4 v[106:109], v[128:129], off offset:256
	v_or_b32_e32 v110, 32, v142
	v_mad_i64_i32 v[112:113], s[4:5], v110, s21, v[144:145]
	v_lshl_add_u64 v[112:113], v[112:113], 0, v[146:147]
	v_ashrrev_i32_e32 v111, 31, v110
	s_waitcnt vmcnt(0)
	v_lshlrev_b32_e32 v114, 16, v106
	v_and_b32_e32 v115, 0xffff0000, v106
	v_lshlrev_b32_e32 v106, 16, v107
	v_and_b32_e32 v107, 0xffff0000, v107
	v_lshlrev_b32_e32 v116, 16, v108
	v_and_b32_e32 v117, 0xffff0000, v108
	v_lshlrev_b32_e32 v108, 16, v109
	v_and_b32_e32 v109, 0xffff0000, v109
	v_pk_mul_f32 v[104:105], v[104:105], v[106:107]
	v_pk_mul_f32 v[102:103], v[102:103], v[114:115]
	v_pk_mul_f32 v[100:101], v[100:101], v[108:109]
	v_pk_mul_f32 v[98:99], v[98:99], v[116:117]
	global_store_dwordx4 v[118:119], v[102:105], off offset:512
	global_store_dwordx4 v[118:119], v[98:101], off offset:528
	s_nop 1
	global_load_dwordx4 v[98:101], v[112:113], off
	v_lshlrev_b64 v[102:103], 12, v[110:111]
	v_lshl_add_u64 v[102:103], s[50:51], 0, v[102:103]
	v_lshl_add_u64 v[102:103], v[102:103], 0, v[140:141]
	s_waitcnt vmcnt(0)
	v_lshlrev_b32_e32 v104, 16, v98
	v_and_b32_e32 v105, 0xffff0000, v98
	v_lshlrev_b32_e32 v98, 16, v99
	v_and_b32_e32 v99, 0xffff0000, v99
	v_lshlrev_b32_e32 v106, 16, v100
	v_and_b32_e32 v107, 0xffff0000, v100
	v_lshlrev_b32_e32 v100, 16, v101
	v_and_b32_e32 v101, 0xffff0000, v101
	v_pk_mul_f32 v[96:97], v[96:97], v[98:99]
	v_pk_mul_f32 v[94:95], v[94:95], v[104:105]
	v_pk_mul_f32 v[92:93], v[92:93], v[100:101]
	v_pk_mul_f32 v[90:91], v[90:91], v[106:107]
	global_store_dwordx4 v[102:103], v[94:97], off
	global_store_dwordx4 v[102:103], v[90:93], off offset:16
	s_nop 1
	global_load_dwordx4 v[90:93], v[112:113], off offset:256
	v_or_b32_e32 v94, 48, v142
	v_mad_i64_i32 v[96:97], s[4:5], v94, s21, v[144:145]
	v_lshl_add_u64 v[96:97], v[96:97], 0, v[146:147]
	v_ashrrev_i32_e32 v95, 31, v94
	s_waitcnt vmcnt(0)
	v_lshlrev_b32_e32 v98, 16, v90
	v_and_b32_e32 v99, 0xffff0000, v90
	v_lshlrev_b32_e32 v90, 16, v91
	v_and_b32_e32 v91, 0xffff0000, v91
	v_lshlrev_b32_e32 v100, 16, v92
	v_and_b32_e32 v101, 0xffff0000, v92
	v_lshlrev_b32_e32 v92, 16, v93
	v_and_b32_e32 v93, 0xffff0000, v93
	v_pk_mul_f32 v[88:89], v[88:89], v[90:91]
	v_pk_mul_f32 v[86:87], v[86:87], v[98:99]
	v_pk_mul_f32 v[84:85], v[84:85], v[92:93]
	v_pk_mul_f32 v[82:83], v[82:83], v[100:101]
	global_store_dwordx4 v[102:103], v[86:89], off offset:512
	global_store_dwordx4 v[102:103], v[82:85], off offset:528
	s_nop 1
	global_load_dwordx4 v[82:85], v[96:97], off
	v_lshlrev_b64 v[86:87], 12, v[94:95]
	v_lshl_add_u64 v[86:87], s[50:51], 0, v[86:87]
	v_lshl_add_u64 v[86:87], v[86:87], 0, v[140:141]
	s_waitcnt vmcnt(0)
; __device__ __forceinline__ u32x4 pack8(f32x4 v0, f32x4 v1) { u32x4 o; o.x = pkbf(v0.x, v0.y); o.y = pkbf(v0.z, v0.w); o.z = pkbf(v1.x, v1.y); o.w = pkbf(v1.z, v1.w); return o; }
;     __device__ __forceinline__ void operator()(int row, int col, f32x4 v0, f32x4 v1) const { *(u32x4*)(G + (size_t)row * 1024 + col) = pack8(v0, v1); }
;     __device__ __forceinline__ void operator()(int row, int col, f32x4 v0, f32x4 v1) const {
;         f32x4 g0, g1; unpack8(*(const u32x4*)(GT + (size_t)row * 3072 + KB * 1024 + col), g0, g1);
;         float* mf = MF + (size_t)row * 1024 + col;
;         f32x4 r0 = g0 * v0, r1 = g1 * v1;
;         if (KB > 0) { r0 += *(const f32x4*)mf; r1 += *(const f32x4*)(mf + 4); }
;         if (KB < 2) { *(f32x4*)mf = r0; *(f32x4*)(mf + 4) = r1; }
;         else *(u32x4*)(MB + (size_t)row * 1024 + col) = pack8(r0, r1);
	v_lshlrev_b32_e32 v88, 16, v82
	v_and_b32_e32 v89, 0xffff0000, v82
	v_lshlrev_b32_e32 v82, 16, v83
	v_and_b32_e32 v83, 0xffff0000, v83
	v_lshlrev_b32_e32 v90, 16, v84
	v_and_b32_e32 v91, 0xffff0000, v84
	v_lshlrev_b32_e32 v84, 16, v85
	v_and_b32_e32 v85, 0xffff0000, v85
	v_pk_mul_f32 v[80:81], v[80:81], v[82:83]
	v_pk_mul_f32 v[78:79], v[78:79], v[88:89]
	v_pk_mul_f32 v[76:77], v[76:77], v[84:85]
	v_pk_mul_f32 v[74:75], v[74:75], v[90:91]
	global_store_dwordx4 v[86:87], v[78:81], off
	global_store_dwordx4 v[86:87], v[74:77], off offset:16
	s_nop 1
	global_load_dwordx4 v[74:77], v[96:97], off offset:256
	v_add_u32_e32 v78, 0x80, v142
	v_mad_i64_i32 v[80:81], s[4:5], v78, s21, v[144:145]
	v_lshl_add_u64 v[80:81], v[80:81], 0, v[146:147]
	v_ashrrev_i32_e32 v79, 31, v78
	s_waitcnt vmcnt(0)
	v_lshlrev_b32_e32 v82, 16, v74
	v_and_b32_e32 v83, 0xffff0000, v74
	v_lshlrev_b32_e32 v74, 16, v75
	v_and_b32_e32 v75, 0xffff0000, v75
	v_lshlrev_b32_e32 v84, 16, v76
	v_and_b32_e32 v85, 0xffff0000, v76
	v_lshlrev_b32_e32 v76, 16, v77
	v_and_b32_e32 v77, 0xffff0000, v77
	v_pk_mul_f32 v[72:73], v[72:73], v[74:75]
	v_pk_mul_f32 v[70:71], v[70:71], v[82:83]
	v_pk_mul_f32 v[68:69], v[68:69], v[76:77]
	v_pk_mul_f32 v[66:67], v[66:67], v[84:85]
	global_store_dwordx4 v[86:87], v[70:73], off offset:512
	global_store_dwordx4 v[86:87], v[66:69], off offset:528
	s_nop 1
	global_load_dwordx4 v[66:69], v[80:81], off
	v_lshlrev_b64 v[70:71], 12, v[78:79]
	v_lshl_add_u64 v[70:71], s[50:51], 0, v[70:71]
	v_lshl_add_u64 v[70:71], v[70:71], 0, v[140:141]
	s_waitcnt vmcnt(0)
	v_lshlrev_b32_e32 v72, 16, v66
	v_and_b32_e32 v73, 0xffff0000, v66
	v_lshlrev_b32_e32 v66, 16, v67
	v_and_b32_e32 v67, 0xffff0000, v67
	v_lshlrev_b32_e32 v74, 16, v68
	v_and_b32_e32 v75, 0xffff0000, v68
	v_lshlrev_b32_e32 v68, 16, v69
	v_and_b32_e32 v69, 0xffff0000, v69
	v_pk_mul_f32 v[64:65], v[64:65], v[66:67]
	v_pk_mul_f32 v[62:63], v[62:63], v[72:73]
	v_pk_mul_f32 v[60:61], v[60:61], v[68:69]
	v_pk_mul_f32 v[58:59], v[58:59], v[74:75]
	global_store_dwordx4 v[70:71], v[62:65], off
	global_store_dwordx4 v[70:71], v[58:61], off offset:16
	s_nop 1
	global_load_dwordx4 v[58:61], v[80:81], off offset:256
	v_add_u32_e32 v62, 0x90, v142
	v_mad_i64_i32 v[64:65], s[4:5], v62, s21, v[144:145]
	v_lshl_add_u64 v[64:65], v[64:65], 0, v[146:147]
	v_ashrrev_i32_e32 v63, 31, v62
	s_waitcnt vmcnt(0)
	v_lshlrev_b32_e32 v66, 16, v58
	v_and_b32_e32 v67, 0xffff0000, v58
	v_lshlrev_b32_e32 v58, 16, v59
	v_and_b32_e32 v59, 0xffff0000, v59
	v_lshlrev_b32_e32 v68, 16, v60
	v_and_b32_e32 v69, 0xffff0000, v60
	v_lshlrev_b32_e32 v60, 16, v61
	v_and_b32_e32 v61, 0xffff0000, v61
	v_pk_mul_f32 v[56:57], v[56:57], v[58:59]
	v_pk_mul_f32 v[54:55], v[54:55], v[66:67]
	v_pk_mul_f32 v[52:53], v[52:53], v[60:61]
	v_pk_mul_f32 v[50:51], v[50:51], v[68:69]
	global_store_dwordx4 v[70:71], v[54:57], off offset:512
	global_store_dwordx4 v[70:71], v[50:53], off offset:528
	s_nop 1
	global_load_dwordx4 v[50:53], v[64:65], off
	v_lshlrev_b64 v[54:55], 12, v[62:63]
	v_lshl_add_u64 v[54:55], s[50:51], 0, v[54:55]
	v_lshl_add_u64 v[54:55], v[54:55], 0, v[140:141]
	s_waitcnt vmcnt(0)
	v_lshlrev_b32_e32 v56, 16, v50
	v_and_b32_e32 v57, 0xffff0000, v50
	v_lshlrev_b32_e32 v50, 16, v51
	v_and_b32_e32 v51, 0xffff0000, v51
	v_lshlrev_b32_e32 v58, 16, v52
	v_and_b32_e32 v59, 0xffff0000, v52
	v_lshlrev_b32_e32 v52, 16, v53
	v_and_b32_e32 v53, 0xffff0000, v53
	v_pk_mul_f32 v[48:49], v[48:49], v[50:51]
	v_pk_mul_f32 v[46:47], v[46:47], v[56:57]
	v_pk_mul_f32 v[44:45], v[44:45], v[52:53]
	v_pk_mul_f32 v[42:43], v[42:43], v[58:59]
	global_store_dwordx4 v[54:55], v[46:49], off
	global_store_dwordx4 v[54:55], v[42:45], off offset:16
	s_nop 1
	global_load_dwordx4 v[42:45], v[64:65], off offset:256
	v_add_u32_e32 v46, 0xa0, v142
	v_mad_i64_i32 v[48:49], s[4:5], v46, s21, v[144:145]
	v_lshl_add_u64 v[48:49], v[48:49], 0, v[146:147]
	v_ashrrev_i32_e32 v47, 31, v46
	s_waitcnt vmcnt(0)
; __device__ __forceinline__ u32x4 pack8(f32x4 v0, f32x4 v1) { u32x4 o; o.x = pkbf(v0.x, v0.y); o.y = pkbf(v0.z, v0.w); o.z = pkbf(v1.x, v1.y); o.w = pkbf(v1.z, v1.w); return o; }
;     __device__ __forceinline__ void operator()(int row, int col, f32x4 v0, f32x4 v1) const { *(u32x4*)(G + (size_t)row * 1024 + col) = pack8(v0, v1); }
;     __device__ __forceinline__ void operator()(const pg8::f32x4 (&acc)[2][2][4][2], const pg8::Unit& u, int wr, int wc, int fr, int fq) const {
;     ...
;         for (int ai = 0; ai < 2; ++ai)
; #pragma unroll
;             for (int m = 0; m < 4; ++m)
; #pragma unroll
;                 for (int bj = 0; bj < 2; ++bj) { op(row0 + ai * 128 + m * 16, col0 + bj * 128, acc[ai][bj][m][0], acc[ai][bj][m][1]); asm volatile("" ::: "memory"); }
;     __device__ __forceinline__ void operator()(int row, int col, f32x4 v0, f32x4 v1) const {
;         f32x4 g0, g1; unpack8(*(const u32x4*)(GT + (size_t)row * 3072 + KB * 1024 + col), g0, g1);
;         float* mf = MF + (size_t)row * 1024 + col;
;         f32x4 r0 = g0 * v0, r1 = g1 * v1;
;         if (KB > 0) { r0 += *(const f32x4*)mf; r1 += *(const f32x4*)(mf + 4); }
;         if (KB < 2) { *(f32x4*)mf = r0; *(f32x4*)(mf + 4) = r1; }
;         else *(u32x4*)(MB + (size_t)row * 1024 + col) = pack8(r0, r1);
	v_lshlrev_b32_e32 v50, 16, v42
	v_and_b32_e32 v51, 0xffff0000, v42
	v_lshlrev_b32_e32 v42, 16, v43
	v_and_b32_e32 v43, 0xffff0000, v43
	v_lshlrev_b32_e32 v52, 16, v44
	v_and_b32_e32 v53, 0xffff0000, v44
	v_lshlrev_b32_e32 v44, 16, v45
	v_and_b32_e32 v45, 0xffff0000, v45
	v_pk_mul_f32 v[40:41], v[40:41], v[42:43]
	v_pk_mul_f32 v[38:39], v[38:39], v[50:51]
	v_pk_mul_f32 v[36:37], v[36:37], v[44:45]
	v_pk_mul_f32 v[34:35], v[34:35], v[52:53]
	global_store_dwordx4 v[54:55], v[38:41], off offset:512
	global_store_dwordx4 v[54:55], v[34:37], off offset:528
	s_nop 1
	global_load_dwordx4 v[34:37], v[48:49], off
	v_lshlrev_b64 v[38:39], 12, v[46:47]
	v_lshl_add_u64 v[38:39], s[50:51], 0, v[38:39]
	v_lshl_add_u64 v[38:39], v[38:39], 0, v[140:141]
	s_waitcnt vmcnt(0)
	v_lshlrev_b32_e32 v40, 16, v34
	v_and_b32_e32 v41, 0xffff0000, v34
	v_lshlrev_b32_e32 v34, 16, v35
	v_and_b32_e32 v35, 0xffff0000, v35
	v_lshlrev_b32_e32 v42, 16, v36
	v_and_b32_e32 v43, 0xffff0000, v36
	v_lshlrev_b32_e32 v36, 16, v37
	v_and_b32_e32 v37, 0xffff0000, v37
	v_pk_mul_f32 v[32:33], v[32:33], v[34:35]
	v_pk_mul_f32 v[30:31], v[30:31], v[40:41]
	v_pk_mul_f32 v[28:29], v[28:29], v[36:37]
	v_pk_mul_f32 v[26:27], v[26:27], v[42:43]
	global_store_dwordx4 v[38:39], v[30:33], off
	global_store_dwordx4 v[38:39], v[26:29], off offset:16
	s_nop 1
	global_load_dwordx4 v[26:29], v[48:49], off offset:256
	v_add_u32_e32 v30, 0xb0, v142
	v_mad_i64_i32 v[32:33], s[4:5], v30, s21, v[144:145]
	v_lshl_add_u64 v[32:33], v[32:33], 0, v[146:147]
	v_ashrrev_i32_e32 v31, 31, v30
	s_mov_b64 s[4:5], -1
	s_waitcnt vmcnt(0)
	v_lshlrev_b32_e32 v34, 16, v26
	v_and_b32_e32 v35, 0xffff0000, v26
	v_lshlrev_b32_e32 v26, 16, v27
	v_and_b32_e32 v27, 0xffff0000, v27
	v_lshlrev_b32_e32 v36, 16, v28
	v_and_b32_e32 v37, 0xffff0000, v28
	v_lshlrev_b32_e32 v28, 16, v29
	v_and_b32_e32 v29, 0xffff0000, v29
	v_pk_mul_f32 v[24:25], v[24:25], v[26:27]
	v_pk_mul_f32 v[22:23], v[22:23], v[34:35]
	v_pk_mul_f32 v[20:21], v[20:21], v[28:29]
	v_pk_mul_f32 v[18:19], v[18:19], v[36:37]
	global_store_dwordx4 v[38:39], v[22:25], off offset:512
	global_store_dwordx4 v[38:39], v[18:21], off offset:528
	s_nop 1
	global_load_dwordx4 v[18:21], v[32:33], off
	v_lshlrev_b64 v[22:23], 12, v[30:31]
	v_lshl_add_u64 v[22:23], s[50:51], 0, v[22:23]
	v_lshl_add_u64 v[22:23], v[22:23], 0, v[140:141]
	s_waitcnt vmcnt(0)
	v_lshlrev_b32_e32 v24, 16, v18
	v_and_b32_e32 v25, 0xffff0000, v18
	v_lshlrev_b32_e32 v18, 16, v19
	v_and_b32_e32 v19, 0xffff0000, v19
	v_lshlrev_b32_e32 v26, 16, v20
	v_and_b32_e32 v27, 0xffff0000, v20
	v_lshlrev_b32_e32 v20, 16, v21
	v_and_b32_e32 v21, 0xffff0000, v21
	v_pk_mul_f32 v[16:17], v[16:17], v[18:19]
	v_pk_mul_f32 v[14:15], v[14:15], v[24:25]
	v_pk_mul_f32 v[12:13], v[12:13], v[20:21]
	v_pk_mul_f32 v[10:11], v[10:11], v[26:27]
	global_store_dwordx4 v[22:23], v[14:17], off
	global_store_dwordx4 v[22:23], v[10:13], off offset:16
	s_nop 1
	global_load_dwordx4 v[10:13], v[32:33], off offset:256
	s_waitcnt vmcnt(0)
	v_lshlrev_b32_e32 v14, 16, v10
	v_and_b32_e32 v15, 0xffff0000, v10
	v_lshlrev_b32_e32 v10, 16, v11
	v_and_b32_e32 v11, 0xffff0000, v11
	v_lshlrev_b32_e32 v16, 16, v12
	v_and_b32_e32 v17, 0xffff0000, v12
	v_lshlrev_b32_e32 v12, 16, v13
	v_and_b32_e32 v13, 0xffff0000, v13
	v_pk_mul_f32 v[8:9], v[8:9], v[10:11]
	v_pk_mul_f32 v[6:7], v[6:7], v[14:15]
	v_pk_mul_f32 v[4:5], v[4:5], v[12:13]
	v_pk_mul_f32 v[2:3], v[2:3], v[16:17]
	global_store_dwordx4 v[22:23], v[6:9], off offset:512
	global_store_dwordx4 v[22:23], v[2:5], off offset:528
	s_cbranch_vccnz .LBB0_168
	s_andn2_b64 vcc, exec, s[56:57]
	s_cbranch_vccnz .LBB0_167
	s_barrier
	s_branch .LBB0_167

; __device__ __forceinline__ u32x4 pack8(f32x4 v0, f32x4 v1) { u32x4 o; o.x = pkbf(v0.x, v0.y); o.y = pkbf(v0.z, v0.w); o.z = pkbf(v1.x, v1.y); o.w = pkbf(v1.z, v1.w); return o; }
;     __device__ __forceinline__ void operator()(int row, int col, f32x4 v0, f32x4 v1) const { *(u32x4*)(G + (size_t)row * 1024 + col) = pack8(v0, v1); }
;     __device__ __forceinline__ void operator()(const pg8::f32x4 (&acc)[2][2][4][2], const pg8::Unit& u, int wr, int wc, int fr, int fq) const {
;         const int row0 = u.pm * 256 + wr * 64 + fr, col0 = u.pn * 256 + wc * 32 + 8 * fq;
; #pragma unroll
;         for (int ai = 0; ai < 2; ++ai)
; #pragma unroll
;             for (int m = 0; m < 4; ++m)
; #pragma unroll
;                 for (int bj = 0; bj < 2; ++bj) { op(row0 + ai * 128 + m * 16, col0 + bj * 128, acc[ai][bj][m][0], acc[ai][bj][m][1]); asm volatile("" ::: "memory"); }
;     __device__ __forceinline__ void operator()(int row, int col, f32x4 v0, f32x4 v1) const {
;         f32x4 g0, g1; unpack8(*(const u32x4*)(GT + (size_t)row * 3072 + KB * 1024 + col), g0, g1);
;         float* mf = MF + (size_t)row * 1024 + col;
;         f32x4 r0 = g0 * v0, r1 = g1 * v1;
;         if (KB > 0) { r0 += *(const f32x4*)mf; r1 += *(const f32x4*)(mf + 4); }
;         if (KB < 2) { *(f32x4*)mf = r0; *(f32x4*)(mf + 4) = r1; }
;         else *(u32x4*)(MB + (size_t)row * 1024 + col) = pack8(r0, r1);
.Lmg_w1_done:
	v_lshl_or_b32 v140, s76, 8, v163
	v_lshl_add_u32 v142, s78, 8, v161
	v_mov_b64_e32 v[144:145], s[48:49]
	v_ashrrev_i32_e32 v141, 31, v140
	v_mad_i64_i32 v[166:167], s[4:5], v142, s21, v[144:145]
	v_lshlrev_b64 v[146:147], 1, v[140:141]
	v_ashrrev_i32_e32 v143, 31, v142
	v_lshl_add_u64 v[170:171], v[166:167], 0, v[146:147]
	v_lshlrev_b64 v[174:175], 12, v[142:143]
	global_load_dwordx4 v[166:169], v[170:171], off offset:2048
	v_lshl_add_u64 v[174:175], s[50:51], 0, v[174:175]
	v_lshlrev_b64 v[140:141], 2, v[140:141]
	v_lshl_add_u64 v[174:175], v[174:175], 0, v[140:141]
	global_load_dwordx4 v[182:185], v[174:175], off
	global_load_dwordx4 v[198:201], v[174:175], off offset:16
	s_and_b64 vcc, exec, s[42:43]
	s_waitcnt vmcnt(0)
	v_lshlrev_b32_e32 v176, 16, v166
	v_and_b32_e32 v177, 0xffff0000, v166
	v_lshlrev_b32_e32 v166, 16, v167
	v_and_b32_e32 v167, 0xffff0000, v167
	v_lshlrev_b32_e32 v202, 16, v168
	v_and_b32_e32 v203, 0xffff0000, v168
	v_lshlrev_b32_e32 v168, 16, v169
	v_and_b32_e32 v169, 0xffff0000, v169
	v_pk_fma_f32 v[128:129], v[128:129], v[166:167], v[184:185]
	v_pk_fma_f32 v[126:127], v[126:127], v[176:177], v[182:183]
	v_pk_fma_f32 v[124:125], v[124:125], v[168:169], v[200:201]
	v_pk_fma_f32 v[122:123], v[122:123], v[202:203], v[198:199]
	global_store_dwordx4 v[174:175], v[126:129], off
	global_store_dwordx4 v[174:175], v[122:125], off offset:16
	s_nop 1
	global_load_dwordx4 v[122:125], v[170:171], off offset:2304
	global_load_dwordx4 v[126:129], v[174:175], off offset:512
	global_load_dwordx4 v[166:169], v[174:175], off offset:528
	v_or_b32_e32 v170, 16, v142
	v_mad_i64_i32 v[176:177], s[4:5], v170, s21, v[144:145]
	v_ashrrev_i32_e32 v171, 31, v170
	v_lshl_add_u64 v[176:177], v[176:177], 0, v[146:147]
	s_waitcnt vmcnt(0)
	v_lshlrev_b32_e32 v182, 16, v122
	v_and_b32_e32 v183, 0xffff0000, v122
	v_lshlrev_b32_e32 v122, 16, v123
	v_and_b32_e32 v123, 0xffff0000, v123
	v_lshlrev_b32_e32 v184, 16, v124
	v_and_b32_e32 v185, 0xffff0000, v124
	v_lshlrev_b32_e32 v124, 16, v125
	v_and_b32_e32 v125, 0xffff0000, v125
	v_pk_fma_f32 v[120:121], v[120:121], v[122:123], v[128:129]
	v_pk_fma_f32 v[118:119], v[118:119], v[182:183], v[126:127]
	v_pk_fma_f32 v[116:117], v[116:117], v[124:125], v[168:169]
	v_pk_fma_f32 v[114:115], v[114:115], v[184:185], v[166:167]
	global_store_dwordx4 v[174:175], v[118:121], off offset:512
	global_store_dwordx4 v[174:175], v[114:117], off offset:528
	s_nop 1
	global_load_dwordx4 v[114:117], v[176:177], off offset:2048
	v_lshlrev_b64 v[118:119], 12, v[170:171]
	v_lshl_add_u64 v[118:119], s[50:51], 0, v[118:119]
	v_lshl_add_u64 v[126:127], v[118:119], 0, v[140:141]
	global_load_dwordx4 v[118:121], v[126:127], off
	global_load_dwordx4 v[122:125], v[126:127], off offset:16
	s_waitcnt vmcnt(0)
	v_lshlrev_b32_e32 v128, 16, v114
	v_and_b32_e32 v129, 0xffff0000, v114
	v_lshlrev_b32_e32 v114, 16, v115
	v_and_b32_e32 v115, 0xffff0000, v115
	v_lshlrev_b32_e32 v166, 16, v116
	v_and_b32_e32 v167, 0xffff0000, v116
	v_lshlrev_b32_e32 v116, 16, v117
	v_and_b32_e32 v117, 0xffff0000, v117
	v_pk_fma_f32 v[112:113], v[112:113], v[114:115], v[120:121]
	v_pk_fma_f32 v[110:111], v[110:111], v[128:129], v[118:119]
	v_pk_fma_f32 v[108:109], v[108:109], v[116:117], v[124:125]
	v_pk_fma_f32 v[106:107], v[106:107], v[166:167], v[122:123]
	global_store_dwordx4 v[126:127], v[110:113], off
	global_store_dwordx4 v[126:127], v[106:109], off offset:16
	s_nop 1
	global_load_dwordx4 v[106:109], v[176:177], off offset:2304
	global_load_dwordx4 v[110:113], v[126:127], off offset:512
	global_load_dwordx4 v[114:117], v[126:127], off offset:528
	v_or_b32_e32 v118, 32, v142
	v_mad_i64_i32 v[120:121], s[4:5], v118, s21, v[144:145]
	v_ashrrev_i32_e32 v119, 31, v118
	v_lshl_add_u64 v[120:121], v[120:121], 0, v[146:147]
	s_waitcnt vmcnt(0)
	v_lshlrev_b32_e32 v122, 16, v106
	v_and_b32_e32 v123, 0xffff0000, v106
	v_lshlrev_b32_e32 v106, 16, v107
	v_and_b32_e32 v107, 0xffff0000, v107
	v_lshlrev_b32_e32 v124, 16, v108
	v_and_b32_e32 v125, 0xffff0000, v108
	v_lshlrev_b32_e32 v108, 16, v109
	v_and_b32_e32 v109, 0xffff0000, v109
	v_pk_fma_f32 v[104:105], v[104:105], v[106:107], v[112:113]
	v_pk_fma_f32 v[102:103], v[102:103], v[122:123], v[110:111]
	v_pk_fma_f32 v[100:101], v[100:101], v[108:109], v[116:117]
	v_pk_fma_f32 v[98:99], v[98:99], v[124:125], v[114:115]
	global_store_dwordx4 v[126:127], v[102:105], off offset:512
	global_store_dwordx4 v[126:127], v[98:101], off offset:528
	s_nop 1
	global_load_dwordx4 v[98:101], v[120:121], off offset:2048
	v_lshlrev_b64 v[102:103], 12, v[118:119]
	v_lshl_add_u64 v[102:103], s[50:51], 0, v[102:103]
	v_lshl_add_u64 v[110:111], v[102:103], 0, v[140:141]
	global_load_dwordx4 v[102:105], v[110:111], off
	global_load_dwordx4 v[106:109], v[110:111], off offset:16
	s_waitcnt vmcnt(0)
	v_lshlrev_b32_e32 v112, 16, v98
	v_and_b32_e32 v113, 0xffff0000, v98
	v_lshlrev_b32_e32 v98, 16, v99
	v_and_b32_e32 v99, 0xffff0000, v99
	v_lshlrev_b32_e32 v114, 16, v100
	v_and_b32_e32 v115, 0xffff0000, v100
	v_lshlrev_b32_e32 v100, 16, v101
	v_and_b32_e32 v101, 0xffff0000, v101
	v_pk_fma_f32 v[96:97], v[96:97], v[98:99], v[104:105]
	v_pk_fma_f32 v[94:95], v[94:95], v[112:113], v[102:103]
	v_pk_fma_f32 v[92:93], v[92:93], v[100:101], v[108:109]
	v_pk_fma_f32 v[90:91], v[90:91], v[114:115], v[106:107]
	global_store_dwordx4 v[110:111], v[94:97], off
	global_store_dwordx4 v[110:111], v[90:93], off offset:16
	s_nop 1
	global_load_dwordx4 v[90:93], v[120:121], off offset:2304
	global_load_dwordx4 v[94:97], v[110:111], off offset:512
	global_load_dwordx4 v[98:101], v[110:111], off offset:528
	v_or_b32_e32 v102, 48, v142
	v_mad_i64_i32 v[104:105], s[4:5], v102, s21, v[144:145]
	v_ashrrev_i32_e32 v103, 31, v102
	v_lshl_add_u64 v[104:105], v[104:105], 0, v[146:147]
	s_waitcnt vmcnt(0)
; __device__ __forceinline__ u32x4 pack8(f32x4 v0, f32x4 v1) { u32x4 o; o.x = pkbf(v0.x, v0.y); o.y = pkbf(v0.z, v0.w); o.z = pkbf(v1.x, v1.y); o.w = pkbf(v1.z, v1.w); return o; }
;     __device__ __forceinline__ void operator()(int row, int col, f32x4 v0, f32x4 v1) const { *(u32x4*)(G + (size_t)row * 1024 + col) = pack8(v0, v1); }
;     __device__ __forceinline__ void operator()(const pg8::f32x4 (&acc)[2][2][4][2], const pg8::Unit& u, int wr, int wc, int fr, int fq) const {
;         const int row0 = u.pm * 256 + wr * 64 + fr, col0 = u.pn * 256 + wc * 32 + 8 * fq;
; #pragma unroll
;         for (int ai = 0; ai < 2; ++ai)
; #pragma unroll
;             for (int m = 0; m < 4; ++m)
; #pragma unroll
;                 for (int bj = 0; bj < 2; ++bj) { op(row0 + ai * 128 + m * 16, col0 + bj * 128, acc[ai][bj][m][0], acc[ai][bj][m][1]); asm volatile("" ::: "memory"); }
;     __device__ __forceinline__ void operator()(int row, int col, f32x4 v0, f32x4 v1) const {
;         f32x4 g0, g1; unpack8(*(const u32x4*)(GT + (size_t)row * 3072 + KB * 1024 + col), g0, g1);
;         float* mf = MF + (size_t)row * 1024 + col;
;         f32x4 r0 = g0 * v0, r1 = g1 * v1;
;         if (KB > 0) { r0 += *(const f32x4*)mf; r1 += *(const f32x4*)(mf + 4); }
;         if (KB < 2) { *(f32x4*)mf = r0; *(f32x4*)(mf + 4) = r1; }
;         else *(u32x4*)(MB + (size_t)row * 1024 + col) = pack8(r0, r1);
	v_lshlrev_b32_e32 v106, 16, v90
	v_and_b32_e32 v107, 0xffff0000, v90
	v_lshlrev_b32_e32 v90, 16, v91
	v_and_b32_e32 v91, 0xffff0000, v91
	v_lshlrev_b32_e32 v108, 16, v92
	v_and_b32_e32 v109, 0xffff0000, v92
	v_lshlrev_b32_e32 v92, 16, v93
	v_and_b32_e32 v93, 0xffff0000, v93
	v_pk_fma_f32 v[88:89], v[88:89], v[90:91], v[96:97]
	v_pk_fma_f32 v[86:87], v[86:87], v[106:107], v[94:95]
	v_pk_fma_f32 v[84:85], v[84:85], v[92:93], v[100:101]
	v_pk_fma_f32 v[82:83], v[82:83], v[108:109], v[98:99]
	global_store_dwordx4 v[110:111], v[86:89], off offset:512
	global_store_dwordx4 v[110:111], v[82:85], off offset:528
	s_nop 1
	global_load_dwordx4 v[82:85], v[104:105], off offset:2048
	v_lshlrev_b64 v[86:87], 12, v[102:103]
	v_lshl_add_u64 v[86:87], s[50:51], 0, v[86:87]
	v_lshl_add_u64 v[94:95], v[86:87], 0, v[140:141]
	global_load_dwordx4 v[86:89], v[94:95], off
	global_load_dwordx4 v[90:93], v[94:95], off offset:16
	s_waitcnt vmcnt(0)
	v_lshlrev_b32_e32 v96, 16, v82
	v_and_b32_e32 v97, 0xffff0000, v82
	v_lshlrev_b32_e32 v82, 16, v83
	v_and_b32_e32 v83, 0xffff0000, v83
	v_lshlrev_b32_e32 v98, 16, v84
	v_and_b32_e32 v99, 0xffff0000, v84
	v_lshlrev_b32_e32 v84, 16, v85
	v_and_b32_e32 v85, 0xffff0000, v85
	v_pk_fma_f32 v[80:81], v[80:81], v[82:83], v[88:89]
	v_pk_fma_f32 v[78:79], v[78:79], v[96:97], v[86:87]
	v_pk_fma_f32 v[76:77], v[76:77], v[84:85], v[92:93]
	v_pk_fma_f32 v[74:75], v[74:75], v[98:99], v[90:91]
	global_store_dwordx4 v[94:95], v[78:81], off
	global_store_dwordx4 v[94:95], v[74:77], off offset:16
	s_nop 1
	global_load_dwordx4 v[74:77], v[104:105], off offset:2304
	global_load_dwordx4 v[78:81], v[94:95], off offset:512
	global_load_dwordx4 v[82:85], v[94:95], off offset:528
	v_add_u32_e32 v86, 0x80, v142
	v_mad_i64_i32 v[88:89], s[4:5], v86, s21, v[144:145]
	v_ashrrev_i32_e32 v87, 31, v86
	v_lshl_add_u64 v[88:89], v[88:89], 0, v[146:147]
	s_waitcnt vmcnt(0)
	v_lshlrev_b32_e32 v90, 16, v74
	v_and_b32_e32 v91, 0xffff0000, v74
	v_lshlrev_b32_e32 v74, 16, v75
	v_and_b32_e32 v75, 0xffff0000, v75
	v_lshlrev_b32_e32 v92, 16, v76
	v_and_b32_e32 v93, 0xffff0000, v76
	v_lshlrev_b32_e32 v76, 16, v77
	v_and_b32_e32 v77, 0xffff0000, v77
	v_pk_fma_f32 v[72:73], v[72:73], v[74:75], v[80:81]
	v_pk_fma_f32 v[70:71], v[70:71], v[90:91], v[78:79]
	v_pk_fma_f32 v[68:69], v[68:69], v[76:77], v[84:85]
	v_pk_fma_f32 v[66:67], v[66:67], v[92:93], v[82:83]
	global_store_dwordx4 v[94:95], v[70:73], off offset:512
	global_store_dwordx4 v[94:95], v[66:69], off offset:528
	s_nop 1
	global_load_dwordx4 v[66:69], v[88:89], off offset:2048
	v_lshlrev_b64 v[70:71], 12, v[86:87]
	v_lshl_add_u64 v[70:71], s[50:51], 0, v[70:71]
	v_lshl_add_u64 v[78:79], v[70:71], 0, v[140:141]
	global_load_dwordx4 v[70:73], v[78:79], off
	global_load_dwordx4 v[74:77], v[78:79], off offset:16
	s_waitcnt vmcnt(0)
	v_lshlrev_b32_e32 v80, 16, v66
	v_and_b32_e32 v81, 0xffff0000, v66
	v_lshlrev_b32_e32 v66, 16, v67
	v_and_b32_e32 v67, 0xffff0000, v67
	v_lshlrev_b32_e32 v82, 16, v68
	v_and_b32_e32 v83, 0xffff0000, v68
	v_lshlrev_b32_e32 v68, 16, v69
	v_and_b32_e32 v69, 0xffff0000, v69
	v_pk_fma_f32 v[64:65], v[64:65], v[66:67], v[72:73]
	v_pk_fma_f32 v[62:63], v[62:63], v[80:81], v[70:71]
	v_pk_fma_f32 v[60:61], v[60:61], v[68:69], v[76:77]
	v_pk_fma_f32 v[58:59], v[58:59], v[82:83], v[74:75]
	global_store_dwordx4 v[78:79], v[62:65], off
	global_store_dwordx4 v[78:79], v[58:61], off offset:16
	s_nop 1
	global_load_dwordx4 v[58:61], v[88:89], off offset:2304
	global_load_dwordx4 v[62:65], v[78:79], off offset:512
	global_load_dwordx4 v[66:69], v[78:79], off offset:528
	v_add_u32_e32 v70, 0x90, v142
	v_mad_i64_i32 v[72:73], s[4:5], v70, s21, v[144:145]
	v_ashrrev_i32_e32 v71, 31, v70
	v_lshl_add_u64 v[72:73], v[72:73], 0, v[146:147]
	s_waitcnt vmcnt(0)
	v_lshlrev_b32_e32 v74, 16, v58
	v_and_b32_e32 v75, 0xffff0000, v58
	v_lshlrev_b32_e32 v58, 16, v59
	v_and_b32_e32 v59, 0xffff0000, v59
	v_lshlrev_b32_e32 v76, 16, v60
	v_and_b32_e32 v77, 0xffff0000, v60
	v_lshlrev_b32_e32 v60, 16, v61
	v_and_b32_e32 v61, 0xffff0000, v61
	v_pk_fma_f32 v[56:57], v[56:57], v[58:59], v[64:65]
	v_pk_fma_f32 v[54:55], v[54:55], v[74:75], v[62:63]
	v_pk_fma_f32 v[52:53], v[52:53], v[60:61], v[68:69]
	v_pk_fma_f32 v[50:51], v[50:51], v[76:77], v[66:67]
	global_store_dwordx4 v[78:79], v[54:57], off offset:512
	global_store_dwordx4 v[78:79], v[50:53], off offset:528
	s_nop 1
	global_load_dwordx4 v[50:53], v[72:73], off offset:2048
	v_lshlrev_b64 v[54:55], 12, v[70:71]
	v_lshl_add_u64 v[54:55], s[50:51], 0, v[54:55]
	v_lshl_add_u64 v[62:63], v[54:55], 0, v[140:141]
	global_load_dwordx4 v[54:57], v[62:63], off
	global_load_dwordx4 v[58:61], v[62:63], off offset:16
	s_waitcnt vmcnt(0)
; __device__ __forceinline__ u32x4 pack8(f32x4 v0, f32x4 v1) { u32x4 o; o.x = pkbf(v0.x, v0.y); o.y = pkbf(v0.z, v0.w); o.z = pkbf(v1.x, v1.y); o.w = pkbf(v1.z, v1.w); return o; }
;     __device__ __forceinline__ void operator()(int row, int col, f32x4 v0, f32x4 v1) const { *(u32x4*)(G + (size_t)row * 1024 + col) = pack8(v0, v1); }
;     __device__ __forceinline__ void operator()(const pg8::f32x4 (&acc)[2][2][4][2], const pg8::Unit& u, int wr, int wc, int fr, int fq) const {
;         const int row0 = u.pm * 256 + wr * 64 + fr, col0 = u.pn * 256 + wc * 32 + 8 * fq;
; #pragma unroll
;         for (int ai = 0; ai < 2; ++ai)
; #pragma unroll
;             for (int m = 0; m < 4; ++m)
; #pragma unroll
;                 for (int bj = 0; bj < 2; ++bj) { op(row0 + ai * 128 + m * 16, col0 + bj * 128, acc[ai][bj][m][0], acc[ai][bj][m][1]); asm volatile("" ::: "memory"); }
;     __device__ __forceinline__ void operator()(int row, int col, f32x4 v0, f32x4 v1) const {
;         f32x4 g0, g1; unpack8(*(const u32x4*)(GT + (size_t)row * 3072 + KB * 1024 + col), g0, g1);
;         float* mf = MF + (size_t)row * 1024 + col;
;         f32x4 r0 = g0 * v0, r1 = g1 * v1;
;         if (KB > 0) { r0 += *(const f32x4*)mf; r1 += *(const f32x4*)(mf + 4); }
;         if (KB < 2) { *(f32x4*)mf = r0; *(f32x4*)(mf + 4) = r1; }
;         else *(u32x4*)(MB + (size_t)row * 1024 + col) = pack8(r0, r1);
	v_lshlrev_b32_e32 v64, 16, v50
	v_and_b32_e32 v65, 0xffff0000, v50
	v_lshlrev_b32_e32 v50, 16, v51
	v_and_b32_e32 v51, 0xffff0000, v51
	v_lshlrev_b32_e32 v66, 16, v52
	v_and_b32_e32 v67, 0xffff0000, v52
	v_lshlrev_b32_e32 v52, 16, v53
	v_and_b32_e32 v53, 0xffff0000, v53
	v_pk_fma_f32 v[48:49], v[48:49], v[50:51], v[56:57]
	v_pk_fma_f32 v[46:47], v[46:47], v[64:65], v[54:55]
	v_pk_fma_f32 v[44:45], v[44:45], v[52:53], v[60:61]
	v_pk_fma_f32 v[42:43], v[42:43], v[66:67], v[58:59]
	global_store_dwordx4 v[62:63], v[46:49], off
	global_store_dwordx4 v[62:63], v[42:45], off offset:16
	s_nop 1
	global_load_dwordx4 v[42:45], v[72:73], off offset:2304
	global_load_dwordx4 v[46:49], v[62:63], off offset:512
	global_load_dwordx4 v[50:53], v[62:63], off offset:528
	v_add_u32_e32 v54, 0xa0, v142
	v_mad_i64_i32 v[56:57], s[4:5], v54, s21, v[144:145]
	v_ashrrev_i32_e32 v55, 31, v54
	v_lshl_add_u64 v[56:57], v[56:57], 0, v[146:147]
	s_waitcnt vmcnt(0)
	v_lshlrev_b32_e32 v58, 16, v42
	v_and_b32_e32 v59, 0xffff0000, v42
	v_lshlrev_b32_e32 v42, 16, v43
	v_and_b32_e32 v43, 0xffff0000, v43
	v_lshlrev_b32_e32 v60, 16, v44
	v_and_b32_e32 v61, 0xffff0000, v44
	v_lshlrev_b32_e32 v44, 16, v45
	v_and_b32_e32 v45, 0xffff0000, v45
	v_pk_fma_f32 v[40:41], v[40:41], v[42:43], v[48:49]
	v_pk_fma_f32 v[38:39], v[38:39], v[58:59], v[46:47]
	v_pk_fma_f32 v[36:37], v[36:37], v[44:45], v[52:53]
	v_pk_fma_f32 v[34:35], v[34:35], v[60:61], v[50:51]
	global_store_dwordx4 v[62:63], v[38:41], off offset:512
	global_store_dwordx4 v[62:63], v[34:37], off offset:528
	s_nop 1
	global_load_dwordx4 v[34:37], v[56:57], off offset:2048
	v_lshlrev_b64 v[38:39], 12, v[54:55]
	v_lshl_add_u64 v[38:39], s[50:51], 0, v[38:39]
	v_lshl_add_u64 v[46:47], v[38:39], 0, v[140:141]
	global_load_dwordx4 v[38:41], v[46:47], off
	global_load_dwordx4 v[42:45], v[46:47], off offset:16
	s_waitcnt vmcnt(0)
	v_lshlrev_b32_e32 v48, 16, v34
	v_and_b32_e32 v49, 0xffff0000, v34
	v_lshlrev_b32_e32 v34, 16, v35
	v_and_b32_e32 v35, 0xffff0000, v35
	v_lshlrev_b32_e32 v50, 16, v36
	v_and_b32_e32 v51, 0xffff0000, v36
	v_lshlrev_b32_e32 v36, 16, v37
	v_and_b32_e32 v37, 0xffff0000, v37
	v_pk_fma_f32 v[32:33], v[32:33], v[34:35], v[40:41]
	v_pk_fma_f32 v[30:31], v[30:31], v[48:49], v[38:39]
	v_pk_fma_f32 v[28:29], v[28:29], v[36:37], v[44:45]
	v_pk_fma_f32 v[26:27], v[26:27], v[50:51], v[42:43]
	global_store_dwordx4 v[46:47], v[30:33], off
	global_store_dwordx4 v[46:47], v[26:29], off offset:16
	s_nop 1
	global_load_dwordx4 v[26:29], v[56:57], off offset:2304
	global_load_dwordx4 v[30:33], v[46:47], off offset:512
	global_load_dwordx4 v[34:37], v[46:47], off offset:528
	v_add_u32_e32 v38, 0xb0, v142
	v_mad_i64_i32 v[40:41], s[4:5], v38, s21, v[144:145]
	v_ashrrev_i32_e32 v39, 31, v38
	v_lshl_add_u64 v[40:41], v[40:41], 0, v[146:147]
	s_mov_b64 s[4:5], -1
	s_waitcnt vmcnt(0)
	v_lshlrev_b32_e32 v42, 16, v26
	v_and_b32_e32 v43, 0xffff0000, v26
	v_lshlrev_b32_e32 v26, 16, v27
	v_and_b32_e32 v27, 0xffff0000, v27
	v_lshlrev_b32_e32 v44, 16, v28
	v_and_b32_e32 v45, 0xffff0000, v28
	v_lshlrev_b32_e32 v28, 16, v29
	v_and_b32_e32 v29, 0xffff0000, v29
	v_pk_fma_f32 v[24:25], v[24:25], v[26:27], v[32:33]
	v_pk_fma_f32 v[22:23], v[22:23], v[42:43], v[30:31]
	v_pk_fma_f32 v[20:21], v[20:21], v[28:29], v[36:37]
	v_pk_fma_f32 v[18:19], v[18:19], v[44:45], v[34:35]
	global_store_dwordx4 v[46:47], v[22:25], off offset:512
	global_store_dwordx4 v[46:47], v[18:21], off offset:528
	s_nop 1
	global_load_dwordx4 v[18:21], v[40:41], off offset:2048
	v_lshlrev_b64 v[22:23], 12, v[38:39]
	v_lshl_add_u64 v[22:23], s[50:51], 0, v[22:23]
	v_lshl_add_u64 v[30:31], v[22:23], 0, v[140:141]
	global_load_dwordx4 v[22:25], v[30:31], off
	global_load_dwordx4 v[26:29], v[30:31], off offset:16
	s_waitcnt vmcnt(0)
	v_lshlrev_b32_e32 v32, 16, v18
	v_and_b32_e32 v33, 0xffff0000, v18
	v_lshlrev_b32_e32 v18, 16, v19
	v_and_b32_e32 v19, 0xffff0000, v19
	v_lshlrev_b32_e32 v34, 16, v20
	v_and_b32_e32 v35, 0xffff0000, v20
	v_lshlrev_b32_e32 v20, 16, v21
	v_and_b32_e32 v21, 0xffff0000, v21
	v_pk_fma_f32 v[16:17], v[16:17], v[18:19], v[24:25]
	v_pk_fma_f32 v[14:15], v[14:15], v[32:33], v[22:23]
	v_pk_fma_f32 v[12:13], v[12:13], v[20:21], v[28:29]
	v_pk_fma_f32 v[10:11], v[10:11], v[34:35], v[26:27]
	global_store_dwordx4 v[30:31], v[14:17], off
	global_store_dwordx4 v[30:31], v[10:13], off offset:16
	s_nop 1
	global_load_dwordx4 v[10:13], v[40:41], off offset:2304
	global_load_dwordx4 v[14:17], v[30:31], off offset:512
	global_load_dwordx4 v[18:21], v[30:31], off offset:528
	s_waitcnt vmcnt(0)
	v_lshlrev_b32_e32 v22, 16, v10
	v_and_b32_e32 v23, 0xffff0000, v10
	v_lshlrev_b32_e32 v10, 16, v11
	v_and_b32_e32 v11, 0xffff0000, v11
	v_lshlrev_b32_e32 v24, 16, v12
	v_and_b32_e32 v25, 0xffff0000, v12
	v_lshlrev_b32_e32 v12, 16, v13
	v_and_b32_e32 v13, 0xffff0000, v13
	v_pk_fma_f32 v[8:9], v[8:9], v[10:11], v[16:17]
	v_pk_fma_f32 v[6:7], v[6:7], v[22:23], v[14:15]
	v_pk_fma_f32 v[4:5], v[4:5], v[12:13], v[20:21]
	v_pk_fma_f32 v[2:3], v[2:3], v[24:25], v[18:19]
	global_store_dwordx4 v[30:31], v[6:9], off offset:512
	global_store_dwordx4 v[30:31], v[2:5], off offset:528
	s_cbranch_vccnz .LBB0_189
	s_andn2_b64 vcc, exec, s[56:57]
	s_cbranch_vccnz .LBB0_188
	s_barrier
	s_branch .LBB0_188

; __device__ __forceinline__ u32x4 pack8(f32x4 v0, f32x4 v1) { u32x4 o; o.x = pkbf(v0.x, v0.y); o.y = pkbf(v0.z, v0.w); o.z = pkbf(v1.x, v1.y); o.w = pkbf(v1.z, v1.w); return o; }
;     __device__ __forceinline__ float f(float x) const { return -0.6065306597126334f * sigmoidf_(x); }
;     __device__ __forceinline__ void operator()(int row, int col, f32x4 v0, f32x4 v1) const { *(u32x4*)(G + (size_t)row * 1024 + col) = pack8(v0, v1); }
;     __device__ __forceinline__ void operator()(const pg8::f32x4 (&acc)[2][2][4][2], const pg8::Unit& u, int wr, int wc, int fr, int fq) const {
;         const int row0 = u.pm * 256 + wr * 64 + fr, col0 = u.pn * 256 + wc * 32 + 8 * fq;
; #pragma unroll
;         for (int ai = 0; ai < 2; ++ai)
; #pragma unroll
;             for (int m = 0; m < 4; ++m)
; #pragma unroll
;                 for (int bj = 0; bj < 2; ++bj) { op(row0 + ai * 128 + m * 16, col0 + bj * 128, acc[ai][bj][m][0], acc[ai][bj][m][1]); asm volatile("" ::: "memory"); }
;     __device__ __forceinline__ void operator()(int row, int col, f32x4 v0, f32x4 v1) const {
;         const f32x4 b0 = *(const f32x4*)(w0 + col), b1 = *(const f32x4*)(w0 + col + 4);
;         v0 += b0; v1 += b1;
;         v0 = (f32x4){f(v0.x), f(v0.y), f(v0.z), f(v0.w)}; v1 = (f32x4){f(v1.x), f(v1.y), f(v1.z), f(v1.w)};
;         bf16_t* dst = (col < 1024 ? D0 : D1) + (size_t)row * 1024 + (col & 1023);
;         *(u32x4*)dst = pack8(v0, v1);
.LBB0_384:
	v_lshl_or_b32 v148, s47, 8, v158
	v_ashrrev_i32_e32 v149, 31, v148
	v_lshl_add_u64 v[142:143], v[148:149], 2, s[54:55]
	global_load_dwordx4 v[200:203], v[142:143], off
	global_load_dwordx4 v[204:207], v[142:143], off offset:16
	global_load_dwordx4 v[208:211], v[142:143], off offset:512
	global_load_dwordx4 v[212:215], v[142:143], off offset:528
	v_lshl_add_u32 v146, s27, 8, v152
	v_ashrrev_i32_e32 v147, 31, v146
	v_lshlrev_b64 v[144:145], 11, v[146:147]
	s_waitcnt vmcnt(0)
	v_pk_add_f32 v[122:123], v[122:123], v[204:205]
	v_pk_add_f32 v[150:151], v[126:127], v[200:201]
	v_pk_add_f32 v[126:127], v[124:125], v[206:207]
	v_mul_f32_e32 v0, 0xbfb8aa3b, v150
	v_exp_f32_e32 v124, v0
	v_mul_f32_e32 v0, 0xbfb8aa3b, v151
	v_exp_f32_e32 v125, v0
	v_pk_add_f32 v[128:129], v[128:129], v[202:203]
	v_pk_add_f32 v[124:125], v[124:125], 1.0 op_sel_hi:[1,0]
	s_nop 0
	v_rcp_f32_e32 v147, v125
	s_nop 0
	v_fma_f32 v149, -v125, v147, 1.0
	v_fmac_f32_e32 v147, v149, v147
	v_fma_f32 v151, -v125, v147, 1.0
	v_fma_f32 v150, v151, v147, v147
	v_fma_f32 v0, -v125, v150, 1.0
	v_fma_f32 v0, v0, v147, v150
	v_div_fixup_f32 v125, v0, v125, 1.0
	v_rcp_f32_e32 v147, v124
	s_nop 0
	v_fma_f32 v149, -v124, v147, 1.0
	v_fmac_f32_e32 v147, v149, v147
	v_fma_f32 v151, -v124, v147, 1.0
	v_fma_f32 v150, v151, v147, v147
	v_fma_f32 v0, -v124, v150, 1.0
	v_fma_f32 v0, v0, v147, v150
	v_div_fixup_f32 v124, v0, v124, 1.0
	v_mul_f32_e32 v0, 0xbfb8aa3b, v128
	v_exp_f32_e32 v128, v0
	v_mul_f32_e32 v0, 0xbfb8aa3b, v129
	v_exp_f32_e32 v129, v0
	v_pk_mul_f32 v[124:125], v[124:125], s[20:21] op_sel_hi:[1,0]
	v_pk_add_f32 v[128:129], v[128:129], 1.0 op_sel_hi:[1,0]
	s_nop 0
	v_rcp_f32_e32 v147, v129
	s_nop 0
	v_fma_f32 v149, -v129, v147, 1.0
	v_fmac_f32_e32 v147, v149, v147
	v_fma_f32 v151, -v129, v147, 1.0
	v_fma_f32 v150, v151, v147, v147
	v_fma_f32 v0, -v129, v150, 1.0
	v_fma_f32 v0, v0, v147, v150
	v_div_fixup_f32 v129, v0, v129, 1.0
	v_rcp_f32_e32 v147, v128
	s_nop 0
	v_fma_f32 v149, -v128, v147, 1.0
	v_fmac_f32_e32 v147, v149, v147
	v_fma_f32 v151, -v128, v147, 1.0
	v_fma_f32 v150, v151, v147, v147
	v_fma_f32 v0, -v128, v150, 1.0
	v_fma_f32 v0, v0, v147, v150
	v_div_fixup_f32 v128, v0, v128, 1.0
	v_mul_f32_e32 v0, 0xbfb8aa3b, v122
	v_exp_f32_e32 v122, v0
	v_mul_f32_e32 v0, 0xbfb8aa3b, v123
	v_exp_f32_e32 v123, v0
	v_pk_mul_f32 v[128:129], v[128:129], s[20:21] op_sel_hi:[1,0]
	v_pk_add_f32 v[122:123], v[122:123], 1.0 op_sel_hi:[1,0]
	s_nop 0
	v_rcp_f32_e32 v147, v123
	s_nop 0
	v_fma_f32 v149, -v123, v147, 1.0
	v_fmac_f32_e32 v147, v149, v147
	v_fma_f32 v151, -v123, v147, 1.0
	v_fma_f32 v150, v151, v147, v147
	v_fma_f32 v0, -v123, v150, 1.0
	v_fma_f32 v0, v0, v147, v150
	v_div_fixup_f32 v123, v0, v123, 1.0
	v_rcp_f32_e32 v147, v122
	s_nop 0
	v_fma_f32 v149, -v122, v147, 1.0
	v_fmac_f32_e32 v147, v149, v147
	v_fma_f32 v151, -v122, v147, 1.0
	v_fma_f32 v150, v151, v147, v147
	v_fma_f32 v0, -v122, v150, 1.0
	v_fma_f32 v0, v0, v147, v150
	v_div_fixup_f32 v122, v0, v122, 1.0
	v_mul_f32_e32 v0, 0xbfb8aa3b, v126
	v_pk_mul_f32 v[150:151], v[122:123], s[20:21] op_sel_hi:[1,0]
	v_exp_f32_e32 v122, v0
	v_mul_f32_e32 v0, 0xbfb8aa3b, v127
	v_exp_f32_e32 v123, v0
	v_cvt_pk_bf16_f32 v162, v150, v151
	v_pk_add_f32 v[122:123], v[122:123], 1.0 op_sel_hi:[1,0]
	s_nop 0
	v_rcp_f32_e32 v126, v123
	s_nop 0
	v_fma_f32 v127, -v123, v126, 1.0
	v_fmac_f32_e32 v126, v127, v126
	v_fma_f32 v149, -v123, v126, 1.0
	v_fma_f32 v147, v149, v126, v126
	v_fma_f32 v0, -v123, v147, 1.0
	v_fma_f32 v0, v0, v126, v147
	v_div_fixup_f32 v123, v0, v123, 1.0
	v_rcp_f32_e32 v126, v122
	s_nop 0
	v_fma_f32 v127, -v122, v126, 1.0
	v_fmac_f32_e32 v126, v127, v126
	v_fma_f32 v149, -v122, v126, 1.0
	v_fma_f32 v147, v149, v126, v126
	v_fma_f32 v0, -v122, v147, 1.0
	v_fma_f32 v0, v0, v126, v147
	v_div_fixup_f32 v122, v0, v122, 1.0
	v_cmp_gt_i32_e32 vcc, s66, v148
	v_mov_b32_e32 v126, s72
	v_mov_b32_e32 v127, s39
	v_mov_b32_e32 v147, s62
	v_mov_b32_e32 v149, s18
	v_pk_mul_f32 v[164:165], v[122:123], s[20:21] op_sel_hi:[1,0]
	v_cndmask_b32_e32 v123, v126, v127, vcc
	v_cndmask_b32_e32 v122, v147, v149, vcc
	v_and_b32_e32 v0, 0x378, v148
	v_lshl_add_u64 v[160:161], v[122:123], 0, v[144:145]
	v_lshlrev_b32_e32 v0, 1, v0
	v_lshl_add_u64 v[166:167], v[160:161], 0, v[0:1]
	v_cvt_pk_bf16_f32 v160, v124, v125
	v_cvt_pk_bf16_f32 v161, v128, v129
	v_cvt_pk_bf16_f32 v163, v164, v165
	global_store_dwordx4 v[166:167], v[160:163], off
	v_or_b32_e32 v124, 0x80, v148
	v_pk_add_f32 v[114:115], v[114:115], v[212:213]
	v_pk_add_f32 v[118:119], v[118:119], v[208:209]
	v_pk_add_f32 v[120:121], v[120:121], v[210:211]
	v_mul_f32_e32 v118, 0xbfb8aa3b, v118
	v_mul_f32_e32 v119, 0xbfb8aa3b, v119
	v_exp_f32_e32 v118, v118
	v_exp_f32_e32 v119, v119
	v_mul_f32_e32 v120, 0xbfb8aa3b, v120
	v_mul_f32_e32 v121, 0xbfb8aa3b, v121
	v_exp_f32_e32 v120, v120
	v_pk_add_f32 v[118:119], v[118:119], 1.0 op_sel_hi:[1,0]
	v_exp_f32_e32 v121, v121
	v_rcp_f32_e32 v128, v119
	v_pk_add_f32 v[120:121], v[120:121], 1.0 op_sel_hi:[1,0]
	v_mul_f32_e32 v114, 0xbfb8aa3b, v114
	v_mul_f32_e32 v115, 0xbfb8aa3b, v115
	v_fma_f32 v129, -v119, v128, 1.0
	v_fmac_f32_e32 v128, v129, v128
	v_fma_f32 v151, -v119, v128, 1.0
	v_fma_f32 v150, v151, v128, v128
	v_fma_f32 v125, -v119, v150, 1.0
	v_fma_f32 v125, v125, v128, v150
	v_div_fixup_f32 v119, v125, v119, 1.0
	v_rcp_f32_e32 v128, v118
	v_exp_f32_e32 v114, v114
	v_exp_f32_e32 v115, v115
	v_pk_add_f32 v[116:117], v[116:117], v[214:215]
	v_fma_f32 v129, -v118, v128, 1.0
	v_fmac_f32_e32 v128, v129, v128
	v_fma_f32 v151, -v118, v128, 1.0
	v_fma_f32 v150, v151, v128, v128
	v_fma_f32 v125, -v118, v150, 1.0
	v_fma_f32 v125, v125, v128, v150
; __device__ __forceinline__ u32x4 pack8(f32x4 v0, f32x4 v1) { u32x4 o; o.x = pkbf(v0.x, v0.y); o.y = pkbf(v0.z, v0.w); o.z = pkbf(v1.x, v1.y); o.w = pkbf(v1.z, v1.w); return o; }
;     __device__ __forceinline__ float f(float x) const { return -0.6065306597126334f * sigmoidf_(x); }
;     __device__ __forceinline__ void operator()(int row, int col, f32x4 v0, f32x4 v1) const { *(u32x4*)(G + (size_t)row * 1024 + col) = pack8(v0, v1); }
;     __device__ __forceinline__ void operator()(const pg8::f32x4 (&acc)[2][2][4][2], const pg8::Unit& u, int wr, int wc, int fr, int fq) const {
;         const int row0 = u.pm * 256 + wr * 64 + fr, col0 = u.pn * 256 + wc * 32 + 8 * fq;
; #pragma unroll
;         for (int ai = 0; ai < 2; ++ai)
; #pragma unroll
;             for (int m = 0; m < 4; ++m)
; #pragma unroll
;                 for (int bj = 0; bj < 2; ++bj) { op(row0 + ai * 128 + m * 16, col0 + bj * 128, acc[ai][bj][m][0], acc[ai][bj][m][1]); asm volatile("" ::: "memory"); }
;     __device__ __forceinline__ void operator()(int row, int col, f32x4 v0, f32x4 v1) const {
;         const f32x4 b0 = *(const f32x4*)(w0 + col), b1 = *(const f32x4*)(w0 + col + 4);
;         v0 += b0; v1 += b1;
;         v0 = (f32x4){f(v0.x), f(v0.y), f(v0.z), f(v0.w)}; v1 = (f32x4){f(v1.x), f(v1.y), f(v1.z), f(v1.w)};
;         bf16_t* dst = (col < 1024 ? D0 : D1) + (size_t)row * 1024 + (col & 1023);
;         *(u32x4*)dst = pack8(v0, v1);
	v_div_fixup_f32 v118, v125, v118, 1.0
	v_rcp_f32_e32 v128, v121
	v_pk_add_f32 v[114:115], v[114:115], 1.0 op_sel_hi:[1,0]
	v_pk_mul_f32 v[118:119], v[118:119], s[20:21] op_sel_hi:[1,0]
	v_fma_f32 v129, -v121, v128, 1.0
	v_fmac_f32_e32 v128, v129, v128
	v_fma_f32 v151, -v121, v128, 1.0
	v_fma_f32 v150, v151, v128, v128
	v_fma_f32 v125, -v121, v150, 1.0
	v_fma_f32 v125, v125, v128, v150
	v_div_fixup_f32 v121, v125, v121, 1.0
	v_rcp_f32_e32 v128, v120
	v_cvt_pk_bf16_f32 v118, v118, v119
	v_fma_f32 v129, -v120, v128, 1.0
	v_fmac_f32_e32 v128, v129, v128
	v_fma_f32 v151, -v120, v128, 1.0
	v_fma_f32 v150, v151, v128, v128
	v_fma_f32 v125, -v120, v150, 1.0
	v_fma_f32 v125, v125, v128, v150
	v_div_fixup_f32 v120, v125, v120, 1.0
	v_rcp_f32_e32 v128, v115
	v_pk_mul_f32 v[120:121], v[120:121], s[20:21] op_sel_hi:[1,0]
	v_fma_f32 v129, -v115, v128, 1.0
	v_fmac_f32_e32 v128, v129, v128
	v_fma_f32 v151, -v115, v128, 1.0
	v_fma_f32 v150, v151, v128, v128
	v_fma_f32 v125, -v115, v150, 1.0
	v_fma_f32 v125, v125, v128, v150
	v_div_fixup_f32 v115, v125, v115, 1.0
	v_rcp_f32_e32 v128, v114
	v_cvt_pk_bf16_f32 v119, v120, v121
	v_fma_f32 v129, -v114, v128, 1.0
	v_fmac_f32_e32 v128, v129, v128
	v_fma_f32 v151, -v114, v128, 1.0
	v_fma_f32 v150, v151, v128, v128
	v_fma_f32 v125, -v114, v150, 1.0
	v_fma_f32 v125, v125, v128, v150
	v_div_fixup_f32 v114, v125, v114, 1.0
	v_pk_mul_f32 v[128:129], v[114:115], s[20:21] op_sel_hi:[1,0]
	v_mul_f32_e32 v114, 0xbfb8aa3b, v116
	v_mul_f32_e32 v115, 0xbfb8aa3b, v117
	v_exp_f32_e32 v114, v114
	v_exp_f32_e32 v115, v115
	v_cvt_pk_bf16_f32 v120, v128, v129
	v_pk_add_f32 v[114:115], v[114:115], 1.0 op_sel_hi:[1,0]
	s_nop 0
	v_rcp_f32_e32 v117, v115
	s_nop 0
	v_fma_f32 v125, -v115, v117, 1.0
	v_fmac_f32_e32 v117, v125, v117
	v_fma_f32 v151, -v115, v117, 1.0
	v_fma_f32 v150, v151, v117, v117
	v_fma_f32 v116, -v115, v150, 1.0
	v_fma_f32 v116, v116, v117, v150
	v_div_fixup_f32 v115, v116, v115, 1.0
	v_rcp_f32_e32 v117, v114
	s_nop 0
	v_fma_f32 v125, -v114, v117, 1.0
	v_fmac_f32_e32 v117, v125, v117
	v_fma_f32 v151, -v114, v117, 1.0
	v_fma_f32 v150, v151, v117, v117
	v_fma_f32 v116, -v114, v150, 1.0
	v_fma_f32 v116, v116, v117, v150
	v_div_fixup_f32 v114, v116, v114, 1.0
	v_cmp_gt_i32_e32 vcc, s66, v124
	v_pk_mul_f32 v[150:151], v[114:115], s[20:21] op_sel_hi:[1,0]
	v_bitop3_b32 v116, v148, s86, v192 bitop3:0xc8
	v_cndmask_b32_e32 v115, v126, v127, vcc
	v_cndmask_b32_e32 v114, v147, v149, vcc
	v_lshl_add_u64 v[124:125], v[114:115], 0, v[144:145]
	v_lshlrev_b32_e32 v116, 1, v116
	v_mov_b32_e32 v117, v1
	v_lshl_add_u64 v[124:125], v[124:125], 0, v[116:117]
	v_cvt_pk_bf16_f32 v121, v150, v151
	global_store_dwordx4 v[124:125], v[118:121], off
	s_nop 1
	v_or_b32_e32 v118, 16, v146
	v_ashrrev_i32_e32 v119, 31, v118
	v_lshlrev_b64 v[118:119], 11, v[118:119]
	v_pk_add_f32 v[120:121], v[106:107], v[204:205]
	v_pk_add_f32 v[110:111], v[110:111], v[200:201]
	v_pk_add_f32 v[108:109], v[108:109], v[206:207]
	v_mul_f32_e32 v106, 0xbfb8aa3b, v110
	v_mul_f32_e32 v107, 0xbfb8aa3b, v111
	v_exp_f32_e32 v106, v106
	v_exp_f32_e32 v107, v107
	v_pk_add_f32 v[112:113], v[112:113], v[202:203]
	v_mul_f32_e32 v108, 0xbfb8aa3b, v108
	v_mul_f32_e32 v109, 0xbfb8aa3b, v109
	v_pk_add_f32 v[106:107], v[106:107], 1.0 op_sel_hi:[1,0]
	v_exp_f32_e32 v108, v108
	v_rcp_f32_e32 v111, v107
	v_exp_f32_e32 v109, v109
	v_fma_f32 v124, -v107, v111, 1.0
	v_fmac_f32_e32 v111, v124, v111
	v_fma_f32 v126, -v107, v111, 1.0
	v_fma_f32 v125, v126, v111, v111
	v_fma_f32 v110, -v107, v125, 1.0
	v_fma_f32 v110, v110, v111, v125
	v_div_fixup_f32 v107, v110, v107, 1.0
	v_rcp_f32_e32 v111, v106
	v_pk_add_f32 v[108:109], v[108:109], 1.0 op_sel_hi:[1,0]
	v_fma_f32 v124, -v106, v111, 1.0
	v_fmac_f32_e32 v111, v124, v111
	v_fma_f32 v126, -v106, v111, 1.0
	v_fma_f32 v125, v126, v111, v111
	v_fma_f32 v110, -v106, v125, 1.0
	v_fma_f32 v110, v110, v111, v125
	v_div_fixup_f32 v106, v110, v106, 1.0
	v_mul_f32_e32 v110, 0xbfb8aa3b, v112
	v_mul_f32_e32 v111, 0xbfb8aa3b, v113
	v_exp_f32_e32 v110, v110
	v_exp_f32_e32 v111, v111
	v_pk_mul_f32 v[106:107], v[106:107], s[20:21] op_sel_hi:[1,0]
	v_pk_add_f32 v[110:111], v[110:111], 1.0 op_sel_hi:[1,0]
	s_nop 0
	v_rcp_f32_e32 v113, v111
	v_cvt_pk_bf16_f32 v106, v106, v107
	v_fma_f32 v124, -v111, v113, 1.0
	v_fmac_f32_e32 v113, v124, v113
	v_fma_f32 v126, -v111, v113, 1.0
	v_fma_f32 v125, v126, v113, v113
	v_fma_f32 v112, -v111, v125, 1.0
	v_fma_f32 v112, v112, v113, v125
	v_div_fixup_f32 v111, v112, v111, 1.0
	v_rcp_f32_e32 v113, v110
	s_nop 0
	v_fma_f32 v124, -v110, v113, 1.0
	v_fmac_f32_e32 v113, v124, v113
	v_fma_f32 v126, -v110, v113, 1.0
	v_fma_f32 v125, v126, v113, v113
	v_fma_f32 v112, -v110, v125, 1.0
	v_fma_f32 v112, v112, v113, v125
	v_div_fixup_f32 v110, v112, v110, 1.0
	v_mul_f32_e32 v112, 0xbfb8aa3b, v120
	v_mul_f32_e32 v113, 0xbfb8aa3b, v121
	v_exp_f32_e32 v112, v112
	v_exp_f32_e32 v113, v113
	v_pk_mul_f32 v[110:111], v[110:111], s[20:21] op_sel_hi:[1,0]
	v_pk_add_f32 v[112:113], v[112:113], 1.0 op_sel_hi:[1,0]
	s_nop 0
	v_rcp_f32_e32 v121, v113
	v_cvt_pk_bf16_f32 v107, v110, v111
	v_fma_f32 v124, -v113, v121, 1.0
	v_fmac_f32_e32 v121, v124, v121
	v_fma_f32 v126, -v113, v121, 1.0
	v_fma_f32 v125, v126, v121, v121
	v_fma_f32 v120, -v113, v125, 1.0
	v_fma_f32 v120, v120, v121, v125
	v_div_fixup_f32 v113, v120, v113, 1.0
	v_rcp_f32_e32 v121, v112
	s_nop 0
	v_fma_f32 v124, -v112, v121, 1.0
	v_fmac_f32_e32 v121, v124, v121
	v_fma_f32 v126, -v112, v121, 1.0
	v_fma_f32 v125, v126, v121, v121
	v_fma_f32 v120, -v112, v125, 1.0
	v_fma_f32 v120, v120, v121, v125
	v_div_fixup_f32 v112, v120, v112, 1.0
	v_rcp_f32_e32 v121, v109
; __device__ __forceinline__ u32x4 pack8(f32x4 v0, f32x4 v1) { u32x4 o; o.x = pkbf(v0.x, v0.y); o.y = pkbf(v0.z, v0.w); o.z = pkbf(v1.x, v1.y); o.w = pkbf(v1.z, v1.w); return o; }
;     __device__ __forceinline__ float f(float x) const { return -0.6065306597126334f * sigmoidf_(x); }
;     __device__ __forceinline__ void operator()(int row, int col, f32x4 v0, f32x4 v1) const { *(u32x4*)(G + (size_t)row * 1024 + col) = pack8(v0, v1); }
;     __device__ __forceinline__ void operator()(const pg8::f32x4 (&acc)[2][2][4][2], const pg8::Unit& u, int wr, int wc, int fr, int fq) const {
;         const int row0 = u.pm * 256 + wr * 64 + fr, col0 = u.pn * 256 + wc * 32 + 8 * fq;
; #pragma unroll
;         for (int ai = 0; ai < 2; ++ai)
; #pragma unroll
;             for (int m = 0; m < 4; ++m)
; #pragma unroll
;                 for (int bj = 0; bj < 2; ++bj) { op(row0 + ai * 128 + m * 16, col0 + bj * 128, acc[ai][bj][m][0], acc[ai][bj][m][1]); asm volatile("" ::: "memory"); }
;     __device__ __forceinline__ void operator()(int row, int col, f32x4 v0, f32x4 v1) const {
;         const f32x4 b0 = *(const f32x4*)(w0 + col), b1 = *(const f32x4*)(w0 + col + 4);
;         v0 += b0; v1 += b1;
;         v0 = (f32x4){f(v0.x), f(v0.y), f(v0.z), f(v0.w)}; v1 = (f32x4){f(v1.x), f(v1.y), f(v1.z), f(v1.w)};
;         bf16_t* dst = (col < 1024 ? D0 : D1) + (size_t)row * 1024 + (col & 1023);
;         *(u32x4*)dst = pack8(v0, v1);
	v_pk_mul_f32 v[112:113], v[112:113], s[20:21] op_sel_hi:[1,0]
	v_fma_f32 v124, -v109, v121, 1.0
	v_fmac_f32_e32 v121, v124, v121
	v_fma_f32 v126, -v109, v121, 1.0
	v_fma_f32 v125, v126, v121, v121
	v_fma_f32 v120, -v109, v125, 1.0
	v_fma_f32 v120, v120, v121, v125
	v_div_fixup_f32 v109, v120, v109, 1.0
	v_rcp_f32_e32 v121, v108
	s_nop 0
	v_fma_f32 v124, -v108, v121, 1.0
	v_fmac_f32_e32 v121, v124, v121
	v_fma_f32 v126, -v108, v121, 1.0
	v_fma_f32 v125, v126, v121, v121
	v_fma_f32 v120, -v108, v125, 1.0
	v_fma_f32 v120, v120, v121, v125
	v_div_fixup_f32 v108, v120, v108, 1.0
	v_pk_mul_f32 v[120:121], v[108:109], s[20:21] op_sel_hi:[1,0]
	v_lshl_add_u64 v[108:109], v[122:123], 0, v[118:119]
	v_lshl_add_u64 v[124:125], v[108:109], 0, v[0:1]
	v_cvt_pk_bf16_f32 v108, v112, v113
	v_cvt_pk_bf16_f32 v109, v120, v121
	global_store_dwordx4 v[124:125], v[106:109], off
	s_nop 1
	v_pk_add_f32 v[106:107], v[98:99], v[212:213]
	v_pk_add_f32 v[102:103], v[102:103], v[208:209]
	v_pk_add_f32 v[100:101], v[100:101], v[214:215]
	v_mul_f32_e32 v98, 0xbfb8aa3b, v102
	v_mul_f32_e32 v99, 0xbfb8aa3b, v103
	v_exp_f32_e32 v98, v98
	v_exp_f32_e32 v99, v99
	v_pk_add_f32 v[104:105], v[104:105], v[210:211]
	v_mul_f32_e32 v100, 0xbfb8aa3b, v100
	v_mul_f32_e32 v101, 0xbfb8aa3b, v101
	v_pk_add_f32 v[98:99], v[98:99], 1.0 op_sel_hi:[1,0]
	v_exp_f32_e32 v100, v100
	v_rcp_f32_e32 v103, v99
	v_exp_f32_e32 v101, v101
	v_fma_f32 v108, -v99, v103, 1.0
	v_fmac_f32_e32 v103, v108, v103
	v_fma_f32 v110, -v99, v103, 1.0
	v_fma_f32 v109, v110, v103, v103
	v_fma_f32 v102, -v99, v109, 1.0
	v_fma_f32 v102, v102, v103, v109
	v_div_fixup_f32 v99, v102, v99, 1.0
	v_rcp_f32_e32 v103, v98
	v_pk_add_f32 v[100:101], v[100:101], 1.0 op_sel_hi:[1,0]
	v_fma_f32 v108, -v98, v103, 1.0
	v_fmac_f32_e32 v103, v108, v103
	v_fma_f32 v110, -v98, v103, 1.0
	v_fma_f32 v109, v110, v103, v103
	v_fma_f32 v102, -v98, v109, 1.0
	v_fma_f32 v102, v102, v103, v109
	v_div_fixup_f32 v98, v102, v98, 1.0
	v_mul_f32_e32 v102, 0xbfb8aa3b, v104
	v_mul_f32_e32 v103, 0xbfb8aa3b, v105
	v_exp_f32_e32 v102, v102
	v_exp_f32_e32 v103, v103
	v_pk_mul_f32 v[98:99], v[98:99], s[20:21] op_sel_hi:[1,0]
	v_pk_add_f32 v[102:103], v[102:103], 1.0 op_sel_hi:[1,0]
	s_nop 0
	v_rcp_f32_e32 v105, v103
	v_cvt_pk_bf16_f32 v98, v98, v99
	v_fma_f32 v108, -v103, v105, 1.0
	v_fmac_f32_e32 v105, v108, v105
	v_fma_f32 v110, -v103, v105, 1.0
	v_fma_f32 v109, v110, v105, v105
	v_fma_f32 v104, -v103, v109, 1.0
	v_fma_f32 v104, v104, v105, v109
	v_div_fixup_f32 v103, v104, v103, 1.0
	v_rcp_f32_e32 v105, v102
	s_nop 0
	v_fma_f32 v108, -v102, v105, 1.0
	v_fmac_f32_e32 v105, v108, v105
	v_fma_f32 v110, -v102, v105, 1.0
	v_fma_f32 v109, v110, v105, v105
	v_fma_f32 v104, -v102, v109, 1.0
	v_fma_f32 v104, v104, v105, v109
	v_div_fixup_f32 v102, v104, v102, 1.0
	v_mul_f32_e32 v104, 0xbfb8aa3b, v106
	v_mul_f32_e32 v105, 0xbfb8aa3b, v107
	v_exp_f32_e32 v104, v104
	v_exp_f32_e32 v105, v105
	v_pk_mul_f32 v[102:103], v[102:103], s[20:21] op_sel_hi:[1,0]
	v_pk_add_f32 v[104:105], v[104:105], 1.0 op_sel_hi:[1,0]
	s_nop 0
	v_rcp_f32_e32 v107, v105
	v_cvt_pk_bf16_f32 v99, v102, v103
	v_fma_f32 v108, -v105, v107, 1.0
	v_fmac_f32_e32 v107, v108, v107
	v_fma_f32 v110, -v105, v107, 1.0
	v_fma_f32 v109, v110, v107, v107
	v_fma_f32 v106, -v105, v109, 1.0
	v_fma_f32 v106, v106, v107, v109
	v_div_fixup_f32 v105, v106, v105, 1.0
	v_rcp_f32_e32 v107, v104
	s_nop 0
	v_fma_f32 v108, -v104, v107, 1.0
	v_fmac_f32_e32 v107, v108, v107
	v_fma_f32 v110, -v104, v107, 1.0
	v_fma_f32 v109, v110, v107, v107
	v_fma_f32 v106, -v104, v109, 1.0
	v_fma_f32 v106, v106, v107, v109
	v_div_fixup_f32 v104, v106, v104, 1.0
	v_rcp_f32_e32 v107, v101
	v_pk_mul_f32 v[104:105], v[104:105], s[20:21] op_sel_hi:[1,0]
	v_fma_f32 v108, -v101, v107, 1.0
	v_fmac_f32_e32 v107, v108, v107
	v_fma_f32 v110, -v101, v107, 1.0
	v_fma_f32 v109, v110, v107, v107
	v_fma_f32 v106, -v101, v109, 1.0
	v_fma_f32 v106, v106, v107, v109
	v_div_fixup_f32 v101, v106, v101, 1.0
	v_rcp_f32_e32 v107, v100
	s_nop 0
	v_fma_f32 v108, -v100, v107, 1.0
	v_fmac_f32_e32 v107, v108, v107
	v_fma_f32 v110, -v100, v107, 1.0
	v_fma_f32 v109, v110, v107, v107
	v_fma_f32 v106, -v100, v109, 1.0
	v_fma_f32 v106, v106, v107, v109
	v_div_fixup_f32 v100, v106, v100, 1.0
	v_pk_mul_f32 v[106:107], v[100:101], s[20:21] op_sel_hi:[1,0]
	v_lshl_add_u64 v[100:101], v[114:115], 0, v[118:119]
	v_lshl_add_u64 v[108:109], v[100:101], 0, v[116:117]
	v_cvt_pk_bf16_f32 v100, v104, v105
	v_cvt_pk_bf16_f32 v101, v106, v107
	global_store_dwordx4 v[108:109], v[98:101], off
	s_nop 1
	v_or_b32_e32 v98, 32, v146
	v_ashrrev_i32_e32 v99, 31, v98
	v_lshlrev_b64 v[98:99], 11, v[98:99]
	v_pk_add_f32 v[100:101], v[90:91], v[204:205]
	v_pk_add_f32 v[94:95], v[94:95], v[200:201]
	v_pk_add_f32 v[92:93], v[92:93], v[206:207]
	v_mul_f32_e32 v90, 0xbfb8aa3b, v94
	v_mul_f32_e32 v91, 0xbfb8aa3b, v95
	v_exp_f32_e32 v90, v90
	v_exp_f32_e32 v91, v91
	v_pk_add_f32 v[96:97], v[96:97], v[202:203]
	v_mul_f32_e32 v92, 0xbfb8aa3b, v92
	v_mul_f32_e32 v93, 0xbfb8aa3b, v93
	v_pk_add_f32 v[90:91], v[90:91], 1.0 op_sel_hi:[1,0]
	v_exp_f32_e32 v92, v92
	v_rcp_f32_e32 v95, v91
	v_exp_f32_e32 v93, v93
	v_fma_f32 v102, -v91, v95, 1.0
	v_fmac_f32_e32 v95, v102, v95
	v_fma_f32 v104, -v91, v95, 1.0
	v_fma_f32 v103, v104, v95, v95
	v_fma_f32 v94, -v91, v103, 1.0
	v_fma_f32 v94, v94, v95, v103
	v_div_fixup_f32 v91, v94, v91, 1.0
	v_rcp_f32_e32 v95, v90
	v_pk_add_f32 v[92:93], v[92:93], 1.0 op_sel_hi:[1,0]
	v_fma_f32 v102, -v90, v95, 1.0
	v_fmac_f32_e32 v95, v102, v95
	v_fma_f32 v104, -v90, v95, 1.0
	v_fma_f32 v103, v104, v95, v95
	v_fma_f32 v94, -v90, v103, 1.0
	v_fma_f32 v94, v94, v95, v103
; __device__ __forceinline__ u32x4 pack8(f32x4 v0, f32x4 v1) { u32x4 o; o.x = pkbf(v0.x, v0.y); o.y = pkbf(v0.z, v0.w); o.z = pkbf(v1.x, v1.y); o.w = pkbf(v1.z, v1.w); return o; }
;     __device__ __forceinline__ float f(float x) const { return -0.6065306597126334f * sigmoidf_(x); }
;     __device__ __forceinline__ void operator()(int row, int col, f32x4 v0, f32x4 v1) const { *(u32x4*)(G + (size_t)row * 1024 + col) = pack8(v0, v1); }
;     __device__ __forceinline__ void operator()(const pg8::f32x4 (&acc)[2][2][4][2], const pg8::Unit& u, int wr, int wc, int fr, int fq) const {
;         const int row0 = u.pm * 256 + wr * 64 + fr, col0 = u.pn * 256 + wc * 32 + 8 * fq;
; #pragma unroll
;         for (int ai = 0; ai < 2; ++ai)
; #pragma unroll
;             for (int m = 0; m < 4; ++m)
; #pragma unroll
;                 for (int bj = 0; bj < 2; ++bj) { op(row0 + ai * 128 + m * 16, col0 + bj * 128, acc[ai][bj][m][0], acc[ai][bj][m][1]); asm volatile("" ::: "memory"); }
;     __device__ __forceinline__ void operator()(int row, int col, f32x4 v0, f32x4 v1) const {
;         const f32x4 b0 = *(const f32x4*)(w0 + col), b1 = *(const f32x4*)(w0 + col + 4);
;         v0 += b0; v1 += b1;
;         v0 = (f32x4){f(v0.x), f(v0.y), f(v0.z), f(v0.w)}; v1 = (f32x4){f(v1.x), f(v1.y), f(v1.z), f(v1.w)};
;         bf16_t* dst = (col < 1024 ? D0 : D1) + (size_t)row * 1024 + (col & 1023);
;         *(u32x4*)dst = pack8(v0, v1);
	v_div_fixup_f32 v90, v94, v90, 1.0
	v_mul_f32_e32 v94, 0xbfb8aa3b, v96
	v_mul_f32_e32 v95, 0xbfb8aa3b, v97
	v_exp_f32_e32 v94, v94
	v_exp_f32_e32 v95, v95
	v_pk_mul_f32 v[90:91], v[90:91], s[20:21] op_sel_hi:[1,0]
	v_pk_add_f32 v[94:95], v[94:95], 1.0 op_sel_hi:[1,0]
	s_nop 0
	v_rcp_f32_e32 v97, v95
	v_cvt_pk_bf16_f32 v90, v90, v91
	v_fma_f32 v102, -v95, v97, 1.0
	v_fmac_f32_e32 v97, v102, v97
	v_fma_f32 v104, -v95, v97, 1.0
	v_fma_f32 v103, v104, v97, v97
	v_fma_f32 v96, -v95, v103, 1.0
	v_fma_f32 v96, v96, v97, v103
	v_div_fixup_f32 v95, v96, v95, 1.0
	v_rcp_f32_e32 v97, v94
	s_nop 0
	v_fma_f32 v102, -v94, v97, 1.0
	v_fmac_f32_e32 v97, v102, v97
	v_fma_f32 v104, -v94, v97, 1.0
	v_fma_f32 v103, v104, v97, v97
	v_fma_f32 v96, -v94, v103, 1.0
	v_fma_f32 v96, v96, v97, v103
	v_div_fixup_f32 v94, v96, v94, 1.0
	v_mul_f32_e32 v96, 0xbfb8aa3b, v100
	v_mul_f32_e32 v97, 0xbfb8aa3b, v101
	v_exp_f32_e32 v96, v96
	v_exp_f32_e32 v97, v97
	v_pk_mul_f32 v[94:95], v[94:95], s[20:21] op_sel_hi:[1,0]
	v_pk_add_f32 v[96:97], v[96:97], 1.0 op_sel_hi:[1,0]
	s_nop 0
	v_rcp_f32_e32 v101, v97
	v_cvt_pk_bf16_f32 v91, v94, v95
	v_fma_f32 v102, -v97, v101, 1.0
	v_fmac_f32_e32 v101, v102, v101
	v_fma_f32 v104, -v97, v101, 1.0
	v_fma_f32 v103, v104, v101, v101
	v_fma_f32 v100, -v97, v103, 1.0
	v_fma_f32 v100, v100, v101, v103
	v_div_fixup_f32 v97, v100, v97, 1.0
	v_rcp_f32_e32 v101, v96
	s_nop 0
	v_fma_f32 v102, -v96, v101, 1.0
	v_fmac_f32_e32 v101, v102, v101
	v_fma_f32 v104, -v96, v101, 1.0
	v_fma_f32 v103, v104, v101, v101
	v_fma_f32 v100, -v96, v103, 1.0
	v_fma_f32 v100, v100, v101, v103
	v_div_fixup_f32 v96, v100, v96, 1.0
	v_rcp_f32_e32 v101, v93
	v_pk_mul_f32 v[96:97], v[96:97], s[20:21] op_sel_hi:[1,0]
	v_fma_f32 v102, -v93, v101, 1.0
	v_fmac_f32_e32 v101, v102, v101
	v_fma_f32 v104, -v93, v101, 1.0
	v_fma_f32 v103, v104, v101, v101
	v_fma_f32 v100, -v93, v103, 1.0
	v_fma_f32 v100, v100, v101, v103
	v_div_fixup_f32 v93, v100, v93, 1.0
	v_rcp_f32_e32 v101, v92
	s_nop 0
	v_fma_f32 v102, -v92, v101, 1.0
	v_fmac_f32_e32 v101, v102, v101
	v_fma_f32 v104, -v92, v101, 1.0
	v_fma_f32 v103, v104, v101, v101
	v_fma_f32 v100, -v92, v103, 1.0
	v_fma_f32 v100, v100, v101, v103
	v_div_fixup_f32 v92, v100, v92, 1.0
	v_pk_mul_f32 v[100:101], v[92:93], s[20:21] op_sel_hi:[1,0]
	v_lshl_add_u64 v[92:93], v[122:123], 0, v[98:99]
	v_lshl_add_u64 v[102:103], v[92:93], 0, v[0:1]
	v_cvt_pk_bf16_f32 v92, v96, v97
	v_cvt_pk_bf16_f32 v93, v100, v101
	global_store_dwordx4 v[102:103], v[90:93], off
	s_nop 1
	v_pk_add_f32 v[90:91], v[82:83], v[212:213]
	v_pk_add_f32 v[86:87], v[86:87], v[208:209]
	v_pk_add_f32 v[84:85], v[84:85], v[214:215]
	v_mul_f32_e32 v82, 0xbfb8aa3b, v86
	v_mul_f32_e32 v83, 0xbfb8aa3b, v87
	v_exp_f32_e32 v82, v82
	v_exp_f32_e32 v83, v83
	v_pk_add_f32 v[88:89], v[88:89], v[210:211]
	v_mul_f32_e32 v84, 0xbfb8aa3b, v84
	v_mul_f32_e32 v85, 0xbfb8aa3b, v85
	v_pk_add_f32 v[82:83], v[82:83], 1.0 op_sel_hi:[1,0]
	v_exp_f32_e32 v84, v84
	v_rcp_f32_e32 v87, v83
	v_exp_f32_e32 v85, v85
	v_fma_f32 v92, -v83, v87, 1.0
	v_fmac_f32_e32 v87, v92, v87
	v_fma_f32 v94, -v83, v87, 1.0
	v_fma_f32 v93, v94, v87, v87
	v_fma_f32 v86, -v83, v93, 1.0
	v_fma_f32 v86, v86, v87, v93
	v_div_fixup_f32 v83, v86, v83, 1.0
	v_rcp_f32_e32 v87, v82
	v_pk_add_f32 v[84:85], v[84:85], 1.0 op_sel_hi:[1,0]
	v_fma_f32 v92, -v82, v87, 1.0
	v_fmac_f32_e32 v87, v92, v87
	v_fma_f32 v94, -v82, v87, 1.0
	v_fma_f32 v93, v94, v87, v87
	v_fma_f32 v86, -v82, v93, 1.0
	v_fma_f32 v86, v86, v87, v93
	v_div_fixup_f32 v82, v86, v82, 1.0
	v_mul_f32_e32 v86, 0xbfb8aa3b, v88
	v_mul_f32_e32 v87, 0xbfb8aa3b, v89
	v_exp_f32_e32 v86, v86
	v_exp_f32_e32 v87, v87
	v_pk_mul_f32 v[82:83], v[82:83], s[20:21] op_sel_hi:[1,0]
	v_pk_add_f32 v[86:87], v[86:87], 1.0 op_sel_hi:[1,0]
	s_nop 0
	v_rcp_f32_e32 v89, v87
	v_cvt_pk_bf16_f32 v82, v82, v83
	v_fma_f32 v92, -v87, v89, 1.0
	v_fmac_f32_e32 v89, v92, v89
	v_fma_f32 v94, -v87, v89, 1.0
	v_fma_f32 v93, v94, v89, v89
	v_fma_f32 v88, -v87, v93, 1.0
	v_fma_f32 v88, v88, v89, v93
	v_div_fixup_f32 v87, v88, v87, 1.0
	v_rcp_f32_e32 v89, v86
	s_nop 0
	v_fma_f32 v92, -v86, v89, 1.0
	v_fmac_f32_e32 v89, v92, v89
	v_fma_f32 v94, -v86, v89, 1.0
	v_fma_f32 v93, v94, v89, v89
	v_fma_f32 v88, -v86, v93, 1.0
	v_fma_f32 v88, v88, v89, v93
	v_div_fixup_f32 v86, v88, v86, 1.0
	v_mul_f32_e32 v88, 0xbfb8aa3b, v90
	v_mul_f32_e32 v89, 0xbfb8aa3b, v91
	v_exp_f32_e32 v88, v88
	v_exp_f32_e32 v89, v89
	v_pk_mul_f32 v[86:87], v[86:87], s[20:21] op_sel_hi:[1,0]
	v_pk_add_f32 v[88:89], v[88:89], 1.0 op_sel_hi:[1,0]
	s_nop 0
	v_rcp_f32_e32 v91, v89
	v_cvt_pk_bf16_f32 v83, v86, v87
	v_fma_f32 v92, -v89, v91, 1.0
	v_fmac_f32_e32 v91, v92, v91
	v_fma_f32 v94, -v89, v91, 1.0
	v_fma_f32 v93, v94, v91, v91
	v_fma_f32 v90, -v89, v93, 1.0
	v_fma_f32 v90, v90, v91, v93
	v_div_fixup_f32 v89, v90, v89, 1.0
	v_rcp_f32_e32 v91, v88
	s_nop 0
	v_fma_f32 v92, -v88, v91, 1.0
	v_fmac_f32_e32 v91, v92, v91
	v_fma_f32 v94, -v88, v91, 1.0
	v_fma_f32 v93, v94, v91, v91
	v_fma_f32 v90, -v88, v93, 1.0
	v_fma_f32 v90, v90, v91, v93
	v_div_fixup_f32 v88, v90, v88, 1.0
	v_rcp_f32_e32 v91, v85
	v_pk_mul_f32 v[88:89], v[88:89], s[20:21] op_sel_hi:[1,0]
	v_fma_f32 v92, -v85, v91, 1.0
	v_fmac_f32_e32 v91, v92, v91
	v_fma_f32 v94, -v85, v91, 1.0
	v_fma_f32 v93, v94, v91, v91
	v_fma_f32 v90, -v85, v93, 1.0
	v_fma_f32 v90, v90, v91, v93
	v_div_fixup_f32 v85, v90, v85, 1.0
	v_rcp_f32_e32 v91, v84
	s_nop 0
	v_fma_f32 v92, -v84, v91, 1.0
	v_fmac_f32_e32 v91, v92, v91
	v_fma_f32 v94, -v84, v91, 1.0
	v_fma_f32 v93, v94, v91, v91
	v_fma_f32 v90, -v84, v93, 1.0
	v_fma_f32 v90, v90, v91, v93
	v_div_fixup_f32 v84, v90, v84, 1.0
; __device__ __forceinline__ u32x4 pack8(f32x4 v0, f32x4 v1) { u32x4 o; o.x = pkbf(v0.x, v0.y); o.y = pkbf(v0.z, v0.w); o.z = pkbf(v1.x, v1.y); o.w = pkbf(v1.z, v1.w); return o; }
;     __device__ __forceinline__ float f(float x) const { return -0.6065306597126334f * sigmoidf_(x); }
;     __device__ __forceinline__ void operator()(int row, int col, f32x4 v0, f32x4 v1) const { *(u32x4*)(G + (size_t)row * 1024 + col) = pack8(v0, v1); }
;     __device__ __forceinline__ void operator()(const pg8::f32x4 (&acc)[2][2][4][2], const pg8::Unit& u, int wr, int wc, int fr, int fq) const {
;         const int row0 = u.pm * 256 + wr * 64 + fr, col0 = u.pn * 256 + wc * 32 + 8 * fq;
; #pragma unroll
;         for (int ai = 0; ai < 2; ++ai)
; #pragma unroll
;             for (int m = 0; m < 4; ++m)
; #pragma unroll
;                 for (int bj = 0; bj < 2; ++bj) { op(row0 + ai * 128 + m * 16, col0 + bj * 128, acc[ai][bj][m][0], acc[ai][bj][m][1]); asm volatile("" ::: "memory"); }
;     __device__ __forceinline__ void operator()(int row, int col, f32x4 v0, f32x4 v1) const {
;         const f32x4 b0 = *(const f32x4*)(w0 + col), b1 = *(const f32x4*)(w0 + col + 4);
;         v0 += b0; v1 += b1;
;         v0 = (f32x4){f(v0.x), f(v0.y), f(v0.z), f(v0.w)}; v1 = (f32x4){f(v1.x), f(v1.y), f(v1.z), f(v1.w)};
;         bf16_t* dst = (col < 1024 ? D0 : D1) + (size_t)row * 1024 + (col & 1023);
;         *(u32x4*)dst = pack8(v0, v1);
	v_pk_mul_f32 v[90:91], v[84:85], s[20:21] op_sel_hi:[1,0]
	v_lshl_add_u64 v[84:85], v[114:115], 0, v[98:99]
	v_lshl_add_u64 v[92:93], v[84:85], 0, v[116:117]
	v_cvt_pk_bf16_f32 v84, v88, v89
	v_cvt_pk_bf16_f32 v85, v90, v91
	global_store_dwordx4 v[92:93], v[82:85], off
	s_nop 1
	v_or_b32_e32 v82, 48, v146
	v_ashrrev_i32_e32 v83, 31, v82
	v_lshlrev_b64 v[82:83], 11, v[82:83]
	v_pk_add_f32 v[84:85], v[74:75], v[204:205]
	v_pk_add_f32 v[78:79], v[78:79], v[200:201]
	v_pk_add_f32 v[76:77], v[76:77], v[206:207]
	v_mul_f32_e32 v74, 0xbfb8aa3b, v78
	v_mul_f32_e32 v75, 0xbfb8aa3b, v79
	v_exp_f32_e32 v74, v74
	v_exp_f32_e32 v75, v75
	v_pk_add_f32 v[80:81], v[80:81], v[202:203]
	v_mul_f32_e32 v76, 0xbfb8aa3b, v76
	v_mul_f32_e32 v77, 0xbfb8aa3b, v77
	v_pk_add_f32 v[74:75], v[74:75], 1.0 op_sel_hi:[1,0]
	v_exp_f32_e32 v76, v76
	v_rcp_f32_e32 v79, v75
	v_exp_f32_e32 v77, v77
	v_fma_f32 v86, -v75, v79, 1.0
	v_fmac_f32_e32 v79, v86, v79
	v_fma_f32 v88, -v75, v79, 1.0
	v_fma_f32 v87, v88, v79, v79
	v_fma_f32 v78, -v75, v87, 1.0
	v_fma_f32 v78, v78, v79, v87
	v_div_fixup_f32 v75, v78, v75, 1.0
	v_rcp_f32_e32 v79, v74
	v_pk_add_f32 v[76:77], v[76:77], 1.0 op_sel_hi:[1,0]
	v_fma_f32 v86, -v74, v79, 1.0
	v_fmac_f32_e32 v79, v86, v79
	v_fma_f32 v88, -v74, v79, 1.0
	v_fma_f32 v87, v88, v79, v79
	v_fma_f32 v78, -v74, v87, 1.0
	v_fma_f32 v78, v78, v79, v87
	v_div_fixup_f32 v74, v78, v74, 1.0
	v_mul_f32_e32 v78, 0xbfb8aa3b, v80
	v_mul_f32_e32 v79, 0xbfb8aa3b, v81
	v_exp_f32_e32 v78, v78
	v_exp_f32_e32 v79, v79
	v_pk_mul_f32 v[74:75], v[74:75], s[20:21] op_sel_hi:[1,0]
	v_pk_add_f32 v[78:79], v[78:79], 1.0 op_sel_hi:[1,0]
	s_nop 0
	v_rcp_f32_e32 v81, v79
	v_cvt_pk_bf16_f32 v74, v74, v75
	v_fma_f32 v86, -v79, v81, 1.0
	v_fmac_f32_e32 v81, v86, v81
	v_fma_f32 v88, -v79, v81, 1.0
	v_fma_f32 v87, v88, v81, v81
	v_fma_f32 v80, -v79, v87, 1.0
	v_fma_f32 v80, v80, v81, v87
	v_div_fixup_f32 v79, v80, v79, 1.0
	v_rcp_f32_e32 v81, v78
	s_nop 0
	v_fma_f32 v86, -v78, v81, 1.0
	v_fmac_f32_e32 v81, v86, v81
	v_fma_f32 v88, -v78, v81, 1.0
	v_fma_f32 v87, v88, v81, v81
	v_fma_f32 v80, -v78, v87, 1.0
	v_fma_f32 v80, v80, v81, v87
	v_div_fixup_f32 v78, v80, v78, 1.0
	v_mul_f32_e32 v80, 0xbfb8aa3b, v84
	v_mul_f32_e32 v81, 0xbfb8aa3b, v85
	v_exp_f32_e32 v80, v80
	v_exp_f32_e32 v81, v81
	v_pk_mul_f32 v[78:79], v[78:79], s[20:21] op_sel_hi:[1,0]
	v_pk_add_f32 v[80:81], v[80:81], 1.0 op_sel_hi:[1,0]
	s_nop 0
	v_rcp_f32_e32 v85, v81
	v_cvt_pk_bf16_f32 v75, v78, v79
	v_fma_f32 v86, -v81, v85, 1.0
	v_fmac_f32_e32 v85, v86, v85
	v_fma_f32 v88, -v81, v85, 1.0
	v_fma_f32 v87, v88, v85, v85
	v_fma_f32 v84, -v81, v87, 1.0
	v_fma_f32 v84, v84, v85, v87
	v_div_fixup_f32 v81, v84, v81, 1.0
	v_rcp_f32_e32 v85, v80
	s_nop 0
	v_fma_f32 v86, -v80, v85, 1.0
	v_fmac_f32_e32 v85, v86, v85
	v_fma_f32 v88, -v80, v85, 1.0
	v_fma_f32 v87, v88, v85, v85
	v_fma_f32 v84, -v80, v87, 1.0
	v_fma_f32 v84, v84, v85, v87
	v_div_fixup_f32 v80, v84, v80, 1.0
	v_rcp_f32_e32 v85, v77
	v_pk_mul_f32 v[80:81], v[80:81], s[20:21] op_sel_hi:[1,0]
	v_fma_f32 v86, -v77, v85, 1.0
	v_fmac_f32_e32 v85, v86, v85
	v_fma_f32 v88, -v77, v85, 1.0
	v_fma_f32 v87, v88, v85, v85
	v_fma_f32 v84, -v77, v87, 1.0
	v_fma_f32 v84, v84, v85, v87
	v_div_fixup_f32 v77, v84, v77, 1.0
	v_rcp_f32_e32 v85, v76
	s_nop 0
	v_fma_f32 v86, -v76, v85, 1.0
	v_fmac_f32_e32 v85, v86, v85
	v_fma_f32 v88, -v76, v85, 1.0
	v_fma_f32 v87, v88, v85, v85
	v_fma_f32 v84, -v76, v87, 1.0
	v_fma_f32 v84, v84, v85, v87
	v_div_fixup_f32 v76, v84, v76, 1.0
	v_pk_mul_f32 v[84:85], v[76:77], s[20:21] op_sel_hi:[1,0]
	v_lshl_add_u64 v[76:77], v[122:123], 0, v[82:83]
	v_lshl_add_u64 v[86:87], v[76:77], 0, v[0:1]
	v_cvt_pk_bf16_f32 v76, v80, v81
	v_cvt_pk_bf16_f32 v77, v84, v85
	global_store_dwordx4 v[86:87], v[74:77], off
	s_nop 1
	v_pk_add_f32 v[74:75], v[66:67], v[212:213]
	v_pk_add_f32 v[70:71], v[70:71], v[208:209]
	v_pk_add_f32 v[68:69], v[68:69], v[214:215]
	v_mul_f32_e32 v66, 0xbfb8aa3b, v70
	v_mul_f32_e32 v67, 0xbfb8aa3b, v71
	v_exp_f32_e32 v66, v66
	v_exp_f32_e32 v67, v67
	v_pk_add_f32 v[72:73], v[72:73], v[210:211]
	v_mul_f32_e32 v68, 0xbfb8aa3b, v68
	v_mul_f32_e32 v69, 0xbfb8aa3b, v69
	v_pk_add_f32 v[66:67], v[66:67], 1.0 op_sel_hi:[1,0]
	v_exp_f32_e32 v68, v68
	v_rcp_f32_e32 v71, v67
	v_exp_f32_e32 v69, v69
	v_fma_f32 v76, -v67, v71, 1.0
	v_fmac_f32_e32 v71, v76, v71
	v_fma_f32 v78, -v67, v71, 1.0
	v_fma_f32 v77, v78, v71, v71
	v_fma_f32 v70, -v67, v77, 1.0
	v_fma_f32 v70, v70, v71, v77
	v_div_fixup_f32 v67, v70, v67, 1.0
	v_rcp_f32_e32 v71, v66
	v_pk_add_f32 v[68:69], v[68:69], 1.0 op_sel_hi:[1,0]
	v_fma_f32 v76, -v66, v71, 1.0
	v_fmac_f32_e32 v71, v76, v71
	v_fma_f32 v78, -v66, v71, 1.0
	v_fma_f32 v77, v78, v71, v71
	v_fma_f32 v70, -v66, v77, 1.0
	v_fma_f32 v70, v70, v71, v77
	v_div_fixup_f32 v66, v70, v66, 1.0
	v_mul_f32_e32 v70, 0xbfb8aa3b, v72
	v_mul_f32_e32 v71, 0xbfb8aa3b, v73
	v_exp_f32_e32 v70, v70
	v_exp_f32_e32 v71, v71
	v_pk_mul_f32 v[66:67], v[66:67], s[20:21] op_sel_hi:[1,0]
	v_pk_add_f32 v[70:71], v[70:71], 1.0 op_sel_hi:[1,0]
	s_nop 0
	v_rcp_f32_e32 v73, v71
	v_cvt_pk_bf16_f32 v66, v66, v67
	v_fma_f32 v76, -v71, v73, 1.0
	v_fmac_f32_e32 v73, v76, v73
	v_fma_f32 v78, -v71, v73, 1.0
	v_fma_f32 v77, v78, v73, v73
	v_fma_f32 v72, -v71, v77, 1.0
	v_fma_f32 v72, v72, v73, v77
	v_div_fixup_f32 v71, v72, v71, 1.0
	v_rcp_f32_e32 v73, v70
	s_nop 0
	v_fma_f32 v76, -v70, v73, 1.0
	v_fmac_f32_e32 v73, v76, v73
	v_fma_f32 v78, -v70, v73, 1.0
	v_fma_f32 v77, v78, v73, v73
	v_fma_f32 v72, -v70, v77, 1.0
	v_fma_f32 v72, v72, v73, v77
	v_div_fixup_f32 v70, v72, v70, 1.0
	v_mul_f32_e32 v72, 0xbfb8aa3b, v74
	v_mul_f32_e32 v73, 0xbfb8aa3b, v75
	v_exp_f32_e32 v72, v72
; __device__ __forceinline__ u32x4 pack8(f32x4 v0, f32x4 v1) { u32x4 o; o.x = pkbf(v0.x, v0.y); o.y = pkbf(v0.z, v0.w); o.z = pkbf(v1.x, v1.y); o.w = pkbf(v1.z, v1.w); return o; }
;     __device__ __forceinline__ float f(float x) const { return -0.6065306597126334f * sigmoidf_(x); }
;     __device__ __forceinline__ void operator()(int row, int col, f32x4 v0, f32x4 v1) const { *(u32x4*)(G + (size_t)row * 1024 + col) = pack8(v0, v1); }
;     __device__ __forceinline__ void operator()(const pg8::f32x4 (&acc)[2][2][4][2], const pg8::Unit& u, int wr, int wc, int fr, int fq) const {
;         const int row0 = u.pm * 256 + wr * 64 + fr, col0 = u.pn * 256 + wc * 32 + 8 * fq;
; #pragma unroll
;         for (int ai = 0; ai < 2; ++ai)
; #pragma unroll
;             for (int m = 0; m < 4; ++m)
; #pragma unroll
;                 for (int bj = 0; bj < 2; ++bj) { op(row0 + ai * 128 + m * 16, col0 + bj * 128, acc[ai][bj][m][0], acc[ai][bj][m][1]); asm volatile("" ::: "memory"); }
;     __device__ __forceinline__ void operator()(int row, int col, f32x4 v0, f32x4 v1) const {
;         const f32x4 b0 = *(const f32x4*)(w0 + col), b1 = *(const f32x4*)(w0 + col + 4);
;         v0 += b0; v1 += b1;
;         v0 = (f32x4){f(v0.x), f(v0.y), f(v0.z), f(v0.w)}; v1 = (f32x4){f(v1.x), f(v1.y), f(v1.z), f(v1.w)};
;         bf16_t* dst = (col < 1024 ? D0 : D1) + (size_t)row * 1024 + (col & 1023);
;         *(u32x4*)dst = pack8(v0, v1);
	v_exp_f32_e32 v73, v73
	v_pk_mul_f32 v[70:71], v[70:71], s[20:21] op_sel_hi:[1,0]
	v_pk_add_f32 v[72:73], v[72:73], 1.0 op_sel_hi:[1,0]
	s_nop 0
	v_rcp_f32_e32 v75, v73
	v_cvt_pk_bf16_f32 v67, v70, v71
	v_fma_f32 v76, -v73, v75, 1.0
	v_fmac_f32_e32 v75, v76, v75
	v_fma_f32 v78, -v73, v75, 1.0
	v_fma_f32 v77, v78, v75, v75
	v_fma_f32 v74, -v73, v77, 1.0
	v_fma_f32 v74, v74, v75, v77
	v_div_fixup_f32 v73, v74, v73, 1.0
	v_rcp_f32_e32 v75, v72
	s_nop 0
	v_fma_f32 v76, -v72, v75, 1.0
	v_fmac_f32_e32 v75, v76, v75
	v_fma_f32 v78, -v72, v75, 1.0
	v_fma_f32 v77, v78, v75, v75
	v_fma_f32 v74, -v72, v77, 1.0
	v_fma_f32 v74, v74, v75, v77
	v_div_fixup_f32 v72, v74, v72, 1.0
	v_rcp_f32_e32 v75, v69
	v_pk_mul_f32 v[72:73], v[72:73], s[20:21] op_sel_hi:[1,0]
	v_fma_f32 v76, -v69, v75, 1.0
	v_fmac_f32_e32 v75, v76, v75
	v_fma_f32 v78, -v69, v75, 1.0
	v_fma_f32 v77, v78, v75, v75
	v_fma_f32 v74, -v69, v77, 1.0
	v_fma_f32 v74, v74, v75, v77
	v_div_fixup_f32 v69, v74, v69, 1.0
	v_rcp_f32_e32 v75, v68
	s_nop 0
	v_fma_f32 v76, -v68, v75, 1.0
	v_fmac_f32_e32 v75, v76, v75
	v_fma_f32 v78, -v68, v75, 1.0
	v_fma_f32 v77, v78, v75, v75
	v_fma_f32 v74, -v68, v77, 1.0
	v_fma_f32 v74, v74, v75, v77
	v_div_fixup_f32 v68, v74, v68, 1.0
	v_pk_mul_f32 v[74:75], v[68:69], s[20:21] op_sel_hi:[1,0]
	v_lshl_add_u64 v[68:69], v[114:115], 0, v[82:83]
	v_lshl_add_u64 v[76:77], v[68:69], 0, v[116:117]
	v_cvt_pk_bf16_f32 v68, v72, v73
	v_cvt_pk_bf16_f32 v69, v74, v75
	global_store_dwordx4 v[76:77], v[66:69], off
	s_nop 1
	v_lshl_add_u64 v[66:67], v[144:145], 0, s[90:91]
	v_pk_add_f32 v[68:69], v[58:59], v[204:205]
	v_pk_add_f32 v[62:63], v[62:63], v[200:201]
	v_pk_add_f32 v[60:61], v[60:61], v[206:207]
	v_mul_f32_e32 v58, 0xbfb8aa3b, v62
	v_mul_f32_e32 v59, 0xbfb8aa3b, v63
	v_exp_f32_e32 v58, v58
	v_exp_f32_e32 v59, v59
	v_pk_add_f32 v[64:65], v[64:65], v[202:203]
	v_mul_f32_e32 v60, 0xbfb8aa3b, v60
	v_mul_f32_e32 v61, 0xbfb8aa3b, v61
	v_pk_add_f32 v[58:59], v[58:59], 1.0 op_sel_hi:[1,0]
	v_exp_f32_e32 v60, v60
	v_rcp_f32_e32 v63, v59
	v_exp_f32_e32 v61, v61
	v_fma_f32 v70, -v59, v63, 1.0
	v_fmac_f32_e32 v63, v70, v63
	v_fma_f32 v72, -v59, v63, 1.0
	v_fma_f32 v71, v72, v63, v63
	v_fma_f32 v62, -v59, v71, 1.0
	v_fma_f32 v62, v62, v63, v71
	v_div_fixup_f32 v59, v62, v59, 1.0
	v_rcp_f32_e32 v63, v58
	v_pk_add_f32 v[60:61], v[60:61], 1.0 op_sel_hi:[1,0]
	v_fma_f32 v70, -v58, v63, 1.0
	v_fmac_f32_e32 v63, v70, v63
	v_fma_f32 v72, -v58, v63, 1.0
	v_fma_f32 v71, v72, v63, v63
	v_fma_f32 v62, -v58, v71, 1.0
	v_fma_f32 v62, v62, v63, v71
	v_div_fixup_f32 v58, v62, v58, 1.0
	v_mul_f32_e32 v62, 0xbfb8aa3b, v64
	v_mul_f32_e32 v63, 0xbfb8aa3b, v65
	v_exp_f32_e32 v62, v62
	v_exp_f32_e32 v63, v63
	v_pk_mul_f32 v[58:59], v[58:59], s[20:21] op_sel_hi:[1,0]
	v_pk_add_f32 v[62:63], v[62:63], 1.0 op_sel_hi:[1,0]
	s_nop 0
	v_rcp_f32_e32 v65, v63
	v_cvt_pk_bf16_f32 v58, v58, v59
	v_fma_f32 v70, -v63, v65, 1.0
	v_fmac_f32_e32 v65, v70, v65
	v_fma_f32 v72, -v63, v65, 1.0
	v_fma_f32 v71, v72, v65, v65
	v_fma_f32 v64, -v63, v71, 1.0
	v_fma_f32 v64, v64, v65, v71
	v_div_fixup_f32 v63, v64, v63, 1.0
	v_rcp_f32_e32 v65, v62
	s_nop 0
	v_fma_f32 v70, -v62, v65, 1.0
	v_fmac_f32_e32 v65, v70, v65
	v_fma_f32 v72, -v62, v65, 1.0
	v_fma_f32 v71, v72, v65, v65
	v_fma_f32 v64, -v62, v71, 1.0
	v_fma_f32 v64, v64, v65, v71
	v_div_fixup_f32 v62, v64, v62, 1.0
	v_mul_f32_e32 v64, 0xbfb8aa3b, v68
	v_mul_f32_e32 v65, 0xbfb8aa3b, v69
	v_exp_f32_e32 v64, v64
	v_exp_f32_e32 v65, v65
	v_pk_mul_f32 v[62:63], v[62:63], s[20:21] op_sel_hi:[1,0]
	v_pk_add_f32 v[64:65], v[64:65], 1.0 op_sel_hi:[1,0]
	s_nop 0
	v_rcp_f32_e32 v69, v65
	v_cvt_pk_bf16_f32 v59, v62, v63
	v_fma_f32 v70, -v65, v69, 1.0
	v_fmac_f32_e32 v69, v70, v69
	v_fma_f32 v72, -v65, v69, 1.0
	v_fma_f32 v71, v72, v69, v69
	v_fma_f32 v68, -v65, v71, 1.0
	v_fma_f32 v68, v68, v69, v71
	v_div_fixup_f32 v65, v68, v65, 1.0
	v_rcp_f32_e32 v69, v64
	s_nop 0
	v_fma_f32 v70, -v64, v69, 1.0
	v_fmac_f32_e32 v69, v70, v69
	v_fma_f32 v72, -v64, v69, 1.0
	v_fma_f32 v71, v72, v69, v69
	v_fma_f32 v68, -v64, v71, 1.0
	v_fma_f32 v68, v68, v69, v71
	v_div_fixup_f32 v64, v68, v64, 1.0
	v_rcp_f32_e32 v69, v61
	v_pk_mul_f32 v[64:65], v[64:65], s[20:21] op_sel_hi:[1,0]
	v_fma_f32 v70, -v61, v69, 1.0
	v_fmac_f32_e32 v69, v70, v69
	v_fma_f32 v72, -v61, v69, 1.0
	v_fma_f32 v71, v72, v69, v69
	v_fma_f32 v68, -v61, v71, 1.0
	v_fma_f32 v68, v68, v69, v71
	v_div_fixup_f32 v61, v68, v61, 1.0
	v_rcp_f32_e32 v69, v60
	s_nop 0
	v_fma_f32 v70, -v60, v69, 1.0
	v_fmac_f32_e32 v69, v70, v69
	v_fma_f32 v72, -v60, v69, 1.0
	v_fma_f32 v71, v72, v69, v69
	v_fma_f32 v68, -v60, v71, 1.0
	v_fma_f32 v68, v68, v69, v71
	v_div_fixup_f32 v60, v68, v60, 1.0
	v_pk_mul_f32 v[68:69], v[60:61], s[20:21] op_sel_hi:[1,0]
	v_lshl_add_u64 v[60:61], v[122:123], 0, v[66:67]
	v_lshl_add_u64 v[70:71], v[60:61], 0, v[0:1]
	v_cvt_pk_bf16_f32 v60, v64, v65
	v_cvt_pk_bf16_f32 v61, v68, v69
	global_store_dwordx4 v[70:71], v[58:61], off
	s_nop 1
	v_pk_add_f32 v[58:59], v[50:51], v[212:213]
	v_pk_add_f32 v[54:55], v[54:55], v[208:209]
	v_pk_add_f32 v[52:53], v[52:53], v[214:215]
	v_mul_f32_e32 v50, 0xbfb8aa3b, v54
	v_mul_f32_e32 v51, 0xbfb8aa3b, v55
	v_exp_f32_e32 v50, v50
	v_exp_f32_e32 v51, v51
	v_pk_add_f32 v[56:57], v[56:57], v[210:211]
	v_mul_f32_e32 v52, 0xbfb8aa3b, v52
	v_mul_f32_e32 v53, 0xbfb8aa3b, v53
	v_pk_add_f32 v[50:51], v[50:51], 1.0 op_sel_hi:[1,0]
	v_exp_f32_e32 v52, v52
	v_rcp_f32_e32 v55, v51
	v_exp_f32_e32 v53, v53
	v_fma_f32 v60, -v51, v55, 1.0
	v_fmac_f32_e32 v55, v60, v55
	v_fma_f32 v62, -v51, v55, 1.0
	v_fma_f32 v61, v62, v55, v55
	v_fma_f32 v54, -v51, v61, 1.0
	v_fma_f32 v54, v54, v55, v61
; __device__ __forceinline__ u32x4 pack8(f32x4 v0, f32x4 v1) { u32x4 o; o.x = pkbf(v0.x, v0.y); o.y = pkbf(v0.z, v0.w); o.z = pkbf(v1.x, v1.y); o.w = pkbf(v1.z, v1.w); return o; }
;     __device__ __forceinline__ float f(float x) const { return -0.6065306597126334f * sigmoidf_(x); }
;     __device__ __forceinline__ void operator()(int row, int col, f32x4 v0, f32x4 v1) const { *(u32x4*)(G + (size_t)row * 1024 + col) = pack8(v0, v1); }
;     __device__ __forceinline__ void operator()(const pg8::f32x4 (&acc)[2][2][4][2], const pg8::Unit& u, int wr, int wc, int fr, int fq) const {
;         const int row0 = u.pm * 256 + wr * 64 + fr, col0 = u.pn * 256 + wc * 32 + 8 * fq;
; #pragma unroll
;         for (int ai = 0; ai < 2; ++ai)
; #pragma unroll
;             for (int m = 0; m < 4; ++m)
; #pragma unroll
;                 for (int bj = 0; bj < 2; ++bj) { op(row0 + ai * 128 + m * 16, col0 + bj * 128, acc[ai][bj][m][0], acc[ai][bj][m][1]); asm volatile("" ::: "memory"); }
;     __device__ __forceinline__ void operator()(int row, int col, f32x4 v0, f32x4 v1) const {
;         const f32x4 b0 = *(const f32x4*)(w0 + col), b1 = *(const f32x4*)(w0 + col + 4);
;         v0 += b0; v1 += b1;
;         v0 = (f32x4){f(v0.x), f(v0.y), f(v0.z), f(v0.w)}; v1 = (f32x4){f(v1.x), f(v1.y), f(v1.z), f(v1.w)};
;         bf16_t* dst = (col < 1024 ? D0 : D1) + (size_t)row * 1024 + (col & 1023);
;         *(u32x4*)dst = pack8(v0, v1);
	v_div_fixup_f32 v51, v54, v51, 1.0
	v_rcp_f32_e32 v55, v50
	v_pk_add_f32 v[52:53], v[52:53], 1.0 op_sel_hi:[1,0]
	v_fma_f32 v60, -v50, v55, 1.0
	v_fmac_f32_e32 v55, v60, v55
	v_fma_f32 v62, -v50, v55, 1.0
	v_fma_f32 v61, v62, v55, v55
	v_fma_f32 v54, -v50, v61, 1.0
	v_fma_f32 v54, v54, v55, v61
	v_div_fixup_f32 v50, v54, v50, 1.0
	v_mul_f32_e32 v54, 0xbfb8aa3b, v56
	v_mul_f32_e32 v55, 0xbfb8aa3b, v57
	v_exp_f32_e32 v54, v54
	v_exp_f32_e32 v55, v55
	v_pk_mul_f32 v[50:51], v[50:51], s[20:21] op_sel_hi:[1,0]
	v_pk_add_f32 v[54:55], v[54:55], 1.0 op_sel_hi:[1,0]
	s_nop 0
	v_rcp_f32_e32 v57, v55
	v_cvt_pk_bf16_f32 v50, v50, v51
	v_fma_f32 v60, -v55, v57, 1.0
	v_fmac_f32_e32 v57, v60, v57
	v_fma_f32 v62, -v55, v57, 1.0
	v_fma_f32 v61, v62, v57, v57
	v_fma_f32 v56, -v55, v61, 1.0
	v_fma_f32 v56, v56, v57, v61
	v_div_fixup_f32 v55, v56, v55, 1.0
	v_rcp_f32_e32 v57, v54
	s_nop 0
	v_fma_f32 v60, -v54, v57, 1.0
	v_fmac_f32_e32 v57, v60, v57
	v_fma_f32 v62, -v54, v57, 1.0
	v_fma_f32 v61, v62, v57, v57
	v_fma_f32 v56, -v54, v61, 1.0
	v_fma_f32 v56, v56, v57, v61
	v_div_fixup_f32 v54, v56, v54, 1.0
	v_mul_f32_e32 v56, 0xbfb8aa3b, v58
	v_mul_f32_e32 v57, 0xbfb8aa3b, v59
	v_exp_f32_e32 v56, v56
	v_exp_f32_e32 v57, v57
	v_pk_mul_f32 v[54:55], v[54:55], s[20:21] op_sel_hi:[1,0]
	v_pk_add_f32 v[56:57], v[56:57], 1.0 op_sel_hi:[1,0]
	s_nop 0
	v_rcp_f32_e32 v59, v57
	v_cvt_pk_bf16_f32 v51, v54, v55
	v_fma_f32 v60, -v57, v59, 1.0
	v_fmac_f32_e32 v59, v60, v59
	v_fma_f32 v62, -v57, v59, 1.0
	v_fma_f32 v61, v62, v59, v59
	v_fma_f32 v58, -v57, v61, 1.0
	v_fma_f32 v58, v58, v59, v61
	v_div_fixup_f32 v57, v58, v57, 1.0
	v_rcp_f32_e32 v59, v56
	s_nop 0
	v_fma_f32 v60, -v56, v59, 1.0
	v_fmac_f32_e32 v59, v60, v59
	v_fma_f32 v62, -v56, v59, 1.0
	v_fma_f32 v61, v62, v59, v59
	v_fma_f32 v58, -v56, v61, 1.0
	v_fma_f32 v58, v58, v59, v61
	v_div_fixup_f32 v56, v58, v56, 1.0
	v_rcp_f32_e32 v59, v53
	v_pk_mul_f32 v[56:57], v[56:57], s[20:21] op_sel_hi:[1,0]
	v_fma_f32 v60, -v53, v59, 1.0
	v_fmac_f32_e32 v59, v60, v59
	v_fma_f32 v62, -v53, v59, 1.0
	v_fma_f32 v61, v62, v59, v59
	v_fma_f32 v58, -v53, v61, 1.0
	v_fma_f32 v58, v58, v59, v61
	v_div_fixup_f32 v53, v58, v53, 1.0
	v_rcp_f32_e32 v59, v52
	s_mov_b64 s[4:5], 0x48000
	v_fma_f32 v60, -v52, v59, 1.0
	v_fmac_f32_e32 v59, v60, v59
	v_fma_f32 v62, -v52, v59, 1.0
	v_fma_f32 v61, v62, v59, v59
	v_fma_f32 v58, -v52, v61, 1.0
	v_fma_f32 v58, v58, v59, v61
	v_div_fixup_f32 v52, v58, v52, 1.0
	v_pk_mul_f32 v[58:59], v[52:53], s[20:21] op_sel_hi:[1,0]
	v_lshl_add_u64 v[52:53], v[114:115], 0, v[66:67]
	v_lshl_add_u64 v[60:61], v[52:53], 0, v[116:117]
	v_cvt_pk_bf16_f32 v52, v56, v57
	v_cvt_pk_bf16_f32 v53, v58, v59
	global_store_dwordx4 v[60:61], v[50:53], off
	s_nop 1
	v_lshl_add_u64 v[50:51], v[144:145], 0, s[4:5]
	v_pk_add_f32 v[52:53], v[42:43], v[204:205]
	v_pk_add_f32 v[46:47], v[46:47], v[200:201]
	v_pk_add_f32 v[44:45], v[44:45], v[206:207]
	v_mul_f32_e32 v42, 0xbfb8aa3b, v46
	v_mul_f32_e32 v43, 0xbfb8aa3b, v47
	v_exp_f32_e32 v42, v42
	v_exp_f32_e32 v43, v43
	v_pk_add_f32 v[48:49], v[48:49], v[202:203]
	v_mul_f32_e32 v44, 0xbfb8aa3b, v44
	v_mul_f32_e32 v45, 0xbfb8aa3b, v45
	v_pk_add_f32 v[42:43], v[42:43], 1.0 op_sel_hi:[1,0]
	v_exp_f32_e32 v44, v44
	v_rcp_f32_e32 v47, v43
	v_exp_f32_e32 v45, v45
	v_fma_f32 v54, -v43, v47, 1.0
	v_fmac_f32_e32 v47, v54, v47
	v_fma_f32 v56, -v43, v47, 1.0
	v_fma_f32 v55, v56, v47, v47
	v_fma_f32 v46, -v43, v55, 1.0
	v_fma_f32 v46, v46, v47, v55
	v_div_fixup_f32 v43, v46, v43, 1.0
	v_rcp_f32_e32 v47, v42
	v_pk_add_f32 v[44:45], v[44:45], 1.0 op_sel_hi:[1,0]
	v_fma_f32 v54, -v42, v47, 1.0
	v_fmac_f32_e32 v47, v54, v47
	v_fma_f32 v56, -v42, v47, 1.0
	v_fma_f32 v55, v56, v47, v47
	v_fma_f32 v46, -v42, v55, 1.0
	v_fma_f32 v46, v46, v47, v55
	v_div_fixup_f32 v42, v46, v42, 1.0
	v_mul_f32_e32 v46, 0xbfb8aa3b, v48
	v_mul_f32_e32 v47, 0xbfb8aa3b, v49
	v_exp_f32_e32 v46, v46
	v_exp_f32_e32 v47, v47
	v_pk_mul_f32 v[42:43], v[42:43], s[20:21] op_sel_hi:[1,0]
	v_pk_add_f32 v[46:47], v[46:47], 1.0 op_sel_hi:[1,0]
	s_nop 0
	v_rcp_f32_e32 v49, v47
	v_cvt_pk_bf16_f32 v42, v42, v43
	v_fma_f32 v54, -v47, v49, 1.0
	v_fmac_f32_e32 v49, v54, v49
	v_fma_f32 v56, -v47, v49, 1.0
	v_fma_f32 v55, v56, v49, v49
	v_fma_f32 v48, -v47, v55, 1.0
	v_fma_f32 v48, v48, v49, v55
	v_div_fixup_f32 v47, v48, v47, 1.0
	v_rcp_f32_e32 v49, v46
	s_nop 0
	v_fma_f32 v54, -v46, v49, 1.0
	v_fmac_f32_e32 v49, v54, v49
	v_fma_f32 v56, -v46, v49, 1.0
	v_fma_f32 v55, v56, v49, v49
	v_fma_f32 v48, -v46, v55, 1.0
	v_fma_f32 v48, v48, v49, v55
	v_div_fixup_f32 v46, v48, v46, 1.0
	v_mul_f32_e32 v48, 0xbfb8aa3b, v52
	v_mul_f32_e32 v49, 0xbfb8aa3b, v53
	v_exp_f32_e32 v48, v48
	v_exp_f32_e32 v49, v49
	v_pk_mul_f32 v[46:47], v[46:47], s[20:21] op_sel_hi:[1,0]
	v_pk_add_f32 v[48:49], v[48:49], 1.0 op_sel_hi:[1,0]
	s_nop 0
	v_rcp_f32_e32 v53, v49
	v_cvt_pk_bf16_f32 v43, v46, v47
	v_fma_f32 v54, -v49, v53, 1.0
	v_fmac_f32_e32 v53, v54, v53
	v_fma_f32 v56, -v49, v53, 1.0
	v_fma_f32 v55, v56, v53, v53
	v_fma_f32 v52, -v49, v55, 1.0
	v_fma_f32 v52, v52, v53, v55
	v_div_fixup_f32 v49, v52, v49, 1.0
	v_rcp_f32_e32 v53, v48
	s_nop 0
	v_fma_f32 v54, -v48, v53, 1.0
	v_fmac_f32_e32 v53, v54, v53
	v_fma_f32 v56, -v48, v53, 1.0
	v_fma_f32 v55, v56, v53, v53
	v_fma_f32 v52, -v48, v55, 1.0
	v_fma_f32 v52, v52, v53, v55
	v_div_fixup_f32 v48, v52, v48, 1.0
	v_rcp_f32_e32 v53, v45
	v_pk_mul_f32 v[48:49], v[48:49], s[20:21] op_sel_hi:[1,0]
	v_fma_f32 v54, -v45, v53, 1.0
	v_fmac_f32_e32 v53, v54, v53
	v_fma_f32 v56, -v45, v53, 1.0
	v_fma_f32 v55, v56, v53, v53
	v_fma_f32 v52, -v45, v55, 1.0
	v_fma_f32 v52, v52, v53, v55
	v_div_fixup_f32 v45, v52, v45, 1.0
; __device__ __forceinline__ u32x4 pack8(f32x4 v0, f32x4 v1) { u32x4 o; o.x = pkbf(v0.x, v0.y); o.y = pkbf(v0.z, v0.w); o.z = pkbf(v1.x, v1.y); o.w = pkbf(v1.z, v1.w); return o; }
;     __device__ __forceinline__ float f(float x) const { return -0.6065306597126334f * sigmoidf_(x); }
;     __device__ __forceinline__ void operator()(int row, int col, f32x4 v0, f32x4 v1) const { *(u32x4*)(G + (size_t)row * 1024 + col) = pack8(v0, v1); }
;     __device__ __forceinline__ void operator()(const pg8::f32x4 (&acc)[2][2][4][2], const pg8::Unit& u, int wr, int wc, int fr, int fq) const {
;         const int row0 = u.pm * 256 + wr * 64 + fr, col0 = u.pn * 256 + wc * 32 + 8 * fq;
; #pragma unroll
;         for (int ai = 0; ai < 2; ++ai)
; #pragma unroll
;             for (int m = 0; m < 4; ++m)
; #pragma unroll
;                 for (int bj = 0; bj < 2; ++bj) { op(row0 + ai * 128 + m * 16, col0 + bj * 128, acc[ai][bj][m][0], acc[ai][bj][m][1]); asm volatile("" ::: "memory"); }
;     __device__ __forceinline__ void operator()(int row, int col, f32x4 v0, f32x4 v1) const {
;         const f32x4 b0 = *(const f32x4*)(w0 + col), b1 = *(const f32x4*)(w0 + col + 4);
;         v0 += b0; v1 += b1;
;         v0 = (f32x4){f(v0.x), f(v0.y), f(v0.z), f(v0.w)}; v1 = (f32x4){f(v1.x), f(v1.y), f(v1.z), f(v1.w)};
;         bf16_t* dst = (col < 1024 ? D0 : D1) + (size_t)row * 1024 + (col & 1023);
;         *(u32x4*)dst = pack8(v0, v1);
	v_rcp_f32_e32 v53, v44
	s_nop 0
	v_fma_f32 v54, -v44, v53, 1.0
	v_fmac_f32_e32 v53, v54, v53
	v_fma_f32 v56, -v44, v53, 1.0
	v_fma_f32 v55, v56, v53, v53
	v_fma_f32 v52, -v44, v55, 1.0
	v_fma_f32 v52, v52, v53, v55
	v_div_fixup_f32 v44, v52, v44, 1.0
	v_pk_mul_f32 v[52:53], v[44:45], s[20:21] op_sel_hi:[1,0]
	v_lshl_add_u64 v[44:45], v[122:123], 0, v[50:51]
	v_lshl_add_u64 v[54:55], v[44:45], 0, v[0:1]
	v_cvt_pk_bf16_f32 v44, v48, v49
	v_cvt_pk_bf16_f32 v45, v52, v53
	global_store_dwordx4 v[54:55], v[42:45], off
	s_nop 1
	v_pk_add_f32 v[42:43], v[34:35], v[212:213]
	v_pk_add_f32 v[38:39], v[38:39], v[208:209]
	v_pk_add_f32 v[36:37], v[36:37], v[214:215]
	v_mul_f32_e32 v34, 0xbfb8aa3b, v38
	v_mul_f32_e32 v35, 0xbfb8aa3b, v39
	v_exp_f32_e32 v34, v34
	v_exp_f32_e32 v35, v35
	v_pk_add_f32 v[40:41], v[40:41], v[210:211]
	v_mul_f32_e32 v36, 0xbfb8aa3b, v36
	v_mul_f32_e32 v37, 0xbfb8aa3b, v37
	v_pk_add_f32 v[34:35], v[34:35], 1.0 op_sel_hi:[1,0]
	v_exp_f32_e32 v36, v36
	v_rcp_f32_e32 v39, v35
	v_exp_f32_e32 v37, v37
	v_fma_f32 v44, -v35, v39, 1.0
	v_fmac_f32_e32 v39, v44, v39
	v_fma_f32 v46, -v35, v39, 1.0
	v_fma_f32 v45, v46, v39, v39
	v_fma_f32 v38, -v35, v45, 1.0
	v_fma_f32 v38, v38, v39, v45
	v_div_fixup_f32 v35, v38, v35, 1.0
	v_rcp_f32_e32 v39, v34
	v_pk_add_f32 v[36:37], v[36:37], 1.0 op_sel_hi:[1,0]
	v_fma_f32 v44, -v34, v39, 1.0
	v_fmac_f32_e32 v39, v44, v39
	v_fma_f32 v46, -v34, v39, 1.0
	v_fma_f32 v45, v46, v39, v39
	v_fma_f32 v38, -v34, v45, 1.0
	v_fma_f32 v38, v38, v39, v45
	v_div_fixup_f32 v34, v38, v34, 1.0
	v_mul_f32_e32 v38, 0xbfb8aa3b, v40
	v_mul_f32_e32 v39, 0xbfb8aa3b, v41
	v_exp_f32_e32 v38, v38
	v_exp_f32_e32 v39, v39
	v_pk_mul_f32 v[34:35], v[34:35], s[20:21] op_sel_hi:[1,0]
	v_pk_add_f32 v[38:39], v[38:39], 1.0 op_sel_hi:[1,0]
	s_nop 0
	v_rcp_f32_e32 v41, v39
	v_cvt_pk_bf16_f32 v34, v34, v35
	v_fma_f32 v44, -v39, v41, 1.0
	v_fmac_f32_e32 v41, v44, v41
	v_fma_f32 v46, -v39, v41, 1.0
	v_fma_f32 v45, v46, v41, v41
	v_fma_f32 v40, -v39, v45, 1.0
	v_fma_f32 v40, v40, v41, v45
	v_div_fixup_f32 v39, v40, v39, 1.0
	v_rcp_f32_e32 v41, v38
	s_nop 0
	v_fma_f32 v44, -v38, v41, 1.0
	v_fmac_f32_e32 v41, v44, v41
	v_fma_f32 v46, -v38, v41, 1.0
	v_fma_f32 v45, v46, v41, v41
	v_fma_f32 v40, -v38, v45, 1.0
	v_fma_f32 v40, v40, v41, v45
	v_div_fixup_f32 v38, v40, v38, 1.0
	v_mul_f32_e32 v40, 0xbfb8aa3b, v42
	v_mul_f32_e32 v41, 0xbfb8aa3b, v43
	v_exp_f32_e32 v40, v40
	v_exp_f32_e32 v41, v41
	v_pk_mul_f32 v[38:39], v[38:39], s[20:21] op_sel_hi:[1,0]
	v_pk_add_f32 v[40:41], v[40:41], 1.0 op_sel_hi:[1,0]
	s_nop 0
	v_rcp_f32_e32 v43, v41
	v_cvt_pk_bf16_f32 v35, v38, v39
	v_fma_f32 v44, -v41, v43, 1.0
	v_fmac_f32_e32 v43, v44, v43
	v_fma_f32 v46, -v41, v43, 1.0
	v_fma_f32 v45, v46, v43, v43
	v_fma_f32 v42, -v41, v45, 1.0
	v_fma_f32 v42, v42, v43, v45
	v_div_fixup_f32 v41, v42, v41, 1.0
	v_rcp_f32_e32 v43, v40
	s_nop 0
	v_fma_f32 v44, -v40, v43, 1.0
	v_fmac_f32_e32 v43, v44, v43
	v_fma_f32 v46, -v40, v43, 1.0
	v_fma_f32 v45, v46, v43, v43
	v_fma_f32 v42, -v40, v45, 1.0
	v_fma_f32 v42, v42, v43, v45
	v_div_fixup_f32 v40, v42, v40, 1.0
	v_rcp_f32_e32 v43, v37
	v_pk_mul_f32 v[40:41], v[40:41], s[20:21] op_sel_hi:[1,0]
	v_fma_f32 v44, -v37, v43, 1.0
	v_fmac_f32_e32 v43, v44, v43
	v_fma_f32 v46, -v37, v43, 1.0
	v_fma_f32 v45, v46, v43, v43
	v_fma_f32 v42, -v37, v45, 1.0
	v_fma_f32 v42, v42, v43, v45
	v_div_fixup_f32 v37, v42, v37, 1.0
	v_rcp_f32_e32 v43, v36
	s_mov_b64 s[4:5], 0x50000
	v_fma_f32 v44, -v36, v43, 1.0
	v_fmac_f32_e32 v43, v44, v43
	v_fma_f32 v46, -v36, v43, 1.0
	v_fma_f32 v45, v46, v43, v43
	v_fma_f32 v42, -v36, v45, 1.0
	v_fma_f32 v42, v42, v43, v45
	v_div_fixup_f32 v36, v42, v36, 1.0
	v_pk_mul_f32 v[42:43], v[36:37], s[20:21] op_sel_hi:[1,0]
	v_lshl_add_u64 v[36:37], v[114:115], 0, v[50:51]
	v_lshl_add_u64 v[44:45], v[36:37], 0, v[116:117]
	v_cvt_pk_bf16_f32 v36, v40, v41
	v_cvt_pk_bf16_f32 v37, v42, v43
	global_store_dwordx4 v[44:45], v[34:37], off
	s_nop 1
	v_lshl_add_u64 v[34:35], v[144:145], 0, s[4:5]
	v_pk_add_f32 v[36:37], v[26:27], v[204:205]
	v_pk_add_f32 v[30:31], v[30:31], v[200:201]
	v_pk_add_f32 v[28:29], v[28:29], v[206:207]
	v_mul_f32_e32 v26, 0xbfb8aa3b, v30
	v_mul_f32_e32 v27, 0xbfb8aa3b, v31
	v_exp_f32_e32 v26, v26
	v_exp_f32_e32 v27, v27
	v_pk_add_f32 v[32:33], v[32:33], v[202:203]
	v_mul_f32_e32 v28, 0xbfb8aa3b, v28
	v_mul_f32_e32 v29, 0xbfb8aa3b, v29
	v_pk_add_f32 v[26:27], v[26:27], 1.0 op_sel_hi:[1,0]
	v_exp_f32_e32 v28, v28
	v_rcp_f32_e32 v31, v27
	v_exp_f32_e32 v29, v29
	v_fma_f32 v38, -v27, v31, 1.0
	v_fmac_f32_e32 v31, v38, v31
	v_fma_f32 v40, -v27, v31, 1.0
	v_fma_f32 v39, v40, v31, v31
	v_fma_f32 v30, -v27, v39, 1.0
	v_fma_f32 v30, v30, v31, v39
	v_div_fixup_f32 v27, v30, v27, 1.0
	v_rcp_f32_e32 v31, v26
	v_pk_add_f32 v[28:29], v[28:29], 1.0 op_sel_hi:[1,0]
	v_fma_f32 v38, -v26, v31, 1.0
	v_fmac_f32_e32 v31, v38, v31
	v_fma_f32 v40, -v26, v31, 1.0
	v_fma_f32 v39, v40, v31, v31
	v_fma_f32 v30, -v26, v39, 1.0
	v_fma_f32 v30, v30, v31, v39
	v_div_fixup_f32 v26, v30, v26, 1.0
	v_mul_f32_e32 v30, 0xbfb8aa3b, v32
	v_mul_f32_e32 v31, 0xbfb8aa3b, v33
	v_exp_f32_e32 v30, v30
	v_exp_f32_e32 v31, v31
	v_pk_mul_f32 v[26:27], v[26:27], s[20:21] op_sel_hi:[1,0]
	v_pk_add_f32 v[30:31], v[30:31], 1.0 op_sel_hi:[1,0]
	s_nop 0
	v_rcp_f32_e32 v33, v31
	v_cvt_pk_bf16_f32 v26, v26, v27
	v_fma_f32 v38, -v31, v33, 1.0
	v_fmac_f32_e32 v33, v38, v33
	v_fma_f32 v40, -v31, v33, 1.0
	v_fma_f32 v39, v40, v33, v33
	v_fma_f32 v32, -v31, v39, 1.0
	v_fma_f32 v32, v32, v33, v39
	v_div_fixup_f32 v31, v32, v31, 1.0
	v_rcp_f32_e32 v33, v30
	s_nop 0
	v_fma_f32 v38, -v30, v33, 1.0
	v_fmac_f32_e32 v33, v38, v33
	v_fma_f32 v40, -v30, v33, 1.0
; __device__ __forceinline__ u32x4 pack8(f32x4 v0, f32x4 v1) { u32x4 o; o.x = pkbf(v0.x, v0.y); o.y = pkbf(v0.z, v0.w); o.z = pkbf(v1.x, v1.y); o.w = pkbf(v1.z, v1.w); return o; }
;     __device__ __forceinline__ float f(float x) const { return -0.6065306597126334f * sigmoidf_(x); }
;     __device__ __forceinline__ void operator()(int row, int col, f32x4 v0, f32x4 v1) const { *(u32x4*)(G + (size_t)row * 1024 + col) = pack8(v0, v1); }
;     __device__ __forceinline__ void operator()(const pg8::f32x4 (&acc)[2][2][4][2], const pg8::Unit& u, int wr, int wc, int fr, int fq) const {
;         const int row0 = u.pm * 256 + wr * 64 + fr, col0 = u.pn * 256 + wc * 32 + 8 * fq;
; #pragma unroll
;         for (int ai = 0; ai < 2; ++ai)
; #pragma unroll
;             for (int m = 0; m < 4; ++m)
; #pragma unroll
;                 for (int bj = 0; bj < 2; ++bj) { op(row0 + ai * 128 + m * 16, col0 + bj * 128, acc[ai][bj][m][0], acc[ai][bj][m][1]); asm volatile("" ::: "memory"); }
;     __device__ __forceinline__ void operator()(int row, int col, f32x4 v0, f32x4 v1) const {
;         const f32x4 b0 = *(const f32x4*)(w0 + col), b1 = *(const f32x4*)(w0 + col + 4);
;         v0 += b0; v1 += b1;
;         v0 = (f32x4){f(v0.x), f(v0.y), f(v0.z), f(v0.w)}; v1 = (f32x4){f(v1.x), f(v1.y), f(v1.z), f(v1.w)};
;         bf16_t* dst = (col < 1024 ? D0 : D1) + (size_t)row * 1024 + (col & 1023);
;         *(u32x4*)dst = pack8(v0, v1);
	v_fma_f32 v39, v40, v33, v33
	v_fma_f32 v32, -v30, v39, 1.0
	v_fma_f32 v32, v32, v33, v39
	v_div_fixup_f32 v30, v32, v30, 1.0
	v_mul_f32_e32 v32, 0xbfb8aa3b, v36
	v_mul_f32_e32 v33, 0xbfb8aa3b, v37
	v_exp_f32_e32 v32, v32
	v_exp_f32_e32 v33, v33
	v_pk_mul_f32 v[30:31], v[30:31], s[20:21] op_sel_hi:[1,0]
	v_pk_add_f32 v[32:33], v[32:33], 1.0 op_sel_hi:[1,0]
	s_nop 0
	v_rcp_f32_e32 v37, v33
	v_cvt_pk_bf16_f32 v27, v30, v31
	v_fma_f32 v38, -v33, v37, 1.0
	v_fmac_f32_e32 v37, v38, v37
	v_fma_f32 v40, -v33, v37, 1.0
	v_fma_f32 v39, v40, v37, v37
	v_fma_f32 v36, -v33, v39, 1.0
	v_fma_f32 v36, v36, v37, v39
	v_div_fixup_f32 v33, v36, v33, 1.0
	v_rcp_f32_e32 v37, v32
	s_nop 0
	v_fma_f32 v38, -v32, v37, 1.0
	v_fmac_f32_e32 v37, v38, v37
	v_fma_f32 v40, -v32, v37, 1.0
	v_fma_f32 v39, v40, v37, v37
	v_fma_f32 v36, -v32, v39, 1.0
	v_fma_f32 v36, v36, v37, v39
	v_div_fixup_f32 v32, v36, v32, 1.0
	v_rcp_f32_e32 v37, v29
	v_pk_mul_f32 v[32:33], v[32:33], s[20:21] op_sel_hi:[1,0]
	v_fma_f32 v38, -v29, v37, 1.0
	v_fmac_f32_e32 v37, v38, v37
	v_fma_f32 v40, -v29, v37, 1.0
	v_fma_f32 v39, v40, v37, v37
	v_fma_f32 v36, -v29, v39, 1.0
	v_fma_f32 v36, v36, v37, v39
	v_div_fixup_f32 v29, v36, v29, 1.0
	v_rcp_f32_e32 v37, v28
	s_nop 0
	v_fma_f32 v38, -v28, v37, 1.0
	v_fmac_f32_e32 v37, v38, v37
	v_fma_f32 v40, -v28, v37, 1.0
	v_fma_f32 v39, v40, v37, v37
	v_fma_f32 v36, -v28, v39, 1.0
	v_fma_f32 v36, v36, v37, v39
	v_div_fixup_f32 v28, v36, v28, 1.0
	v_pk_mul_f32 v[36:37], v[28:29], s[20:21] op_sel_hi:[1,0]
	v_lshl_add_u64 v[28:29], v[122:123], 0, v[34:35]
	v_lshl_add_u64 v[38:39], v[28:29], 0, v[0:1]
	v_cvt_pk_bf16_f32 v28, v32, v33
	v_cvt_pk_bf16_f32 v29, v36, v37
	global_store_dwordx4 v[38:39], v[26:29], off
	s_nop 1
	v_pk_add_f32 v[26:27], v[18:19], v[212:213]
	v_pk_add_f32 v[22:23], v[22:23], v[208:209]
	v_pk_add_f32 v[20:21], v[20:21], v[214:215]
	v_mul_f32_e32 v18, 0xbfb8aa3b, v22
	v_mul_f32_e32 v19, 0xbfb8aa3b, v23
	v_exp_f32_e32 v18, v18
	v_exp_f32_e32 v19, v19
	v_pk_add_f32 v[24:25], v[24:25], v[210:211]
	v_mul_f32_e32 v20, 0xbfb8aa3b, v20
	v_mul_f32_e32 v21, 0xbfb8aa3b, v21
	v_pk_add_f32 v[18:19], v[18:19], 1.0 op_sel_hi:[1,0]
	v_exp_f32_e32 v20, v20
	v_rcp_f32_e32 v23, v19
	v_exp_f32_e32 v21, v21
	v_fma_f32 v28, -v19, v23, 1.0
	v_fmac_f32_e32 v23, v28, v23
	v_fma_f32 v30, -v19, v23, 1.0
	v_fma_f32 v29, v30, v23, v23
	v_fma_f32 v22, -v19, v29, 1.0
	v_fma_f32 v22, v22, v23, v29
	v_div_fixup_f32 v19, v22, v19, 1.0
	v_rcp_f32_e32 v23, v18
	v_pk_add_f32 v[20:21], v[20:21], 1.0 op_sel_hi:[1,0]
	v_fma_f32 v28, -v18, v23, 1.0
	v_fmac_f32_e32 v23, v28, v23
	v_fma_f32 v30, -v18, v23, 1.0
	v_fma_f32 v29, v30, v23, v23
	v_fma_f32 v22, -v18, v29, 1.0
	v_fma_f32 v22, v22, v23, v29
	v_div_fixup_f32 v18, v22, v18, 1.0
	v_mul_f32_e32 v22, 0xbfb8aa3b, v24
	v_mul_f32_e32 v23, 0xbfb8aa3b, v25
	v_exp_f32_e32 v22, v22
	v_exp_f32_e32 v23, v23
	v_pk_mul_f32 v[18:19], v[18:19], s[20:21] op_sel_hi:[1,0]
	v_pk_add_f32 v[22:23], v[22:23], 1.0 op_sel_hi:[1,0]
	s_nop 0
	v_rcp_f32_e32 v25, v23
	v_cvt_pk_bf16_f32 v18, v18, v19
	v_fma_f32 v28, -v23, v25, 1.0
	v_fmac_f32_e32 v25, v28, v25
	v_fma_f32 v30, -v23, v25, 1.0
	v_fma_f32 v29, v30, v25, v25
	v_fma_f32 v24, -v23, v29, 1.0
	v_fma_f32 v24, v24, v25, v29
	v_div_fixup_f32 v23, v24, v23, 1.0
	v_rcp_f32_e32 v25, v22
	s_nop 0
	v_fma_f32 v28, -v22, v25, 1.0
	v_fmac_f32_e32 v25, v28, v25
	v_fma_f32 v30, -v22, v25, 1.0
	v_fma_f32 v29, v30, v25, v25
	v_fma_f32 v24, -v22, v29, 1.0
	v_fma_f32 v24, v24, v25, v29
	v_div_fixup_f32 v22, v24, v22, 1.0
	v_mul_f32_e32 v24, 0xbfb8aa3b, v26
	v_mul_f32_e32 v25, 0xbfb8aa3b, v27
	v_exp_f32_e32 v24, v24
	v_exp_f32_e32 v25, v25
	v_pk_mul_f32 v[22:23], v[22:23], s[20:21] op_sel_hi:[1,0]
	v_pk_add_f32 v[24:25], v[24:25], 1.0 op_sel_hi:[1,0]
	s_nop 0
	v_rcp_f32_e32 v27, v25
	v_cvt_pk_bf16_f32 v19, v22, v23
	v_fma_f32 v28, -v25, v27, 1.0
	v_fmac_f32_e32 v27, v28, v27
	v_fma_f32 v30, -v25, v27, 1.0
	v_fma_f32 v29, v30, v27, v27
	v_fma_f32 v26, -v25, v29, 1.0
	v_fma_f32 v26, v26, v27, v29
	v_div_fixup_f32 v25, v26, v25, 1.0
	v_rcp_f32_e32 v27, v24
	s_nop 0
	v_fma_f32 v28, -v24, v27, 1.0
	v_fmac_f32_e32 v27, v28, v27
	v_fma_f32 v30, -v24, v27, 1.0
	v_fma_f32 v29, v30, v27, v27
	v_fma_f32 v26, -v24, v29, 1.0
	v_fma_f32 v26, v26, v27, v29
	v_div_fixup_f32 v24, v26, v24, 1.0
	v_rcp_f32_e32 v27, v21
	v_pk_mul_f32 v[24:25], v[24:25], s[20:21] op_sel_hi:[1,0]
	v_fma_f32 v28, -v21, v27, 1.0
	v_fmac_f32_e32 v27, v28, v27
	v_fma_f32 v30, -v21, v27, 1.0
	v_fma_f32 v29, v30, v27, v27
	v_fma_f32 v26, -v21, v29, 1.0
	v_fma_f32 v26, v26, v27, v29
	v_div_fixup_f32 v21, v26, v21, 1.0
	v_rcp_f32_e32 v27, v20
	s_mov_b64 s[4:5], 0x58000
	v_fma_f32 v28, -v20, v27, 1.0
	v_fmac_f32_e32 v27, v28, v27
	v_fma_f32 v30, -v20, v27, 1.0
	v_fma_f32 v29, v30, v27, v27
	v_fma_f32 v26, -v20, v29, 1.0
	v_fma_f32 v26, v26, v27, v29
	v_div_fixup_f32 v20, v26, v20, 1.0
	v_pk_mul_f32 v[26:27], v[20:21], s[20:21] op_sel_hi:[1,0]
	v_lshl_add_u64 v[20:21], v[114:115], 0, v[34:35]
	v_lshl_add_u64 v[28:29], v[20:21], 0, v[116:117]
	v_cvt_pk_bf16_f32 v20, v24, v25
	v_cvt_pk_bf16_f32 v21, v26, v27
	global_store_dwordx4 v[28:29], v[18:21], off
	s_nop 1
	v_lshl_add_u64 v[18:19], v[144:145], 0, s[4:5]
	v_pk_add_f32 v[20:21], v[10:11], v[204:205]
	v_pk_add_f32 v[14:15], v[14:15], v[200:201]
	v_pk_add_f32 v[12:13], v[12:13], v[206:207]
	v_mul_f32_e32 v10, 0xbfb8aa3b, v14
	v_mul_f32_e32 v11, 0xbfb8aa3b, v15
	v_exp_f32_e32 v10, v10
	v_exp_f32_e32 v11, v11
	v_pk_add_f32 v[16:17], v[16:17], v[202:203]
	v_mul_f32_e32 v12, 0xbfb8aa3b, v12
	v_mul_f32_e32 v13, 0xbfb8aa3b, v13
	v_pk_add_f32 v[10:11], v[10:11], 1.0 op_sel_hi:[1,0]
	v_exp_f32_e32 v12, v12
; __device__ __forceinline__ u32x4 pack8(f32x4 v0, f32x4 v1) { u32x4 o; o.x = pkbf(v0.x, v0.y); o.y = pkbf(v0.z, v0.w); o.z = pkbf(v1.x, v1.y); o.w = pkbf(v1.z, v1.w); return o; }
;     __device__ __forceinline__ float f(float x) const { return -0.6065306597126334f * sigmoidf_(x); }
;     __device__ __forceinline__ void operator()(int row, int col, f32x4 v0, f32x4 v1) const { *(u32x4*)(G + (size_t)row * 1024 + col) = pack8(v0, v1); }
;     __device__ __forceinline__ void operator()(const pg8::f32x4 (&acc)[2][2][4][2], const pg8::Unit& u, int wr, int wc, int fr, int fq) const {
;         const int row0 = u.pm * 256 + wr * 64 + fr, col0 = u.pn * 256 + wc * 32 + 8 * fq;
; #pragma unroll
;         for (int ai = 0; ai < 2; ++ai)
; #pragma unroll
;             for (int m = 0; m < 4; ++m)
; #pragma unroll
;                 for (int bj = 0; bj < 2; ++bj) { op(row0 + ai * 128 + m * 16, col0 + bj * 128, acc[ai][bj][m][0], acc[ai][bj][m][1]); asm volatile("" ::: "memory"); }
;     __device__ __forceinline__ void operator()(int row, int col, f32x4 v0, f32x4 v1) const {
;         const f32x4 b0 = *(const f32x4*)(w0 + col), b1 = *(const f32x4*)(w0 + col + 4);
;         v0 += b0; v1 += b1;
;         v0 = (f32x4){f(v0.x), f(v0.y), f(v0.z), f(v0.w)}; v1 = (f32x4){f(v1.x), f(v1.y), f(v1.z), f(v1.w)};
;         bf16_t* dst = (col < 1024 ? D0 : D1) + (size_t)row * 1024 + (col & 1023);
;         *(u32x4*)dst = pack8(v0, v1);
	v_rcp_f32_e32 v15, v11
	v_exp_f32_e32 v13, v13
	v_fma_f32 v22, -v11, v15, 1.0
	v_fmac_f32_e32 v15, v22, v15
	v_fma_f32 v24, -v11, v15, 1.0
	v_fma_f32 v23, v24, v15, v15
	v_fma_f32 v14, -v11, v23, 1.0
	v_fma_f32 v14, v14, v15, v23
	v_div_fixup_f32 v11, v14, v11, 1.0
	v_rcp_f32_e32 v15, v10
	v_pk_add_f32 v[12:13], v[12:13], 1.0 op_sel_hi:[1,0]
	v_fma_f32 v22, -v10, v15, 1.0
	v_fmac_f32_e32 v15, v22, v15
	v_fma_f32 v24, -v10, v15, 1.0
	v_fma_f32 v23, v24, v15, v15
	v_fma_f32 v14, -v10, v23, 1.0
	v_fma_f32 v14, v14, v15, v23
	v_div_fixup_f32 v10, v14, v10, 1.0
	v_mul_f32_e32 v14, 0xbfb8aa3b, v16
	v_mul_f32_e32 v15, 0xbfb8aa3b, v17
	v_exp_f32_e32 v14, v14
	v_exp_f32_e32 v15, v15
	v_pk_mul_f32 v[10:11], v[10:11], s[20:21] op_sel_hi:[1,0]
	v_pk_add_f32 v[14:15], v[14:15], 1.0 op_sel_hi:[1,0]
	s_nop 0
	v_rcp_f32_e32 v17, v15
	v_cvt_pk_bf16_f32 v10, v10, v11
	v_fma_f32 v22, -v15, v17, 1.0
	v_fmac_f32_e32 v17, v22, v17
	v_fma_f32 v24, -v15, v17, 1.0
	v_fma_f32 v23, v24, v17, v17
	v_fma_f32 v16, -v15, v23, 1.0
	v_fma_f32 v16, v16, v17, v23
	v_div_fixup_f32 v15, v16, v15, 1.0
	v_rcp_f32_e32 v17, v14
	s_nop 0
	v_fma_f32 v22, -v14, v17, 1.0
	v_fmac_f32_e32 v17, v22, v17
	v_fma_f32 v24, -v14, v17, 1.0
	v_fma_f32 v23, v24, v17, v17
	v_fma_f32 v16, -v14, v23, 1.0
	v_fma_f32 v16, v16, v17, v23
	v_div_fixup_f32 v14, v16, v14, 1.0
	v_mul_f32_e32 v16, 0xbfb8aa3b, v20
	v_mul_f32_e32 v17, 0xbfb8aa3b, v21
	v_exp_f32_e32 v16, v16
	v_exp_f32_e32 v17, v17
	v_pk_mul_f32 v[14:15], v[14:15], s[20:21] op_sel_hi:[1,0]
	v_pk_add_f32 v[16:17], v[16:17], 1.0 op_sel_hi:[1,0]
	s_nop 0
	v_rcp_f32_e32 v21, v17
	v_cvt_pk_bf16_f32 v11, v14, v15
	v_fma_f32 v22, -v17, v21, 1.0
	v_fmac_f32_e32 v21, v22, v21
	v_fma_f32 v24, -v17, v21, 1.0
	v_fma_f32 v23, v24, v21, v21
	v_fma_f32 v20, -v17, v23, 1.0
	v_fma_f32 v20, v20, v21, v23
	v_div_fixup_f32 v17, v20, v17, 1.0
	v_rcp_f32_e32 v21, v16
	s_nop 0
	v_fma_f32 v22, -v16, v21, 1.0
	v_fmac_f32_e32 v21, v22, v21
	v_fma_f32 v24, -v16, v21, 1.0
	v_fma_f32 v23, v24, v21, v21
	v_fma_f32 v20, -v16, v23, 1.0
	v_fma_f32 v20, v20, v21, v23
	v_div_fixup_f32 v16, v20, v16, 1.0
	v_rcp_f32_e32 v21, v13
	v_pk_mul_f32 v[16:17], v[16:17], s[20:21] op_sel_hi:[1,0]
	v_fma_f32 v22, -v13, v21, 1.0
	v_fmac_f32_e32 v21, v22, v21
	v_fma_f32 v24, -v13, v21, 1.0
	v_fma_f32 v23, v24, v21, v21
	v_fma_f32 v20, -v13, v23, 1.0
	v_fma_f32 v20, v20, v21, v23
	v_div_fixup_f32 v13, v20, v13, 1.0
	v_rcp_f32_e32 v21, v12
	s_nop 0
	v_fma_f32 v22, -v12, v21, 1.0
	v_fmac_f32_e32 v21, v22, v21
	v_fma_f32 v24, -v12, v21, 1.0
	v_fma_f32 v23, v24, v21, v21
	v_fma_f32 v20, -v12, v23, 1.0
	v_fma_f32 v20, v20, v21, v23
	v_div_fixup_f32 v12, v20, v12, 1.0
	v_pk_mul_f32 v[20:21], v[12:13], s[20:21] op_sel_hi:[1,0]
	v_lshl_add_u64 v[12:13], v[122:123], 0, v[18:19]
	v_lshl_add_u64 v[22:23], v[12:13], 0, v[0:1]
	v_cvt_pk_bf16_f32 v12, v16, v17
	v_cvt_pk_bf16_f32 v13, v20, v21
	global_store_dwordx4 v[22:23], v[10:13], off
	s_nop 1
	v_pk_add_f32 v[10:11], v[2:3], v[212:213]
	v_pk_add_f32 v[6:7], v[6:7], v[208:209]
	v_pk_add_f32 v[4:5], v[4:5], v[214:215]
	v_mul_f32_e32 v0, 0xbfb8aa3b, v6
	v_exp_f32_e32 v2, v0
	v_mul_f32_e32 v0, 0xbfb8aa3b, v7
	v_exp_f32_e32 v3, v0
	v_pk_add_f32 v[8:9], v[8:9], v[210:211]
	v_pk_add_f32 v[2:3], v[2:3], 1.0 op_sel_hi:[1,0]
	s_nop 0
	v_rcp_f32_e32 v6, v3
	s_nop 0
	v_fma_f32 v7, -v3, v6, 1.0
	v_fmac_f32_e32 v6, v7, v6
	v_fma_f32 v13, -v3, v6, 1.0
	v_fma_f32 v12, v13, v6, v6
	v_fma_f32 v0, -v3, v12, 1.0
	v_fma_f32 v0, v0, v6, v12
	v_div_fixup_f32 v3, v0, v3, 1.0
	v_rcp_f32_e32 v6, v2
	s_nop 0
	v_fma_f32 v7, -v2, v6, 1.0
	v_fmac_f32_e32 v6, v7, v6
	v_fma_f32 v13, -v2, v6, 1.0
	v_fma_f32 v12, v13, v6, v6
	v_fma_f32 v0, -v2, v12, 1.0
	v_fma_f32 v0, v0, v6, v12
	v_div_fixup_f32 v2, v0, v2, 1.0
	v_mul_f32_e32 v0, 0xbfb8aa3b, v8
	v_exp_f32_e32 v6, v0
	v_mul_f32_e32 v0, 0xbfb8aa3b, v9
	v_exp_f32_e32 v7, v0
	v_pk_mul_f32 v[2:3], v[2:3], s[20:21] op_sel_hi:[1,0]
	v_pk_add_f32 v[6:7], v[6:7], 1.0 op_sel_hi:[1,0]
	s_nop 0
	v_rcp_f32_e32 v8, v7
	v_cvt_pk_bf16_f32 v2, v2, v3
	v_fma_f32 v9, -v7, v8, 1.0
	v_fmac_f32_e32 v8, v9, v8
	v_fma_f32 v13, -v7, v8, 1.0
	v_fma_f32 v12, v13, v8, v8
	v_fma_f32 v0, -v7, v12, 1.0
	v_fma_f32 v0, v0, v8, v12
	v_div_fixup_f32 v7, v0, v7, 1.0
	v_rcp_f32_e32 v8, v6
	s_nop 0
	v_fma_f32 v9, -v6, v8, 1.0
	v_fmac_f32_e32 v8, v9, v8
	v_fma_f32 v13, -v6, v8, 1.0
	v_fma_f32 v12, v13, v8, v8
	v_fma_f32 v0, -v6, v12, 1.0
	v_fma_f32 v0, v0, v8, v12
	v_div_fixup_f32 v6, v0, v6, 1.0
	v_mul_f32_e32 v0, 0xbfb8aa3b, v10
	v_exp_f32_e32 v8, v0
	v_mul_f32_e32 v0, 0xbfb8aa3b, v11
	v_exp_f32_e32 v9, v0
	v_pk_mul_f32 v[6:7], v[6:7], s[20:21] op_sel_hi:[1,0]
	v_pk_add_f32 v[8:9], v[8:9], 1.0 op_sel_hi:[1,0]
	s_nop 0
	v_rcp_f32_e32 v10, v9
	v_cvt_pk_bf16_f32 v3, v6, v7
	v_fma_f32 v11, -v9, v10, 1.0
	v_fmac_f32_e32 v10, v11, v10
	v_fma_f32 v13, -v9, v10, 1.0
	v_fma_f32 v12, v13, v10, v10
	v_fma_f32 v0, -v9, v12, 1.0
	v_fma_f32 v0, v0, v10, v12
	v_div_fixup_f32 v9, v0, v9, 1.0
	v_rcp_f32_e32 v10, v8
	s_nop 0
	v_fma_f32 v11, -v8, v10, 1.0
	v_fmac_f32_e32 v10, v11, v10
	v_fma_f32 v13, -v8, v10, 1.0
	v_fma_f32 v12, v13, v10, v10
	v_fma_f32 v0, -v8, v12, 1.0
	v_fma_f32 v0, v0, v10, v12
	v_div_fixup_f32 v8, v0, v8, 1.0
	v_mul_f32_e32 v0, 0xbfb8aa3b, v4
	v_exp_f32_e32 v4, v0
	v_mul_f32_e32 v0, 0xbfb8aa3b, v5
	v_exp_f32_e32 v5, v0
	v_pk_mul_f32 v[8:9], v[8:9], s[20:21] op_sel_hi:[1,0]
	v_pk_add_f32 v[4:5], v[4:5], 1.0 op_sel_hi:[1,0]
	s_nop 0
	v_rcp_f32_e32 v10, v5
	s_nop 0
	v_fma_f32 v11, -v5, v10, 1.0
	v_fmac_f32_e32 v10, v11, v10
	v_fma_f32 v13, -v5, v10, 1.0
	v_fma_f32 v12, v13, v10, v10
	v_fma_f32 v0, -v5, v12, 1.0
	v_fma_f32 v0, v0, v10, v12
	v_div_fixup_f32 v5, v0, v5, 1.0
	v_rcp_f32_e32 v10, v4
	s_mov_b64 s[4:5], -1
	v_fma_f32 v11, -v4, v10, 1.0
	v_fmac_f32_e32 v10, v11, v10
	v_fma_f32 v13, -v4, v10, 1.0
	v_fma_f32 v12, v13, v10, v10
	v_fma_f32 v0, -v4, v12, 1.0
	v_fma_f32 v0, v0, v10, v12
	v_div_fixup_f32 v4, v0, v4, 1.0
	v_pk_mul_f32 v[10:11], v[4:5], s[20:21] op_sel_hi:[1,0]
	v_lshl_add_u64 v[4:5], v[114:115], 0, v[18:19]
	v_lshl_add_u64 v[12:13], v[4:5], 0, v[116:117]
	v_cvt_pk_bf16_f32 v4, v8, v9
	v_cvt_pk_bf16_f32 v5, v10, v11
	global_store_dwordx4 v[12:13], v[2:5], off
	s_and_b64 vcc, exec, s[40:41]
	s_cbranch_vccnz .LBB0_371
	s_andn2_b64 vcc, exec, s[52:53]
	s_cbranch_vccnz .LBB0_370
	s_barrier
	s_branch .LBB0_370

; __device__ __forceinline__ u32x4 pack8(f32x4 v0, f32x4 v1) { u32x4 o; o.x = pkbf(v0.x, v0.y); o.y = pkbf(v0.z, v0.w); o.z = pkbf(v1.x, v1.y); o.w = pkbf(v1.z, v1.w); return o; }
; __device__ __forceinline__ f32x4 sig4(f32x4 v) { return (f32x4){sigmoidf_(v.x), sigmoidf_(v.y), sigmoidf_(v.z), sigmoidf_(v.w)}; }
;     __device__ __forceinline__ void operator()(int row, int col, f32x4 v0, f32x4 v1) const { *(u32x4*)(G + (size_t)row * 1024 + col) = pack8(v0, v1); }
;     __device__ __forceinline__ void operator()(const pg8::f32x4 (&acc)[2][2][4][2], const pg8::Unit& u, int wr, int wc, int fr, int fq) const {
;         const int row0 = u.pm * 256 + wr * 64 + fr, col0 = u.pn * 256 + wc * 32 + 8 * fq;
; #pragma unroll
;         for (int ai = 0; ai < 2; ++ai)
; #pragma unroll
;             for (int m = 0; m < 4; ++m)
; #pragma unroll
;                 for (int bj = 0; bj < 2; ++bj) { op(row0 + ai * 128 + m * 16, col0 + bj * 128, acc[ai][bj][m][0], acc[ai][bj][m][1]); asm volatile("" ::: "memory"); }
;     __device__ __forceinline__ void operator()(int row, int col, f32x4 v0, f32x4 v1) const {
;         const f32x4 b0 = *(const f32x4*)(a0 + col), b1 = *(const f32x4*)(a0 + col + 4);
;         v0 = sig4(v0 + b0); v1 = sig4(v1 + b1);
;         bf16_t* dst = (col < 1024 ? A0 : A1) + (size_t)row * 1024 + (col & 1023);
;         *(u32x4*)dst = pack8(v0, v1);
.LBB0_406:
	v_lshl_or_b32 v152, s78, 8, v160
	v_ashrrev_i32_e32 v153, 31, v152
	v_lshl_add_u64 v[146:147], v[152:153], 2, s[44:45]
	global_load_dwordx4 v[200:203], v[146:147], off
	global_load_dwordx4 v[204:207], v[146:147], off offset:16
	global_load_dwordx4 v[208:211], v[146:147], off offset:512
	global_load_dwordx4 v[212:215], v[146:147], off offset:528
	v_lshl_add_u32 v150, s27, 8, v158
	v_ashrrev_i32_e32 v151, 31, v150
	v_lshlrev_b64 v[148:149], 11, v[150:151]
	s_waitcnt vmcnt(0)
	v_pk_add_f32 v[122:123], v[122:123], v[204:205]
	v_pk_add_f32 v[126:127], v[126:127], v[200:201]
	v_pk_add_f32 v[164:165], v[128:129], v[202:203]
	v_mul_f32_e32 v0, 0xbfb8aa3b, v126
	v_exp_f32_e32 v126, v0
	v_mul_f32_e32 v0, 0xbfb8aa3b, v127
	v_exp_f32_e32 v127, v0
	v_pk_add_f32 v[124:125], v[124:125], v[206:207]
	v_mov_b32_e32 v132, s60
	v_mov_b32_e32 v133, s18
	v_pk_add_f32 v[126:127], v[126:127], 1.0 op_sel_hi:[1,0]
	s_nop 0
	v_rcp_f32_e32 v128, v127
	s_nop 0
	v_fma_f32 v129, -v127, v128, 1.0
	v_fmac_f32_e32 v128, v129, v128
	v_fma_f32 v153, -v127, v128, 1.0
	v_fma_f32 v151, v153, v128, v128
	v_fma_f32 v0, -v127, v151, 1.0
	v_fma_f32 v0, v0, v128, v151
	v_div_fixup_f32 v128, v0, v127, 1.0
	v_rcp_f32_e32 v127, v126
	s_nop 0
	v_fma_f32 v129, -v126, v127, 1.0
	v_fmac_f32_e32 v127, v129, v127
	v_fma_f32 v153, -v126, v127, 1.0
	v_fma_f32 v151, v153, v127, v127
	v_fma_f32 v0, -v126, v151, 1.0
	v_fma_f32 v0, v0, v127, v151
	v_div_fixup_f32 v129, v0, v126, 1.0
	v_mul_f32_e32 v0, 0xbfb8aa3b, v164
	v_exp_f32_e32 v126, v0
	v_mul_f32_e32 v0, 0xbfb8aa3b, v165
	v_exp_f32_e32 v127, v0
	s_nop 0
	v_pk_add_f32 v[126:127], v[126:127], 1.0 op_sel_hi:[1,0]
	s_nop 0
	v_rcp_f32_e32 v151, v127
	s_nop 0
	v_fma_f32 v153, -v127, v151, 1.0
	v_fmac_f32_e32 v151, v153, v151
	v_fma_f32 v163, -v127, v151, 1.0
	v_fma_f32 v162, v163, v151, v151
	v_fma_f32 v0, -v127, v162, 1.0
	v_fma_f32 v0, v0, v151, v162
	v_div_fixup_f32 v151, v0, v127, 1.0
	v_rcp_f32_e32 v127, v126
	s_nop 0
	v_fma_f32 v153, -v126, v127, 1.0
	v_fmac_f32_e32 v127, v153, v127
	v_fma_f32 v163, -v126, v127, 1.0
	v_fma_f32 v162, v163, v127, v127
	v_fma_f32 v0, -v126, v162, 1.0
	v_fma_f32 v0, v0, v127, v162
	v_div_fixup_f32 v153, v0, v126, 1.0
	v_mul_f32_e32 v0, 0xbfb8aa3b, v122
	v_exp_f32_e32 v122, v0
	v_mul_f32_e32 v0, 0xbfb8aa3b, v123
	v_exp_f32_e32 v123, v0
	s_nop 0
	v_pk_add_f32 v[122:123], v[122:123], 1.0 op_sel_hi:[1,0]
	s_nop 0
	v_rcp_f32_e32 v126, v123
	s_nop 0
	v_fma_f32 v127, -v123, v126, 1.0
	v_fmac_f32_e32 v126, v127, v126
	v_fma_f32 v131, -v123, v126, 1.0
	v_fma_f32 v130, v131, v126, v126
	v_fma_f32 v0, -v123, v130, 1.0
	v_fma_f32 v0, v0, v126, v130
	v_div_fixup_f32 v162, v0, v123, 1.0
	v_rcp_f32_e32 v123, v122
	v_mov_b32_e32 v131, s39
	v_fma_f32 v126, -v122, v123, 1.0
	v_fmac_f32_e32 v123, v126, v123
	v_fma_f32 v130, -v122, v123, 1.0
	v_fma_f32 v127, v130, v123, v123
	v_fma_f32 v0, -v122, v127, 1.0
	v_fma_f32 v0, v0, v123, v127
	v_div_fixup_f32 v163, v0, v122, 1.0
	v_mul_f32_e32 v0, 0xbfb8aa3b, v124
	v_exp_f32_e32 v122, v0
	v_mul_f32_e32 v0, 0xbfb8aa3b, v125
	v_exp_f32_e32 v123, v0
	v_mov_b32_e32 v130, s61
	v_pk_add_f32 v[122:123], v[122:123], 1.0 op_sel_hi:[1,0]
	s_nop 0
	v_rcp_f32_e32 v124, v123
	s_nop 0
	v_fma_f32 v125, -v123, v124, 1.0
	v_fmac_f32_e32 v124, v125, v124
	v_fma_f32 v127, -v123, v124, 1.0
	v_fma_f32 v126, v127, v124, v124
	v_fma_f32 v0, -v123, v126, 1.0
	v_fma_f32 v0, v0, v124, v126
	v_div_fixup_f32 v125, v0, v123, 1.0
	v_div_scale_f32 v0, s[4:5], v122, v122, 1.0
	v_rcp_f32_e32 v123, v0
	s_nop 0
	v_fma_f32 v124, -v0, v123, 1.0
	v_fmac_f32_e32 v123, v124, v123
	v_div_scale_f32 v124, vcc, 1.0, v122, 1.0
	v_mul_f32_e32 v126, v124, v123
	v_fma_f32 v127, -v0, v126, v124
	v_fmac_f32_e32 v126, v127, v123
	v_fma_f32 v0, -v0, v126, v124
	v_div_fmas_f32 v0, v0, v123, v126
	v_cmp_gt_i32_e32 vcc, s66, v152
	v_div_fixup_f32 v166, v0, v122, 1.0
	v_and_b32_e32 v0, 0x378, v152
	v_cndmask_b32_e32 v127, v130, v131, vcc
	v_cndmask_b32_e32 v126, v132, v133, vcc
	v_lshl_add_u64 v[122:123], v[126:127], 0, v[148:149]
	v_lshlrev_b32_e32 v0, 1, v0
	v_lshl_add_u64 v[164:165], v[122:123], 0, v[0:1]
	v_cvt_pk_bf16_f32 v122, v129, v128
	v_cvt_pk_bf16_f32 v123, v153, v151
	v_cvt_pk_bf16_f32 v124, v163, v162
	v_cvt_pk_bf16_f32 v125, v166, v125
	global_store_dwordx4 v[164:165], v[122:125], off
	v_or_b32_e32 v128, 0x80, v152
	v_pk_add_f32 v[114:115], v[114:115], v[212:213]
	v_pk_add_f32 v[118:119], v[118:119], v[208:209]
	v_pk_add_f32 v[120:121], v[120:121], v[210:211]
	v_mul_f32_e32 v118, 0xbfb8aa3b, v118
	v_mul_f32_e32 v119, 0xbfb8aa3b, v119
	v_exp_f32_e32 v118, v118
	v_exp_f32_e32 v119, v119
	v_mul_f32_e32 v114, 0xbfb8aa3b, v114
	v_mul_f32_e32 v115, 0xbfb8aa3b, v115
	v_exp_f32_e32 v114, v114
	v_pk_add_f32 v[118:119], v[118:119], 1.0 op_sel_hi:[1,0]
	v_exp_f32_e32 v115, v115
	v_rcp_f32_e32 v151, v119
	v_pk_add_f32 v[114:115], v[114:115], 1.0 op_sel_hi:[1,0]
	v_pk_add_f32 v[116:117], v[116:117], v[214:215]
	v_fma_f32 v153, -v119, v151, 1.0
	v_fmac_f32_e32 v151, v153, v151
	v_fma_f32 v163, -v119, v151, 1.0
	v_fma_f32 v162, v163, v151, v151
	v_fma_f32 v129, -v119, v162, 1.0
	v_fma_f32 v129, v129, v151, v162
	v_div_fixup_f32 v129, v129, v119, 1.0
	v_rcp_f32_e32 v151, v118
	s_nop 0
	v_fma_f32 v153, -v118, v151, 1.0
	v_fmac_f32_e32 v151, v153, v151
	v_fma_f32 v163, -v118, v151, 1.0
	v_fma_f32 v162, v163, v151, v151
	v_fma_f32 v119, -v118, v162, 1.0
	v_fma_f32 v119, v119, v151, v162
	v_div_fixup_f32 v151, v119, v118, 1.0
	v_mul_f32_e32 v118, 0xbfb8aa3b, v120
	v_mul_f32_e32 v119, 0xbfb8aa3b, v121
	v_exp_f32_e32 v118, v118
	v_exp_f32_e32 v119, v119
	s_nop 0
	v_pk_add_f32 v[118:119], v[118:119], 1.0 op_sel_hi:[1,0]
	s_nop 0
; __device__ __forceinline__ u32x4 pack8(f32x4 v0, f32x4 v1) { u32x4 o; o.x = pkbf(v0.x, v0.y); o.y = pkbf(v0.z, v0.w); o.z = pkbf(v1.x, v1.y); o.w = pkbf(v1.z, v1.w); return o; }
; __device__ __forceinline__ f32x4 sig4(f32x4 v) { return (f32x4){sigmoidf_(v.x), sigmoidf_(v.y), sigmoidf_(v.z), sigmoidf_(v.w)}; }
;     __device__ __forceinline__ void operator()(int row, int col, f32x4 v0, f32x4 v1) const { *(u32x4*)(G + (size_t)row * 1024 + col) = pack8(v0, v1); }
;     __device__ __forceinline__ void operator()(const pg8::f32x4 (&acc)[2][2][4][2], const pg8::Unit& u, int wr, int wc, int fr, int fq) const {
;         const int row0 = u.pm * 256 + wr * 64 + fr, col0 = u.pn * 256 + wc * 32 + 8 * fq;
; #pragma unroll
;         for (int ai = 0; ai < 2; ++ai)
; #pragma unroll
;             for (int m = 0; m < 4; ++m)
; #pragma unroll
;                 for (int bj = 0; bj < 2; ++bj) { op(row0 + ai * 128 + m * 16, col0 + bj * 128, acc[ai][bj][m][0], acc[ai][bj][m][1]); asm volatile("" ::: "memory"); }
;     __device__ __forceinline__ void operator()(int row, int col, f32x4 v0, f32x4 v1) const {
;         const f32x4 b0 = *(const f32x4*)(a0 + col), b1 = *(const f32x4*)(a0 + col + 4);
;         v0 = sig4(v0 + b0); v1 = sig4(v1 + b1);
;         bf16_t* dst = (col < 1024 ? A0 : A1) + (size_t)row * 1024 + (col & 1023);
;         *(u32x4*)dst = pack8(v0, v1);
	v_rcp_f32_e32 v121, v119
	s_nop 0
	v_fma_f32 v153, -v119, v121, 1.0
	v_fmac_f32_e32 v121, v153, v121
	v_fma_f32 v163, -v119, v121, 1.0
	v_fma_f32 v162, v163, v121, v121
	v_fma_f32 v120, -v119, v162, 1.0
	v_fma_f32 v120, v120, v121, v162
	v_div_fixup_f32 v153, v120, v119, 1.0
	v_rcp_f32_e32 v120, v118
	s_nop 0
	v_fma_f32 v121, -v118, v120, 1.0
	v_fmac_f32_e32 v120, v121, v120
	v_fma_f32 v163, -v118, v120, 1.0
	v_fma_f32 v162, v163, v120, v120
	v_fma_f32 v119, -v118, v162, 1.0
	v_fma_f32 v119, v119, v120, v162
	v_div_fixup_f32 v162, v119, v118, 1.0
	v_rcp_f32_e32 v119, v115
	s_nop 0
	v_fma_f32 v120, -v115, v119, 1.0
	v_fmac_f32_e32 v119, v120, v119
	v_fma_f32 v122, -v115, v119, 1.0
	v_fma_f32 v121, v122, v119, v119
	v_fma_f32 v118, -v115, v121, 1.0
	v_fma_f32 v118, v118, v119, v121
	v_div_fixup_f32 v124, v118, v115, 1.0
	v_rcp_f32_e32 v118, v114
	s_nop 0
	v_fma_f32 v119, -v114, v118, 1.0
	v_fmac_f32_e32 v118, v119, v118
	v_fma_f32 v121, -v114, v118, 1.0
	v_fma_f32 v120, v121, v118, v118
	v_fma_f32 v115, -v114, v120, 1.0
	v_fma_f32 v115, v115, v118, v120
	v_div_fixup_f32 v125, v115, v114, 1.0
	v_mul_f32_e32 v114, 0xbfb8aa3b, v116
	v_mul_f32_e32 v115, 0xbfb8aa3b, v117
	v_exp_f32_e32 v114, v114
	v_exp_f32_e32 v115, v115
	v_mov_b32_e32 v121, v1
	v_pk_add_f32 v[114:115], v[114:115], 1.0 op_sel_hi:[1,0]
	s_nop 0
	v_rcp_f32_e32 v117, v115
	s_nop 0
	v_fma_f32 v118, -v115, v117, 1.0
	v_fmac_f32_e32 v117, v118, v117
	v_fma_f32 v120, -v115, v117, 1.0
	v_fma_f32 v119, v120, v117, v117
	v_fma_f32 v116, -v115, v119, 1.0
	v_fma_f32 v116, v116, v117, v119
	v_div_fixup_f32 v117, v116, v115, 1.0
	v_div_scale_f32 v115, s[4:5], v114, v114, 1.0
	v_rcp_f32_e32 v116, v115
	s_nop 0
	v_fma_f32 v118, -v115, v116, 1.0
	v_fmac_f32_e32 v116, v118, v116
	v_div_scale_f32 v118, vcc, 1.0, v114, 1.0
	v_mul_f32_e32 v119, v118, v116
	v_fma_f32 v120, -v115, v119, v118
	v_fmac_f32_e32 v119, v120, v116
	v_fma_f32 v115, -v115, v119, v118
	v_div_fmas_f32 v115, v115, v116, v119
	v_cmp_gt_i32_e32 vcc, s66, v128
	v_bitop3_b32 v116, v152, s86, v192 bitop3:0xc8
	v_div_fixup_f32 v163, v115, v114, 1.0
	v_cndmask_b32_e32 v119, v130, v131, vcc
	v_cndmask_b32_e32 v118, v132, v133, vcc
	v_lshl_add_u64 v[114:115], v[118:119], 0, v[148:149]
	v_lshlrev_b32_e32 v120, 1, v116
	v_lshl_add_u64 v[122:123], v[114:115], 0, v[120:121]
	v_cvt_pk_bf16_f32 v114, v151, v129
	v_cvt_pk_bf16_f32 v115, v162, v153
	v_cvt_pk_bf16_f32 v116, v125, v124
	v_cvt_pk_bf16_f32 v117, v163, v117
	global_store_dwordx4 v[122:123], v[114:117], off
	s_nop 1
	v_or_b32_e32 v114, 16, v150
	v_ashrrev_i32_e32 v115, 31, v114
	v_lshlrev_b64 v[122:123], 11, v[114:115]
	v_pk_add_f32 v[106:107], v[106:107], v[204:205]
	v_pk_add_f32 v[110:111], v[110:111], v[200:201]
	v_pk_add_f32 v[112:113], v[112:113], v[202:203]
	v_mul_f32_e32 v110, 0xbfb8aa3b, v110
	v_mul_f32_e32 v111, 0xbfb8aa3b, v111
	v_exp_f32_e32 v110, v110
	v_exp_f32_e32 v111, v111
	v_mul_f32_e32 v106, 0xbfb8aa3b, v106
	v_mul_f32_e32 v107, 0xbfb8aa3b, v107
	v_exp_f32_e32 v106, v106
	v_pk_add_f32 v[110:111], v[110:111], 1.0 op_sel_hi:[1,0]
	v_exp_f32_e32 v107, v107
	v_rcp_f32_e32 v125, v111
	v_pk_add_f32 v[106:107], v[106:107], 1.0 op_sel_hi:[1,0]
	v_pk_add_f32 v[108:109], v[108:109], v[206:207]
	v_fma_f32 v128, -v111, v125, 1.0
	v_fmac_f32_e32 v125, v128, v125
	v_fma_f32 v130, -v111, v125, 1.0
	v_fma_f32 v129, v130, v125, v125
	v_fma_f32 v124, -v111, v129, 1.0
	v_fma_f32 v124, v124, v125, v129
	v_div_fixup_f32 v124, v124, v111, 1.0
	v_rcp_f32_e32 v125, v110
	s_nop 0
	v_fma_f32 v128, -v110, v125, 1.0
	v_fmac_f32_e32 v125, v128, v125
	v_fma_f32 v130, -v110, v125, 1.0
	v_fma_f32 v129, v130, v125, v125
	v_fma_f32 v111, -v110, v129, 1.0
	v_fma_f32 v111, v111, v125, v129
	v_div_fixup_f32 v125, v111, v110, 1.0
	v_mul_f32_e32 v110, 0xbfb8aa3b, v112
	v_mul_f32_e32 v111, 0xbfb8aa3b, v113
	v_exp_f32_e32 v110, v110
	v_exp_f32_e32 v111, v111
	s_nop 0
	v_pk_add_f32 v[110:111], v[110:111], 1.0 op_sel_hi:[1,0]
	s_nop 0
	v_rcp_f32_e32 v113, v111
	s_nop 0
	v_fma_f32 v128, -v111, v113, 1.0
	v_fmac_f32_e32 v113, v128, v113
	v_fma_f32 v130, -v111, v113, 1.0
	v_fma_f32 v129, v130, v113, v113
	v_fma_f32 v112, -v111, v129, 1.0
	v_fma_f32 v112, v112, v113, v129
	v_div_fixup_f32 v112, v112, v111, 1.0
	v_rcp_f32_e32 v113, v110
	s_nop 0
	v_fma_f32 v128, -v110, v113, 1.0
	v_fmac_f32_e32 v113, v128, v113
	v_fma_f32 v130, -v110, v113, 1.0
	v_fma_f32 v129, v130, v113, v113
	v_fma_f32 v111, -v110, v129, 1.0
	v_fma_f32 v111, v111, v113, v129
	v_div_fixup_f32 v113, v111, v110, 1.0
	v_rcp_f32_e32 v111, v107
	s_nop 0
	v_fma_f32 v114, -v107, v111, 1.0
	v_fmac_f32_e32 v111, v114, v111
	v_fma_f32 v116, -v107, v111, 1.0
	v_fma_f32 v115, v116, v111, v111
	v_fma_f32 v110, -v107, v115, 1.0
	v_fma_f32 v110, v110, v111, v115
	v_div_fixup_f32 v114, v110, v107, 1.0
	v_rcp_f32_e32 v110, v106
	s_nop 0
	v_fma_f32 v111, -v106, v110, 1.0
	v_fmac_f32_e32 v110, v111, v110
	v_fma_f32 v116, -v106, v110, 1.0
	v_fma_f32 v115, v116, v110, v110
	v_fma_f32 v107, -v106, v115, 1.0
	v_fma_f32 v107, v107, v110, v115
	v_div_fixup_f32 v115, v107, v106, 1.0
	v_mul_f32_e32 v106, 0xbfb8aa3b, v108
	v_mul_f32_e32 v107, 0xbfb8aa3b, v109
	v_exp_f32_e32 v106, v106
	v_exp_f32_e32 v107, v107
	s_nop 0
	v_pk_add_f32 v[106:107], v[106:107], 1.0 op_sel_hi:[1,0]
	s_nop 0
	v_rcp_f32_e32 v109, v107
	s_nop 0
	v_fma_f32 v110, -v107, v109, 1.0
	v_fmac_f32_e32 v109, v110, v109
	v_fma_f32 v116, -v107, v109, 1.0
	v_fma_f32 v111, v116, v109, v109
	v_fma_f32 v108, -v107, v111, 1.0
	v_fma_f32 v108, v108, v109, v111
	v_div_fixup_f32 v109, v108, v107, 1.0
	v_rcp_f32_e32 v108, v106
	s_nop 0
	v_fma_f32 v110, -v106, v108, 1.0
	v_fmac_f32_e32 v108, v110, v108
; __device__ __forceinline__ u32x4 pack8(f32x4 v0, f32x4 v1) { u32x4 o; o.x = pkbf(v0.x, v0.y); o.y = pkbf(v0.z, v0.w); o.z = pkbf(v1.x, v1.y); o.w = pkbf(v1.z, v1.w); return o; }
; __device__ __forceinline__ f32x4 sig4(f32x4 v) { return (f32x4){sigmoidf_(v.x), sigmoidf_(v.y), sigmoidf_(v.z), sigmoidf_(v.w)}; }
;     __device__ __forceinline__ void operator()(int row, int col, f32x4 v0, f32x4 v1) const { *(u32x4*)(G + (size_t)row * 1024 + col) = pack8(v0, v1); }
;     __device__ __forceinline__ void operator()(const pg8::f32x4 (&acc)[2][2][4][2], const pg8::Unit& u, int wr, int wc, int fr, int fq) const {
;         const int row0 = u.pm * 256 + wr * 64 + fr, col0 = u.pn * 256 + wc * 32 + 8 * fq;
; #pragma unroll
;         for (int ai = 0; ai < 2; ++ai)
; #pragma unroll
;             for (int m = 0; m < 4; ++m)
; #pragma unroll
;                 for (int bj = 0; bj < 2; ++bj) { op(row0 + ai * 128 + m * 16, col0 + bj * 128, acc[ai][bj][m][0], acc[ai][bj][m][1]); asm volatile("" ::: "memory"); }
;     __device__ __forceinline__ void operator()(int row, int col, f32x4 v0, f32x4 v1) const {
;         const f32x4 b0 = *(const f32x4*)(a0 + col), b1 = *(const f32x4*)(a0 + col + 4);
;         v0 = sig4(v0 + b0); v1 = sig4(v1 + b1);
;         bf16_t* dst = (col < 1024 ? A0 : A1) + (size_t)row * 1024 + (col & 1023);
;         *(u32x4*)dst = pack8(v0, v1);
	v_fma_f32 v116, -v106, v108, 1.0
	v_fma_f32 v111, v116, v108, v108
	v_fma_f32 v107, -v106, v111, 1.0
	v_fma_f32 v107, v107, v108, v111
	v_div_fixup_f32 v116, v107, v106, 1.0
	v_lshl_add_u64 v[106:107], v[126:127], 0, v[122:123]
	v_lshl_add_u64 v[110:111], v[106:107], 0, v[0:1]
	v_cvt_pk_bf16_f32 v106, v125, v124
	v_cvt_pk_bf16_f32 v107, v113, v112
	v_cvt_pk_bf16_f32 v108, v115, v114
	v_cvt_pk_bf16_f32 v109, v116, v109
	global_store_dwordx4 v[110:111], v[106:109], off
	v_pk_add_f32 v[98:99], v[98:99], v[212:213]
	v_pk_add_f32 v[102:103], v[102:103], v[208:209]
	v_pk_add_f32 v[104:105], v[104:105], v[210:211]
	v_mul_f32_e32 v102, 0xbfb8aa3b, v102
	v_mul_f32_e32 v103, 0xbfb8aa3b, v103
	v_exp_f32_e32 v102, v102
	v_exp_f32_e32 v103, v103
	v_mul_f32_e32 v98, 0xbfb8aa3b, v98
	v_mul_f32_e32 v99, 0xbfb8aa3b, v99
	v_exp_f32_e32 v98, v98
	v_pk_add_f32 v[102:103], v[102:103], 1.0 op_sel_hi:[1,0]
	v_exp_f32_e32 v99, v99
	v_rcp_f32_e32 v111, v103
	v_pk_add_f32 v[98:99], v[98:99], 1.0 op_sel_hi:[1,0]
	v_pk_add_f32 v[100:101], v[100:101], v[214:215]
	v_fma_f32 v112, -v103, v111, 1.0
	v_fmac_f32_e32 v111, v112, v111
	v_fma_f32 v114, -v103, v111, 1.0
	v_fma_f32 v113, v114, v111, v111
	v_fma_f32 v110, -v103, v113, 1.0
	v_fma_f32 v110, v110, v111, v113
	v_div_fixup_f32 v110, v110, v103, 1.0
	v_rcp_f32_e32 v111, v102
	s_nop 0
	v_fma_f32 v112, -v102, v111, 1.0
	v_fmac_f32_e32 v111, v112, v111
	v_fma_f32 v114, -v102, v111, 1.0
	v_fma_f32 v113, v114, v111, v111
	v_fma_f32 v103, -v102, v113, 1.0
	v_fma_f32 v103, v103, v111, v113
	v_div_fixup_f32 v111, v103, v102, 1.0
	v_mul_f32_e32 v102, 0xbfb8aa3b, v104
	v_mul_f32_e32 v103, 0xbfb8aa3b, v105
	v_exp_f32_e32 v102, v102
	v_exp_f32_e32 v103, v103
	s_nop 0
	v_pk_add_f32 v[102:103], v[102:103], 1.0 op_sel_hi:[1,0]
	s_nop 0
	v_rcp_f32_e32 v105, v103
	s_nop 0
	v_fma_f32 v112, -v103, v105, 1.0
	v_fmac_f32_e32 v105, v112, v105
	v_fma_f32 v114, -v103, v105, 1.0
	v_fma_f32 v113, v114, v105, v105
	v_fma_f32 v104, -v103, v113, 1.0
	v_fma_f32 v104, v104, v105, v113
	v_div_fixup_f32 v104, v104, v103, 1.0
	v_rcp_f32_e32 v105, v102
	s_nop 0
	v_fma_f32 v112, -v102, v105, 1.0
	v_fmac_f32_e32 v105, v112, v105
	v_fma_f32 v114, -v102, v105, 1.0
	v_fma_f32 v113, v114, v105, v105
	v_fma_f32 v103, -v102, v113, 1.0
	v_fma_f32 v103, v103, v105, v113
	v_div_fixup_f32 v105, v103, v102, 1.0
	v_rcp_f32_e32 v103, v99
	s_nop 0
	v_fma_f32 v106, -v99, v103, 1.0
	v_fmac_f32_e32 v103, v106, v103
	v_fma_f32 v108, -v99, v103, 1.0
	v_fma_f32 v107, v108, v103, v103
	v_fma_f32 v102, -v99, v107, 1.0
	v_fma_f32 v102, v102, v103, v107
	v_div_fixup_f32 v106, v102, v99, 1.0
	v_rcp_f32_e32 v102, v98
	s_nop 0
	v_fma_f32 v103, -v98, v102, 1.0
	v_fmac_f32_e32 v102, v103, v102
	v_fma_f32 v108, -v98, v102, 1.0
	v_fma_f32 v107, v108, v102, v102
	v_fma_f32 v99, -v98, v107, 1.0
	v_fma_f32 v99, v99, v102, v107
	v_div_fixup_f32 v107, v99, v98, 1.0
	v_mul_f32_e32 v98, 0xbfb8aa3b, v100
	v_mul_f32_e32 v99, 0xbfb8aa3b, v101
	v_exp_f32_e32 v98, v98
	v_exp_f32_e32 v99, v99
	s_nop 0
	v_pk_add_f32 v[98:99], v[98:99], 1.0 op_sel_hi:[1,0]
	s_nop 0
	v_rcp_f32_e32 v101, v99
	s_nop 0
	v_fma_f32 v102, -v99, v101, 1.0
	v_fmac_f32_e32 v101, v102, v101
	v_fma_f32 v108, -v99, v101, 1.0
	v_fma_f32 v103, v108, v101, v101
	v_fma_f32 v100, -v99, v103, 1.0
	v_fma_f32 v100, v100, v101, v103
	v_div_fixup_f32 v101, v100, v99, 1.0
	v_rcp_f32_e32 v100, v98
	s_nop 0
	v_fma_f32 v102, -v98, v100, 1.0
	v_fmac_f32_e32 v100, v102, v100
	v_fma_f32 v108, -v98, v100, 1.0
	v_fma_f32 v103, v108, v100, v100
	v_fma_f32 v99, -v98, v103, 1.0
	v_fma_f32 v99, v99, v100, v103
	v_div_fixup_f32 v108, v99, v98, 1.0
	v_lshl_add_u64 v[98:99], v[118:119], 0, v[122:123]
	v_lshl_add_u64 v[102:103], v[98:99], 0, v[120:121]
	v_cvt_pk_bf16_f32 v98, v111, v110
	v_cvt_pk_bf16_f32 v99, v105, v104
	v_cvt_pk_bf16_f32 v100, v107, v106
	v_cvt_pk_bf16_f32 v101, v108, v101
	global_store_dwordx4 v[102:103], v[98:101], off
	s_nop 1
	v_or_b32_e32 v98, 32, v150
	v_ashrrev_i32_e32 v99, 31, v98
	v_lshlrev_b64 v[102:103], 11, v[98:99]
	v_pk_add_f32 v[90:91], v[90:91], v[204:205]
	v_pk_add_f32 v[94:95], v[94:95], v[200:201]
	v_pk_add_f32 v[96:97], v[96:97], v[202:203]
	v_mul_f32_e32 v94, 0xbfb8aa3b, v94
	v_mul_f32_e32 v95, 0xbfb8aa3b, v95
	v_exp_f32_e32 v94, v94
	v_exp_f32_e32 v95, v95
	v_mul_f32_e32 v90, 0xbfb8aa3b, v90
	v_mul_f32_e32 v91, 0xbfb8aa3b, v91
	v_exp_f32_e32 v90, v90
	v_pk_add_f32 v[94:95], v[94:95], 1.0 op_sel_hi:[1,0]
	v_exp_f32_e32 v91, v91
	v_rcp_f32_e32 v105, v95
	v_pk_add_f32 v[90:91], v[90:91], 1.0 op_sel_hi:[1,0]
	v_pk_add_f32 v[92:93], v[92:93], v[206:207]
	v_fma_f32 v106, -v95, v105, 1.0
	v_fmac_f32_e32 v105, v106, v105
	v_fma_f32 v108, -v95, v105, 1.0
	v_fma_f32 v107, v108, v105, v105
	v_fma_f32 v104, -v95, v107, 1.0
	v_fma_f32 v104, v104, v105, v107
	v_div_fixup_f32 v104, v104, v95, 1.0
	v_rcp_f32_e32 v105, v94
	s_nop 0
	v_fma_f32 v106, -v94, v105, 1.0
	v_fmac_f32_e32 v105, v106, v105
	v_fma_f32 v108, -v94, v105, 1.0
	v_fma_f32 v107, v108, v105, v105
	v_fma_f32 v95, -v94, v107, 1.0
	v_fma_f32 v95, v95, v105, v107
	v_div_fixup_f32 v105, v95, v94, 1.0
	v_mul_f32_e32 v94, 0xbfb8aa3b, v96
	v_mul_f32_e32 v95, 0xbfb8aa3b, v97
	v_exp_f32_e32 v94, v94
	v_exp_f32_e32 v95, v95
	s_nop 0
	v_pk_add_f32 v[94:95], v[94:95], 1.0 op_sel_hi:[1,0]
	s_nop 0
	v_rcp_f32_e32 v97, v95
	s_nop 0
	v_fma_f32 v106, -v95, v97, 1.0
	v_fmac_f32_e32 v97, v106, v97
	v_fma_f32 v108, -v95, v97, 1.0
	v_fma_f32 v107, v108, v97, v97
	v_fma_f32 v96, -v95, v107, 1.0
	v_fma_f32 v96, v96, v97, v107
	v_div_fixup_f32 v96, v96, v95, 1.0
	v_rcp_f32_e32 v97, v94
	s_nop 0
	v_fma_f32 v106, -v94, v97, 1.0
	v_fmac_f32_e32 v97, v106, v97
	v_fma_f32 v108, -v94, v97, 1.0
; __device__ __forceinline__ u32x4 pack8(f32x4 v0, f32x4 v1) { u32x4 o; o.x = pkbf(v0.x, v0.y); o.y = pkbf(v0.z, v0.w); o.z = pkbf(v1.x, v1.y); o.w = pkbf(v1.z, v1.w); return o; }
; __device__ __forceinline__ f32x4 sig4(f32x4 v) { return (f32x4){sigmoidf_(v.x), sigmoidf_(v.y), sigmoidf_(v.z), sigmoidf_(v.w)}; }
;     __device__ __forceinline__ void operator()(int row, int col, f32x4 v0, f32x4 v1) const { *(u32x4*)(G + (size_t)row * 1024 + col) = pack8(v0, v1); }
;     __device__ __forceinline__ void operator()(const pg8::f32x4 (&acc)[2][2][4][2], const pg8::Unit& u, int wr, int wc, int fr, int fq) const {
;         const int row0 = u.pm * 256 + wr * 64 + fr, col0 = u.pn * 256 + wc * 32 + 8 * fq;
; #pragma unroll
;         for (int ai = 0; ai < 2; ++ai)
; #pragma unroll
;             for (int m = 0; m < 4; ++m)
; #pragma unroll
;                 for (int bj = 0; bj < 2; ++bj) { op(row0 + ai * 128 + m * 16, col0 + bj * 128, acc[ai][bj][m][0], acc[ai][bj][m][1]); asm volatile("" ::: "memory"); }
;     __device__ __forceinline__ void operator()(int row, int col, f32x4 v0, f32x4 v1) const {
;         const f32x4 b0 = *(const f32x4*)(a0 + col), b1 = *(const f32x4*)(a0 + col + 4);
;         v0 = sig4(v0 + b0); v1 = sig4(v1 + b1);
;         bf16_t* dst = (col < 1024 ? A0 : A1) + (size_t)row * 1024 + (col & 1023);
;         *(u32x4*)dst = pack8(v0, v1);
	v_fma_f32 v107, v108, v97, v97
	v_fma_f32 v95, -v94, v107, 1.0
	v_fma_f32 v95, v95, v97, v107
	v_div_fixup_f32 v97, v95, v94, 1.0
	v_rcp_f32_e32 v95, v91
	s_nop 0
	v_fma_f32 v98, -v91, v95, 1.0
	v_fmac_f32_e32 v95, v98, v95
	v_fma_f32 v100, -v91, v95, 1.0
	v_fma_f32 v99, v100, v95, v95
	v_fma_f32 v94, -v91, v99, 1.0
	v_fma_f32 v94, v94, v95, v99
	v_div_fixup_f32 v98, v94, v91, 1.0
	v_rcp_f32_e32 v94, v90
	s_nop 0
	v_fma_f32 v95, -v90, v94, 1.0
	v_fmac_f32_e32 v94, v95, v94
	v_fma_f32 v100, -v90, v94, 1.0
	v_fma_f32 v99, v100, v94, v94
	v_fma_f32 v91, -v90, v99, 1.0
	v_fma_f32 v91, v91, v94, v99
	v_div_fixup_f32 v99, v91, v90, 1.0
	v_mul_f32_e32 v90, 0xbfb8aa3b, v92
	v_mul_f32_e32 v91, 0xbfb8aa3b, v93
	v_exp_f32_e32 v90, v90
	v_exp_f32_e32 v91, v91
	s_nop 0
	v_pk_add_f32 v[90:91], v[90:91], 1.0 op_sel_hi:[1,0]
	s_nop 0
	v_rcp_f32_e32 v93, v91
	s_nop 0
	v_fma_f32 v94, -v91, v93, 1.0
	v_fmac_f32_e32 v93, v94, v93
	v_fma_f32 v100, -v91, v93, 1.0
	v_fma_f32 v95, v100, v93, v93
	v_fma_f32 v92, -v91, v95, 1.0
	v_fma_f32 v92, v92, v93, v95
	v_div_fixup_f32 v93, v92, v91, 1.0
	v_rcp_f32_e32 v92, v90
	s_nop 0
	v_fma_f32 v94, -v90, v92, 1.0
	v_fmac_f32_e32 v92, v94, v92
	v_fma_f32 v100, -v90, v92, 1.0
	v_fma_f32 v95, v100, v92, v92
	v_fma_f32 v91, -v90, v95, 1.0
	v_fma_f32 v91, v91, v92, v95
	v_div_fixup_f32 v100, v91, v90, 1.0
	v_lshl_add_u64 v[90:91], v[126:127], 0, v[102:103]
	v_lshl_add_u64 v[94:95], v[90:91], 0, v[0:1]
	v_cvt_pk_bf16_f32 v90, v105, v104
	v_cvt_pk_bf16_f32 v91, v97, v96
	v_cvt_pk_bf16_f32 v92, v99, v98
	v_cvt_pk_bf16_f32 v93, v100, v93
	global_store_dwordx4 v[94:95], v[90:93], off
	v_pk_add_f32 v[82:83], v[82:83], v[212:213]
	v_pk_add_f32 v[86:87], v[86:87], v[208:209]
	v_pk_add_f32 v[88:89], v[88:89], v[210:211]
	v_mul_f32_e32 v86, 0xbfb8aa3b, v86
	v_mul_f32_e32 v87, 0xbfb8aa3b, v87
	v_exp_f32_e32 v86, v86
	v_exp_f32_e32 v87, v87
	v_mul_f32_e32 v82, 0xbfb8aa3b, v82
	v_mul_f32_e32 v83, 0xbfb8aa3b, v83
	v_exp_f32_e32 v82, v82
	v_pk_add_f32 v[86:87], v[86:87], 1.0 op_sel_hi:[1,0]
	v_exp_f32_e32 v83, v83
	v_rcp_f32_e32 v95, v87
	v_pk_add_f32 v[82:83], v[82:83], 1.0 op_sel_hi:[1,0]
	v_pk_add_f32 v[84:85], v[84:85], v[214:215]
	v_fma_f32 v96, -v87, v95, 1.0
	v_fmac_f32_e32 v95, v96, v95
	v_fma_f32 v98, -v87, v95, 1.0
	v_fma_f32 v97, v98, v95, v95
	v_fma_f32 v94, -v87, v97, 1.0
	v_fma_f32 v94, v94, v95, v97
	v_div_fixup_f32 v94, v94, v87, 1.0
	v_rcp_f32_e32 v95, v86
	s_nop 0
	v_fma_f32 v96, -v86, v95, 1.0
	v_fmac_f32_e32 v95, v96, v95
	v_fma_f32 v98, -v86, v95, 1.0
	v_fma_f32 v97, v98, v95, v95
	v_fma_f32 v87, -v86, v97, 1.0
	v_fma_f32 v87, v87, v95, v97
	v_div_fixup_f32 v95, v87, v86, 1.0
	v_mul_f32_e32 v86, 0xbfb8aa3b, v88
	v_mul_f32_e32 v87, 0xbfb8aa3b, v89
	v_exp_f32_e32 v86, v86
	v_exp_f32_e32 v87, v87
	s_nop 0
	v_pk_add_f32 v[86:87], v[86:87], 1.0 op_sel_hi:[1,0]
	s_nop 0
	v_rcp_f32_e32 v89, v87
	s_nop 0
	v_fma_f32 v96, -v87, v89, 1.0
	v_fmac_f32_e32 v89, v96, v89
	v_fma_f32 v98, -v87, v89, 1.0
	v_fma_f32 v97, v98, v89, v89
	v_fma_f32 v88, -v87, v97, 1.0
	v_fma_f32 v88, v88, v89, v97
	v_div_fixup_f32 v88, v88, v87, 1.0
	v_rcp_f32_e32 v89, v86
	s_nop 0
	v_fma_f32 v96, -v86, v89, 1.0
	v_fmac_f32_e32 v89, v96, v89
	v_fma_f32 v98, -v86, v89, 1.0
	v_fma_f32 v97, v98, v89, v89
	v_fma_f32 v87, -v86, v97, 1.0
	v_fma_f32 v87, v87, v89, v97
	v_div_fixup_f32 v89, v87, v86, 1.0
	v_rcp_f32_e32 v87, v83
	s_nop 0
	v_fma_f32 v90, -v83, v87, 1.0
	v_fmac_f32_e32 v87, v90, v87
	v_fma_f32 v92, -v83, v87, 1.0
	v_fma_f32 v91, v92, v87, v87
	v_fma_f32 v86, -v83, v91, 1.0
	v_fma_f32 v86, v86, v87, v91
	v_div_fixup_f32 v90, v86, v83, 1.0
	v_rcp_f32_e32 v86, v82
	s_nop 0
	v_fma_f32 v87, -v82, v86, 1.0
	v_fmac_f32_e32 v86, v87, v86
	v_fma_f32 v92, -v82, v86, 1.0
	v_fma_f32 v91, v92, v86, v86
	v_fma_f32 v83, -v82, v91, 1.0
	v_fma_f32 v83, v83, v86, v91
	v_div_fixup_f32 v91, v83, v82, 1.0
	v_mul_f32_e32 v82, 0xbfb8aa3b, v84
	v_mul_f32_e32 v83, 0xbfb8aa3b, v85
	v_exp_f32_e32 v82, v82
	v_exp_f32_e32 v83, v83
	s_nop 0
	v_pk_add_f32 v[82:83], v[82:83], 1.0 op_sel_hi:[1,0]
	s_nop 0
	v_rcp_f32_e32 v85, v83
	s_nop 0
	v_fma_f32 v86, -v83, v85, 1.0
	v_fmac_f32_e32 v85, v86, v85
	v_fma_f32 v92, -v83, v85, 1.0
	v_fma_f32 v87, v92, v85, v85
	v_fma_f32 v84, -v83, v87, 1.0
	v_fma_f32 v84, v84, v85, v87
	v_div_fixup_f32 v85, v84, v83, 1.0
	v_rcp_f32_e32 v84, v82
	s_nop 0
	v_fma_f32 v86, -v82, v84, 1.0
	v_fmac_f32_e32 v84, v86, v84
	v_fma_f32 v92, -v82, v84, 1.0
	v_fma_f32 v87, v92, v84, v84
	v_fma_f32 v83, -v82, v87, 1.0
	v_fma_f32 v83, v83, v84, v87
	v_div_fixup_f32 v92, v83, v82, 1.0
	v_lshl_add_u64 v[82:83], v[118:119], 0, v[102:103]
	v_lshl_add_u64 v[86:87], v[82:83], 0, v[120:121]
	v_cvt_pk_bf16_f32 v82, v95, v94
	v_cvt_pk_bf16_f32 v83, v89, v88
	v_cvt_pk_bf16_f32 v84, v91, v90
	v_cvt_pk_bf16_f32 v85, v92, v85
	global_store_dwordx4 v[86:87], v[82:85], off
	s_nop 1
	v_or_b32_e32 v82, 48, v150
	v_ashrrev_i32_e32 v83, 31, v82
	v_lshlrev_b64 v[86:87], 11, v[82:83]
	v_pk_add_f32 v[74:75], v[74:75], v[204:205]
	v_pk_add_f32 v[78:79], v[78:79], v[200:201]
	v_pk_add_f32 v[80:81], v[80:81], v[202:203]
	v_mul_f32_e32 v78, 0xbfb8aa3b, v78
	v_mul_f32_e32 v79, 0xbfb8aa3b, v79
	v_exp_f32_e32 v78, v78
	v_exp_f32_e32 v79, v79
	v_mul_f32_e32 v74, 0xbfb8aa3b, v74
	v_mul_f32_e32 v75, 0xbfb8aa3b, v75
	v_exp_f32_e32 v74, v74
	v_pk_add_f32 v[78:79], v[78:79], 1.0 op_sel_hi:[1,0]
	v_exp_f32_e32 v75, v75
	v_rcp_f32_e32 v89, v79
	v_pk_add_f32 v[74:75], v[74:75], 1.0 op_sel_hi:[1,0]
	v_pk_add_f32 v[76:77], v[76:77], v[206:207]
	v_fma_f32 v90, -v79, v89, 1.0
	v_fmac_f32_e32 v89, v90, v89
	v_fma_f32 v92, -v79, v89, 1.0
	v_fma_f32 v91, v92, v89, v89
	v_fma_f32 v88, -v79, v91, 1.0
; __device__ __forceinline__ u32x4 pack8(f32x4 v0, f32x4 v1) { u32x4 o; o.x = pkbf(v0.x, v0.y); o.y = pkbf(v0.z, v0.w); o.z = pkbf(v1.x, v1.y); o.w = pkbf(v1.z, v1.w); return o; }
; __device__ __forceinline__ f32x4 sig4(f32x4 v) { return (f32x4){sigmoidf_(v.x), sigmoidf_(v.y), sigmoidf_(v.z), sigmoidf_(v.w)}; }
;     __device__ __forceinline__ void operator()(int row, int col, f32x4 v0, f32x4 v1) const { *(u32x4*)(G + (size_t)row * 1024 + col) = pack8(v0, v1); }
;     __device__ __forceinline__ void operator()(const pg8::f32x4 (&acc)[2][2][4][2], const pg8::Unit& u, int wr, int wc, int fr, int fq) const {
;         const int row0 = u.pm * 256 + wr * 64 + fr, col0 = u.pn * 256 + wc * 32 + 8 * fq;
; #pragma unroll
;         for (int ai = 0; ai < 2; ++ai)
; #pragma unroll
;             for (int m = 0; m < 4; ++m)
; #pragma unroll
;                 for (int bj = 0; bj < 2; ++bj) { op(row0 + ai * 128 + m * 16, col0 + bj * 128, acc[ai][bj][m][0], acc[ai][bj][m][1]); asm volatile("" ::: "memory"); }
;     __device__ __forceinline__ void operator()(int row, int col, f32x4 v0, f32x4 v1) const {
;         const f32x4 b0 = *(const f32x4*)(a0 + col), b1 = *(const f32x4*)(a0 + col + 4);
;         v0 = sig4(v0 + b0); v1 = sig4(v1 + b1);
;         bf16_t* dst = (col < 1024 ? A0 : A1) + (size_t)row * 1024 + (col & 1023);
;         *(u32x4*)dst = pack8(v0, v1);
	v_fma_f32 v88, v88, v89, v91
	v_div_fixup_f32 v88, v88, v79, 1.0
	v_rcp_f32_e32 v89, v78
	s_nop 0
	v_fma_f32 v90, -v78, v89, 1.0
	v_fmac_f32_e32 v89, v90, v89
	v_fma_f32 v92, -v78, v89, 1.0
	v_fma_f32 v91, v92, v89, v89
	v_fma_f32 v79, -v78, v91, 1.0
	v_fma_f32 v79, v79, v89, v91
	v_div_fixup_f32 v89, v79, v78, 1.0
	v_mul_f32_e32 v78, 0xbfb8aa3b, v80
	v_mul_f32_e32 v79, 0xbfb8aa3b, v81
	v_exp_f32_e32 v78, v78
	v_exp_f32_e32 v79, v79
	s_nop 0
	v_pk_add_f32 v[78:79], v[78:79], 1.0 op_sel_hi:[1,0]
	s_nop 0
	v_rcp_f32_e32 v81, v79
	s_nop 0
	v_fma_f32 v90, -v79, v81, 1.0
	v_fmac_f32_e32 v81, v90, v81
	v_fma_f32 v92, -v79, v81, 1.0
	v_fma_f32 v91, v92, v81, v81
	v_fma_f32 v80, -v79, v91, 1.0
	v_fma_f32 v80, v80, v81, v91
	v_div_fixup_f32 v80, v80, v79, 1.0
	v_rcp_f32_e32 v81, v78
	s_nop 0
	v_fma_f32 v90, -v78, v81, 1.0
	v_fmac_f32_e32 v81, v90, v81
	v_fma_f32 v92, -v78, v81, 1.0
	v_fma_f32 v91, v92, v81, v81
	v_fma_f32 v79, -v78, v91, 1.0
	v_fma_f32 v79, v79, v81, v91
	v_div_fixup_f32 v81, v79, v78, 1.0
	v_rcp_f32_e32 v79, v75
	s_nop 0
	v_fma_f32 v82, -v75, v79, 1.0
	v_fmac_f32_e32 v79, v82, v79
	v_fma_f32 v84, -v75, v79, 1.0
	v_fma_f32 v83, v84, v79, v79
	v_fma_f32 v78, -v75, v83, 1.0
	v_fma_f32 v78, v78, v79, v83
	v_div_fixup_f32 v82, v78, v75, 1.0
	v_rcp_f32_e32 v78, v74
	s_nop 0
	v_fma_f32 v79, -v74, v78, 1.0
	v_fmac_f32_e32 v78, v79, v78
	v_fma_f32 v84, -v74, v78, 1.0
	v_fma_f32 v83, v84, v78, v78
	v_fma_f32 v75, -v74, v83, 1.0
	v_fma_f32 v75, v75, v78, v83
	v_div_fixup_f32 v83, v75, v74, 1.0
	v_mul_f32_e32 v74, 0xbfb8aa3b, v76
	v_mul_f32_e32 v75, 0xbfb8aa3b, v77
	v_exp_f32_e32 v74, v74
	v_exp_f32_e32 v75, v75
	s_nop 0
	v_pk_add_f32 v[74:75], v[74:75], 1.0 op_sel_hi:[1,0]
	s_nop 0
	v_rcp_f32_e32 v77, v75
	s_nop 0
	v_fma_f32 v78, -v75, v77, 1.0
	v_fmac_f32_e32 v77, v78, v77
	v_fma_f32 v84, -v75, v77, 1.0
	v_fma_f32 v79, v84, v77, v77
	v_fma_f32 v76, -v75, v79, 1.0
	v_fma_f32 v76, v76, v77, v79
	v_div_fixup_f32 v77, v76, v75, 1.0
	v_rcp_f32_e32 v76, v74
	s_nop 0
	v_fma_f32 v78, -v74, v76, 1.0
	v_fmac_f32_e32 v76, v78, v76
	v_fma_f32 v84, -v74, v76, 1.0
	v_fma_f32 v79, v84, v76, v76
	v_fma_f32 v75, -v74, v79, 1.0
	v_fma_f32 v75, v75, v76, v79
	v_div_fixup_f32 v84, v75, v74, 1.0
	v_lshl_add_u64 v[74:75], v[126:127], 0, v[86:87]
	v_lshl_add_u64 v[78:79], v[74:75], 0, v[0:1]
	v_cvt_pk_bf16_f32 v74, v89, v88
	v_cvt_pk_bf16_f32 v75, v81, v80
	v_cvt_pk_bf16_f32 v76, v83, v82
	v_cvt_pk_bf16_f32 v77, v84, v77
	global_store_dwordx4 v[78:79], v[74:77], off
	v_pk_add_f32 v[66:67], v[66:67], v[212:213]
	v_pk_add_f32 v[70:71], v[70:71], v[208:209]
	v_pk_add_f32 v[72:73], v[72:73], v[210:211]
	v_mul_f32_e32 v70, 0xbfb8aa3b, v70
	v_mul_f32_e32 v71, 0xbfb8aa3b, v71
	v_exp_f32_e32 v70, v70
	v_exp_f32_e32 v71, v71
	v_mul_f32_e32 v66, 0xbfb8aa3b, v66
	v_mul_f32_e32 v67, 0xbfb8aa3b, v67
	v_exp_f32_e32 v66, v66
	v_pk_add_f32 v[70:71], v[70:71], 1.0 op_sel_hi:[1,0]
	v_exp_f32_e32 v67, v67
	v_rcp_f32_e32 v79, v71
	v_pk_add_f32 v[66:67], v[66:67], 1.0 op_sel_hi:[1,0]
	v_pk_add_f32 v[68:69], v[68:69], v[214:215]
	v_fma_f32 v80, -v71, v79, 1.0
	v_fmac_f32_e32 v79, v80, v79
	v_fma_f32 v82, -v71, v79, 1.0
	v_fma_f32 v81, v82, v79, v79
	v_fma_f32 v78, -v71, v81, 1.0
	v_fma_f32 v78, v78, v79, v81
	v_div_fixup_f32 v78, v78, v71, 1.0
	v_rcp_f32_e32 v79, v70
	s_nop 0
	v_fma_f32 v80, -v70, v79, 1.0
	v_fmac_f32_e32 v79, v80, v79
	v_fma_f32 v82, -v70, v79, 1.0
	v_fma_f32 v81, v82, v79, v79
	v_fma_f32 v71, -v70, v81, 1.0
	v_fma_f32 v71, v71, v79, v81
	v_div_fixup_f32 v79, v71, v70, 1.0
	v_mul_f32_e32 v70, 0xbfb8aa3b, v72
	v_mul_f32_e32 v71, 0xbfb8aa3b, v73
	v_exp_f32_e32 v70, v70
	v_exp_f32_e32 v71, v71
	s_nop 0
	v_pk_add_f32 v[70:71], v[70:71], 1.0 op_sel_hi:[1,0]
	s_nop 0
	v_rcp_f32_e32 v73, v71
	s_nop 0
	v_fma_f32 v80, -v71, v73, 1.0
	v_fmac_f32_e32 v73, v80, v73
	v_fma_f32 v82, -v71, v73, 1.0
	v_fma_f32 v81, v82, v73, v73
	v_fma_f32 v72, -v71, v81, 1.0
	v_fma_f32 v72, v72, v73, v81
	v_div_fixup_f32 v72, v72, v71, 1.0
	v_rcp_f32_e32 v73, v70
	s_nop 0
	v_fma_f32 v80, -v70, v73, 1.0
	v_fmac_f32_e32 v73, v80, v73
	v_fma_f32 v82, -v70, v73, 1.0
	v_fma_f32 v81, v82, v73, v73
	v_fma_f32 v71, -v70, v81, 1.0
	v_fma_f32 v71, v71, v73, v81
	v_div_fixup_f32 v73, v71, v70, 1.0
	v_rcp_f32_e32 v71, v67
	s_nop 0
	v_fma_f32 v74, -v67, v71, 1.0
	v_fmac_f32_e32 v71, v74, v71
	v_fma_f32 v76, -v67, v71, 1.0
	v_fma_f32 v75, v76, v71, v71
	v_fma_f32 v70, -v67, v75, 1.0
	v_fma_f32 v70, v70, v71, v75
	v_div_fixup_f32 v74, v70, v67, 1.0
	v_rcp_f32_e32 v70, v66
	s_nop 0
	v_fma_f32 v71, -v66, v70, 1.0
	v_fmac_f32_e32 v70, v71, v70
	v_fma_f32 v76, -v66, v70, 1.0
	v_fma_f32 v75, v76, v70, v70
	v_fma_f32 v67, -v66, v75, 1.0
	v_fma_f32 v67, v67, v70, v75
	v_div_fixup_f32 v75, v67, v66, 1.0
	v_mul_f32_e32 v66, 0xbfb8aa3b, v68
	v_mul_f32_e32 v67, 0xbfb8aa3b, v69
	v_exp_f32_e32 v66, v66
	v_exp_f32_e32 v67, v67
	s_nop 0
	v_pk_add_f32 v[66:67], v[66:67], 1.0 op_sel_hi:[1,0]
	s_nop 0
	v_rcp_f32_e32 v69, v67
	s_nop 0
	v_fma_f32 v70, -v67, v69, 1.0
	v_fmac_f32_e32 v69, v70, v69
	v_fma_f32 v76, -v67, v69, 1.0
	v_fma_f32 v71, v76, v69, v69
	v_fma_f32 v68, -v67, v71, 1.0
	v_fma_f32 v68, v68, v69, v71
	v_div_fixup_f32 v69, v68, v67, 1.0
	v_rcp_f32_e32 v68, v66
	s_nop 0
	v_fma_f32 v70, -v66, v68, 1.0
	v_fmac_f32_e32 v68, v70, v68
	v_fma_f32 v76, -v66, v68, 1.0
	v_fma_f32 v71, v76, v68, v68
	v_fma_f32 v67, -v66, v71, 1.0
	v_fma_f32 v67, v67, v68, v71
	v_div_fixup_f32 v76, v67, v66, 1.0
	v_lshl_add_u64 v[66:67], v[118:119], 0, v[86:87]
	v_lshl_add_u64 v[70:71], v[66:67], 0, v[120:121]
	v_cvt_pk_bf16_f32 v66, v79, v78
	v_cvt_pk_bf16_f32 v67, v73, v72
	v_cvt_pk_bf16_f32 v68, v75, v74
	v_cvt_pk_bf16_f32 v69, v76, v69
; __device__ __forceinline__ u32x4 pack8(f32x4 v0, f32x4 v1) { u32x4 o; o.x = pkbf(v0.x, v0.y); o.y = pkbf(v0.z, v0.w); o.z = pkbf(v1.x, v1.y); o.w = pkbf(v1.z, v1.w); return o; }
; __device__ __forceinline__ f32x4 sig4(f32x4 v) { return (f32x4){sigmoidf_(v.x), sigmoidf_(v.y), sigmoidf_(v.z), sigmoidf_(v.w)}; }
;     __device__ __forceinline__ void operator()(int row, int col, f32x4 v0, f32x4 v1) const { *(u32x4*)(G + (size_t)row * 1024 + col) = pack8(v0, v1); }
;     __device__ __forceinline__ void operator()(const pg8::f32x4 (&acc)[2][2][4][2], const pg8::Unit& u, int wr, int wc, int fr, int fq) const {
;         const int row0 = u.pm * 256 + wr * 64 + fr, col0 = u.pn * 256 + wc * 32 + 8 * fq;
; #pragma unroll
;         for (int ai = 0; ai < 2; ++ai)
; #pragma unroll
;             for (int m = 0; m < 4; ++m)
; #pragma unroll
;                 for (int bj = 0; bj < 2; ++bj) { op(row0 + ai * 128 + m * 16, col0 + bj * 128, acc[ai][bj][m][0], acc[ai][bj][m][1]); asm volatile("" ::: "memory"); }
;     __device__ __forceinline__ void operator()(int row, int col, f32x4 v0, f32x4 v1) const {
;         const f32x4 b0 = *(const f32x4*)(a0 + col), b1 = *(const f32x4*)(a0 + col + 4);
;         v0 = sig4(v0 + b0); v1 = sig4(v1 + b1);
;         bf16_t* dst = (col < 1024 ? A0 : A1) + (size_t)row * 1024 + (col & 1023);
;         *(u32x4*)dst = pack8(v0, v1);
	global_store_dwordx4 v[70:71], v[66:69], off
	s_nop 1
	v_lshl_add_u64 v[66:67], v[148:149], 0, s[90:91]
	v_pk_add_f32 v[58:59], v[58:59], v[204:205]
	v_pk_add_f32 v[62:63], v[62:63], v[200:201]
	v_pk_add_f32 v[64:65], v[64:65], v[202:203]
	v_mul_f32_e32 v62, 0xbfb8aa3b, v62
	v_mul_f32_e32 v63, 0xbfb8aa3b, v63
	v_exp_f32_e32 v62, v62
	v_exp_f32_e32 v63, v63
	v_mul_f32_e32 v58, 0xbfb8aa3b, v58
	v_mul_f32_e32 v59, 0xbfb8aa3b, v59
	v_exp_f32_e32 v58, v58
	v_pk_add_f32 v[62:63], v[62:63], 1.0 op_sel_hi:[1,0]
	v_exp_f32_e32 v59, v59
	v_rcp_f32_e32 v73, v63
	v_pk_add_f32 v[58:59], v[58:59], 1.0 op_sel_hi:[1,0]
	v_pk_add_f32 v[60:61], v[60:61], v[206:207]
	v_fma_f32 v74, -v63, v73, 1.0
	v_fmac_f32_e32 v73, v74, v73
	v_fma_f32 v76, -v63, v73, 1.0
	v_fma_f32 v75, v76, v73, v73
	v_fma_f32 v72, -v63, v75, 1.0
	v_fma_f32 v72, v72, v73, v75
	v_div_fixup_f32 v72, v72, v63, 1.0
	v_rcp_f32_e32 v73, v62
	s_nop 0
	v_fma_f32 v74, -v62, v73, 1.0
	v_fmac_f32_e32 v73, v74, v73
	v_fma_f32 v76, -v62, v73, 1.0
	v_fma_f32 v75, v76, v73, v73
	v_fma_f32 v63, -v62, v75, 1.0
	v_fma_f32 v63, v63, v73, v75
	v_div_fixup_f32 v73, v63, v62, 1.0
	v_mul_f32_e32 v62, 0xbfb8aa3b, v64
	v_mul_f32_e32 v63, 0xbfb8aa3b, v65
	v_exp_f32_e32 v62, v62
	v_exp_f32_e32 v63, v63
	s_nop 0
	v_pk_add_f32 v[62:63], v[62:63], 1.0 op_sel_hi:[1,0]
	s_nop 0
	v_rcp_f32_e32 v65, v63
	s_nop 0
	v_fma_f32 v74, -v63, v65, 1.0
	v_fmac_f32_e32 v65, v74, v65
	v_fma_f32 v76, -v63, v65, 1.0
	v_fma_f32 v75, v76, v65, v65
	v_fma_f32 v64, -v63, v75, 1.0
	v_fma_f32 v64, v64, v65, v75
	v_div_fixup_f32 v64, v64, v63, 1.0
	v_rcp_f32_e32 v65, v62
	s_nop 0
	v_fma_f32 v74, -v62, v65, 1.0
	v_fmac_f32_e32 v65, v74, v65
	v_fma_f32 v76, -v62, v65, 1.0
	v_fma_f32 v75, v76, v65, v65
	v_fma_f32 v63, -v62, v75, 1.0
	v_fma_f32 v63, v63, v65, v75
	v_div_fixup_f32 v65, v63, v62, 1.0
	v_rcp_f32_e32 v63, v59
	s_nop 0
	v_fma_f32 v68, -v59, v63, 1.0
	v_fmac_f32_e32 v63, v68, v63
	v_fma_f32 v70, -v59, v63, 1.0
	v_fma_f32 v69, v70, v63, v63
	v_fma_f32 v62, -v59, v69, 1.0
	v_fma_f32 v62, v62, v63, v69
	v_div_fixup_f32 v68, v62, v59, 1.0
	v_rcp_f32_e32 v62, v58
	s_nop 0
	v_fma_f32 v63, -v58, v62, 1.0
	v_fmac_f32_e32 v62, v63, v62
	v_fma_f32 v70, -v58, v62, 1.0
	v_fma_f32 v69, v70, v62, v62
	v_fma_f32 v59, -v58, v69, 1.0
	v_fma_f32 v59, v59, v62, v69
	v_div_fixup_f32 v69, v59, v58, 1.0
	v_mul_f32_e32 v58, 0xbfb8aa3b, v60
	v_mul_f32_e32 v59, 0xbfb8aa3b, v61
	v_exp_f32_e32 v58, v58
	v_exp_f32_e32 v59, v59
	s_nop 0
	v_pk_add_f32 v[58:59], v[58:59], 1.0 op_sel_hi:[1,0]
	s_nop 0
	v_rcp_f32_e32 v61, v59
	s_nop 0
	v_fma_f32 v62, -v59, v61, 1.0
	v_fmac_f32_e32 v61, v62, v61
	v_fma_f32 v70, -v59, v61, 1.0
	v_fma_f32 v63, v70, v61, v61
	v_fma_f32 v60, -v59, v63, 1.0
	v_fma_f32 v60, v60, v61, v63
	v_div_fixup_f32 v61, v60, v59, 1.0
	v_rcp_f32_e32 v60, v58
	s_nop 0
	v_fma_f32 v62, -v58, v60, 1.0
	v_fmac_f32_e32 v60, v62, v60
	v_fma_f32 v70, -v58, v60, 1.0
	v_fma_f32 v63, v70, v60, v60
	v_fma_f32 v59, -v58, v63, 1.0
	v_fma_f32 v59, v59, v60, v63
	v_div_fixup_f32 v70, v59, v58, 1.0
	v_lshl_add_u64 v[58:59], v[126:127], 0, v[66:67]
	v_lshl_add_u64 v[62:63], v[58:59], 0, v[0:1]
	v_cvt_pk_bf16_f32 v58, v73, v72
	v_cvt_pk_bf16_f32 v59, v65, v64
	v_cvt_pk_bf16_f32 v60, v69, v68
	v_cvt_pk_bf16_f32 v61, v70, v61
	global_store_dwordx4 v[62:63], v[58:61], off
	v_pk_add_f32 v[50:51], v[50:51], v[212:213]
	v_pk_add_f32 v[54:55], v[54:55], v[208:209]
	v_pk_add_f32 v[56:57], v[56:57], v[210:211]
	v_mul_f32_e32 v54, 0xbfb8aa3b, v54
	v_mul_f32_e32 v55, 0xbfb8aa3b, v55
	v_exp_f32_e32 v54, v54
	v_exp_f32_e32 v55, v55
	v_mul_f32_e32 v50, 0xbfb8aa3b, v50
	v_mul_f32_e32 v51, 0xbfb8aa3b, v51
	v_exp_f32_e32 v50, v50
	v_pk_add_f32 v[54:55], v[54:55], 1.0 op_sel_hi:[1,0]
	v_exp_f32_e32 v51, v51
	v_rcp_f32_e32 v63, v55
	v_pk_add_f32 v[50:51], v[50:51], 1.0 op_sel_hi:[1,0]
	v_pk_add_f32 v[52:53], v[52:53], v[214:215]
	v_fma_f32 v64, -v55, v63, 1.0
	v_fmac_f32_e32 v63, v64, v63
	v_fma_f32 v68, -v55, v63, 1.0
	v_fma_f32 v65, v68, v63, v63
	v_fma_f32 v62, -v55, v65, 1.0
	v_fma_f32 v62, v62, v63, v65
	v_div_fixup_f32 v62, v62, v55, 1.0
	v_rcp_f32_e32 v63, v54
	s_nop 0
	v_fma_f32 v64, -v54, v63, 1.0
	v_fmac_f32_e32 v63, v64, v63
	v_fma_f32 v68, -v54, v63, 1.0
	v_fma_f32 v65, v68, v63, v63
	v_fma_f32 v55, -v54, v65, 1.0
	v_fma_f32 v55, v55, v63, v65
	v_div_fixup_f32 v63, v55, v54, 1.0
	v_mul_f32_e32 v54, 0xbfb8aa3b, v56
	v_mul_f32_e32 v55, 0xbfb8aa3b, v57
	v_exp_f32_e32 v54, v54
	v_exp_f32_e32 v55, v55
	s_nop 0
	v_pk_add_f32 v[54:55], v[54:55], 1.0 op_sel_hi:[1,0]
	s_nop 0
	v_rcp_f32_e32 v57, v55
	s_nop 0
	v_fma_f32 v64, -v55, v57, 1.0
	v_fmac_f32_e32 v57, v64, v57
	v_fma_f32 v68, -v55, v57, 1.0
	v_fma_f32 v65, v68, v57, v57
	v_fma_f32 v56, -v55, v65, 1.0
	v_fma_f32 v56, v56, v57, v65
	v_div_fixup_f32 v56, v56, v55, 1.0
	v_rcp_f32_e32 v57, v54
	s_nop 0
	v_fma_f32 v64, -v54, v57, 1.0
	v_fmac_f32_e32 v57, v64, v57
	v_fma_f32 v68, -v54, v57, 1.0
	v_fma_f32 v65, v68, v57, v57
	v_fma_f32 v55, -v54, v65, 1.0
	v_fma_f32 v55, v55, v57, v65
	v_div_fixup_f32 v57, v55, v54, 1.0
	v_rcp_f32_e32 v55, v51
	s_nop 0
	v_fma_f32 v58, -v51, v55, 1.0
	v_fmac_f32_e32 v55, v58, v55
	v_fma_f32 v60, -v51, v55, 1.0
	v_fma_f32 v59, v60, v55, v55
	v_fma_f32 v54, -v51, v59, 1.0
	v_fma_f32 v54, v54, v55, v59
	v_div_fixup_f32 v58, v54, v51, 1.0
	v_rcp_f32_e32 v54, v50
	s_nop 0
	v_fma_f32 v55, -v50, v54, 1.0
	v_fmac_f32_e32 v54, v55, v54
	v_fma_f32 v60, -v50, v54, 1.0
	v_fma_f32 v59, v60, v54, v54
	v_fma_f32 v51, -v50, v59, 1.0
	v_fma_f32 v51, v51, v54, v59
	v_div_fixup_f32 v59, v51, v50, 1.0
	v_mul_f32_e32 v50, 0xbfb8aa3b, v52
	v_mul_f32_e32 v51, 0xbfb8aa3b, v53
	v_exp_f32_e32 v50, v50
	v_exp_f32_e32 v51, v51
; __device__ __forceinline__ u32x4 pack8(f32x4 v0, f32x4 v1) { u32x4 o; o.x = pkbf(v0.x, v0.y); o.y = pkbf(v0.z, v0.w); o.z = pkbf(v1.x, v1.y); o.w = pkbf(v1.z, v1.w); return o; }
; __device__ __forceinline__ f32x4 sig4(f32x4 v) { return (f32x4){sigmoidf_(v.x), sigmoidf_(v.y), sigmoidf_(v.z), sigmoidf_(v.w)}; }
;     __device__ __forceinline__ void operator()(int row, int col, f32x4 v0, f32x4 v1) const { *(u32x4*)(G + (size_t)row * 1024 + col) = pack8(v0, v1); }
;     __device__ __forceinline__ void operator()(const pg8::f32x4 (&acc)[2][2][4][2], const pg8::Unit& u, int wr, int wc, int fr, int fq) const {
;     ...
;         for (int ai = 0; ai < 2; ++ai)
; #pragma unroll
;             for (int m = 0; m < 4; ++m)
; #pragma unroll
;                 for (int bj = 0; bj < 2; ++bj) { op(row0 + ai * 128 + m * 16, col0 + bj * 128, acc[ai][bj][m][0], acc[ai][bj][m][1]); asm volatile("" ::: "memory"); }
;     __device__ __forceinline__ void operator()(int row, int col, f32x4 v0, f32x4 v1) const {
;         const f32x4 b0 = *(const f32x4*)(a0 + col), b1 = *(const f32x4*)(a0 + col + 4);
;         v0 = sig4(v0 + b0); v1 = sig4(v1 + b1);
;         bf16_t* dst = (col < 1024 ? A0 : A1) + (size_t)row * 1024 + (col & 1023);
;         *(u32x4*)dst = pack8(v0, v1);
;     }
	s_nop 0
	v_pk_add_f32 v[50:51], v[50:51], 1.0 op_sel_hi:[1,0]
	s_nop 0
	v_rcp_f32_e32 v53, v51
	s_nop 0
	v_fma_f32 v54, -v51, v53, 1.0
	v_fmac_f32_e32 v53, v54, v53
	v_fma_f32 v60, -v51, v53, 1.0
	v_fma_f32 v55, v60, v53, v53
	v_fma_f32 v52, -v51, v55, 1.0
	v_fma_f32 v52, v52, v53, v55
	v_div_fixup_f32 v53, v52, v51, 1.0
	v_rcp_f32_e32 v52, v50
	s_mov_b64 s[4:5], 0x48000
	v_fma_f32 v54, -v50, v52, 1.0
	v_fmac_f32_e32 v52, v54, v52
	v_fma_f32 v60, -v50, v52, 1.0
	v_fma_f32 v55, v60, v52, v52
	v_fma_f32 v51, -v50, v55, 1.0
	v_fma_f32 v51, v51, v52, v55
	v_div_fixup_f32 v60, v51, v50, 1.0
	v_lshl_add_u64 v[50:51], v[118:119], 0, v[66:67]
	v_lshl_add_u64 v[54:55], v[50:51], 0, v[120:121]
	v_cvt_pk_bf16_f32 v50, v63, v62
	v_cvt_pk_bf16_f32 v51, v57, v56
	v_cvt_pk_bf16_f32 v52, v59, v58
	v_cvt_pk_bf16_f32 v53, v60, v53
	global_store_dwordx4 v[54:55], v[50:53], off
	s_nop 1
	v_lshl_add_u64 v[50:51], v[148:149], 0, s[4:5]
	v_pk_add_f32 v[42:43], v[42:43], v[204:205]
	v_pk_add_f32 v[46:47], v[46:47], v[200:201]
	v_pk_add_f32 v[48:49], v[48:49], v[202:203]
	v_mul_f32_e32 v46, 0xbfb8aa3b, v46
	v_mul_f32_e32 v47, 0xbfb8aa3b, v47
	v_exp_f32_e32 v46, v46
	v_exp_f32_e32 v47, v47
	v_mul_f32_e32 v42, 0xbfb8aa3b, v42
	v_mul_f32_e32 v43, 0xbfb8aa3b, v43
	v_exp_f32_e32 v42, v42
	v_pk_add_f32 v[46:47], v[46:47], 1.0 op_sel_hi:[1,0]
	v_exp_f32_e32 v43, v43
	v_rcp_f32_e32 v57, v47
	v_pk_add_f32 v[42:43], v[42:43], 1.0 op_sel_hi:[1,0]
	v_pk_add_f32 v[44:45], v[44:45], v[206:207]
	v_fma_f32 v58, -v47, v57, 1.0
	v_fmac_f32_e32 v57, v58, v57
	v_fma_f32 v60, -v47, v57, 1.0
	v_fma_f32 v59, v60, v57, v57
	v_fma_f32 v56, -v47, v59, 1.0
	v_fma_f32 v56, v56, v57, v59
	v_div_fixup_f32 v56, v56, v47, 1.0
	v_rcp_f32_e32 v57, v46
	s_nop 0
	v_fma_f32 v58, -v46, v57, 1.0
	v_fmac_f32_e32 v57, v58, v57
	v_fma_f32 v60, -v46, v57, 1.0
	v_fma_f32 v59, v60, v57, v57
	v_fma_f32 v47, -v46, v59, 1.0
	v_fma_f32 v47, v47, v57, v59
	v_div_fixup_f32 v57, v47, v46, 1.0
	v_mul_f32_e32 v46, 0xbfb8aa3b, v48
	v_mul_f32_e32 v47, 0xbfb8aa3b, v49
	v_exp_f32_e32 v46, v46
	v_exp_f32_e32 v47, v47
	s_nop 0
	v_pk_add_f32 v[46:47], v[46:47], 1.0 op_sel_hi:[1,0]
	s_nop 0
	v_rcp_f32_e32 v49, v47
	s_nop 0
	v_fma_f32 v58, -v47, v49, 1.0
	v_fmac_f32_e32 v49, v58, v49
	v_fma_f32 v60, -v47, v49, 1.0
	v_fma_f32 v59, v60, v49, v49
	v_fma_f32 v48, -v47, v59, 1.0
	v_fma_f32 v48, v48, v49, v59
	v_div_fixup_f32 v48, v48, v47, 1.0
	v_rcp_f32_e32 v49, v46
	s_nop 0
	v_fma_f32 v58, -v46, v49, 1.0
	v_fmac_f32_e32 v49, v58, v49
	v_fma_f32 v60, -v46, v49, 1.0
	v_fma_f32 v59, v60, v49, v49
	v_fma_f32 v47, -v46, v59, 1.0
	v_fma_f32 v47, v47, v49, v59
	v_div_fixup_f32 v49, v47, v46, 1.0
	v_rcp_f32_e32 v47, v43
	s_nop 0
	v_fma_f32 v52, -v43, v47, 1.0
	v_fmac_f32_e32 v47, v52, v47
	v_fma_f32 v54, -v43, v47, 1.0
	v_fma_f32 v53, v54, v47, v47
	v_fma_f32 v46, -v43, v53, 1.0
	v_fma_f32 v46, v46, v47, v53
	v_div_fixup_f32 v52, v46, v43, 1.0
	v_rcp_f32_e32 v46, v42
	s_nop 0
	v_fma_f32 v47, -v42, v46, 1.0
	v_fmac_f32_e32 v46, v47, v46
	v_fma_f32 v54, -v42, v46, 1.0
	v_fma_f32 v53, v54, v46, v46
	v_fma_f32 v43, -v42, v53, 1.0
	v_fma_f32 v43, v43, v46, v53
	v_div_fixup_f32 v53, v43, v42, 1.0
	v_mul_f32_e32 v42, 0xbfb8aa3b, v44
	v_mul_f32_e32 v43, 0xbfb8aa3b, v45
	v_exp_f32_e32 v42, v42
	v_exp_f32_e32 v43, v43
	s_nop 0
	v_pk_add_f32 v[42:43], v[42:43], 1.0 op_sel_hi:[1,0]
	s_nop 0
	v_rcp_f32_e32 v45, v43
	s_nop 0
	v_fma_f32 v46, -v43, v45, 1.0
	v_fmac_f32_e32 v45, v46, v45
	v_fma_f32 v54, -v43, v45, 1.0
	v_fma_f32 v47, v54, v45, v45
	v_fma_f32 v44, -v43, v47, 1.0
	v_fma_f32 v44, v44, v45, v47
	v_div_fixup_f32 v45, v44, v43, 1.0
	v_rcp_f32_e32 v44, v42
	s_nop 0
	v_fma_f32 v46, -v42, v44, 1.0
	v_fmac_f32_e32 v44, v46, v44
	v_fma_f32 v54, -v42, v44, 1.0
	v_fma_f32 v47, v54, v44, v44
	v_fma_f32 v43, -v42, v47, 1.0
	v_fma_f32 v43, v43, v44, v47
	v_div_fixup_f32 v54, v43, v42, 1.0
	v_lshl_add_u64 v[42:43], v[126:127], 0, v[50:51]
	v_lshl_add_u64 v[46:47], v[42:43], 0, v[0:1]
	v_cvt_pk_bf16_f32 v42, v57, v56
	v_cvt_pk_bf16_f32 v43, v49, v48
	v_cvt_pk_bf16_f32 v44, v53, v52
	v_cvt_pk_bf16_f32 v45, v54, v45
	global_store_dwordx4 v[46:47], v[42:45], off
	v_pk_add_f32 v[34:35], v[34:35], v[212:213]
	v_pk_add_f32 v[38:39], v[38:39], v[208:209]
	v_pk_add_f32 v[40:41], v[40:41], v[210:211]
	v_mul_f32_e32 v38, 0xbfb8aa3b, v38
	v_mul_f32_e32 v39, 0xbfb8aa3b, v39
	v_exp_f32_e32 v38, v38
	v_exp_f32_e32 v39, v39
	v_mul_f32_e32 v34, 0xbfb8aa3b, v34
	v_mul_f32_e32 v35, 0xbfb8aa3b, v35
	v_exp_f32_e32 v34, v34
	v_pk_add_f32 v[38:39], v[38:39], 1.0 op_sel_hi:[1,0]
	v_exp_f32_e32 v35, v35
	v_rcp_f32_e32 v47, v39
	v_pk_add_f32 v[34:35], v[34:35], 1.0 op_sel_hi:[1,0]
	v_pk_add_f32 v[36:37], v[36:37], v[214:215]
	v_fma_f32 v48, -v39, v47, 1.0
	v_fmac_f32_e32 v47, v48, v47
	v_fma_f32 v52, -v39, v47, 1.0
	v_fma_f32 v49, v52, v47, v47
	v_fma_f32 v46, -v39, v49, 1.0
	v_fma_f32 v46, v46, v47, v49
	v_div_fixup_f32 v46, v46, v39, 1.0
	v_rcp_f32_e32 v47, v38
	s_nop 0
	v_fma_f32 v48, -v38, v47, 1.0
	v_fmac_f32_e32 v47, v48, v47
	v_fma_f32 v52, -v38, v47, 1.0
	v_fma_f32 v49, v52, v47, v47
	v_fma_f32 v39, -v38, v49, 1.0
	v_fma_f32 v39, v39, v47, v49
	v_div_fixup_f32 v47, v39, v38, 1.0
	v_mul_f32_e32 v38, 0xbfb8aa3b, v40
	v_mul_f32_e32 v39, 0xbfb8aa3b, v41
	v_exp_f32_e32 v38, v38
	v_exp_f32_e32 v39, v39
	s_nop 0
	v_pk_add_f32 v[38:39], v[38:39], 1.0 op_sel_hi:[1,0]
	s_nop 0
	v_rcp_f32_e32 v41, v39
	s_nop 0
	v_fma_f32 v48, -v39, v41, 1.0
	v_fmac_f32_e32 v41, v48, v41
	v_fma_f32 v52, -v39, v41, 1.0
	v_fma_f32 v49, v52, v41, v41
	v_fma_f32 v40, -v39, v49, 1.0
	v_fma_f32 v40, v40, v41, v49
	v_div_fixup_f32 v40, v40, v39, 1.0
	v_rcp_f32_e32 v41, v38
	s_nop 0
	v_fma_f32 v48, -v38, v41, 1.0
; __device__ __forceinline__ u32x4 pack8(f32x4 v0, f32x4 v1) { u32x4 o; o.x = pkbf(v0.x, v0.y); o.y = pkbf(v0.z, v0.w); o.z = pkbf(v1.x, v1.y); o.w = pkbf(v1.z, v1.w); return o; }
; __device__ __forceinline__ f32x4 sig4(f32x4 v) { return (f32x4){sigmoidf_(v.x), sigmoidf_(v.y), sigmoidf_(v.z), sigmoidf_(v.w)}; }
;     __device__ __forceinline__ void operator()(int row, int col, f32x4 v0, f32x4 v1) const { *(u32x4*)(G + (size_t)row * 1024 + col) = pack8(v0, v1); }
;     __device__ __forceinline__ void operator()(const pg8::f32x4 (&acc)[2][2][4][2], const pg8::Unit& u, int wr, int wc, int fr, int fq) const {
;     ...
;         for (int ai = 0; ai < 2; ++ai)
; #pragma unroll
;             for (int m = 0; m < 4; ++m)
; #pragma unroll
;                 for (int bj = 0; bj < 2; ++bj) { op(row0 + ai * 128 + m * 16, col0 + bj * 128, acc[ai][bj][m][0], acc[ai][bj][m][1]); asm volatile("" ::: "memory"); }
;     __device__ __forceinline__ void operator()(int row, int col, f32x4 v0, f32x4 v1) const {
;         const f32x4 b0 = *(const f32x4*)(a0 + col), b1 = *(const f32x4*)(a0 + col + 4);
;         v0 = sig4(v0 + b0); v1 = sig4(v1 + b1);
;         bf16_t* dst = (col < 1024 ? A0 : A1) + (size_t)row * 1024 + (col & 1023);
;         *(u32x4*)dst = pack8(v0, v1);
;     }
	v_fmac_f32_e32 v41, v48, v41
	v_fma_f32 v52, -v38, v41, 1.0
	v_fma_f32 v49, v52, v41, v41
	v_fma_f32 v39, -v38, v49, 1.0
	v_fma_f32 v39, v39, v41, v49
	v_div_fixup_f32 v41, v39, v38, 1.0
	v_rcp_f32_e32 v39, v35
	s_nop 0
	v_fma_f32 v42, -v35, v39, 1.0
	v_fmac_f32_e32 v39, v42, v39
	v_fma_f32 v44, -v35, v39, 1.0
	v_fma_f32 v43, v44, v39, v39
	v_fma_f32 v38, -v35, v43, 1.0
	v_fma_f32 v38, v38, v39, v43
	v_div_fixup_f32 v42, v38, v35, 1.0
	v_rcp_f32_e32 v38, v34
	s_nop 0
	v_fma_f32 v39, -v34, v38, 1.0
	v_fmac_f32_e32 v38, v39, v38
	v_fma_f32 v44, -v34, v38, 1.0
	v_fma_f32 v43, v44, v38, v38
	v_fma_f32 v35, -v34, v43, 1.0
	v_fma_f32 v35, v35, v38, v43
	v_div_fixup_f32 v43, v35, v34, 1.0
	v_mul_f32_e32 v34, 0xbfb8aa3b, v36
	v_mul_f32_e32 v35, 0xbfb8aa3b, v37
	v_exp_f32_e32 v34, v34
	v_exp_f32_e32 v35, v35
	s_nop 0
	v_pk_add_f32 v[34:35], v[34:35], 1.0 op_sel_hi:[1,0]
	s_nop 0
	v_rcp_f32_e32 v37, v35
	s_nop 0
	v_fma_f32 v38, -v35, v37, 1.0
	v_fmac_f32_e32 v37, v38, v37
	v_fma_f32 v44, -v35, v37, 1.0
	v_fma_f32 v39, v44, v37, v37
	v_fma_f32 v36, -v35, v39, 1.0
	v_fma_f32 v36, v36, v37, v39
	v_div_fixup_f32 v37, v36, v35, 1.0
	v_rcp_f32_e32 v36, v34
	s_mov_b64 s[4:5], 0x50000
	v_fma_f32 v38, -v34, v36, 1.0
	v_fmac_f32_e32 v36, v38, v36
	v_fma_f32 v44, -v34, v36, 1.0
	v_fma_f32 v39, v44, v36, v36
	v_fma_f32 v35, -v34, v39, 1.0
	v_fma_f32 v35, v35, v36, v39
	v_div_fixup_f32 v44, v35, v34, 1.0
	v_lshl_add_u64 v[34:35], v[118:119], 0, v[50:51]
	v_lshl_add_u64 v[38:39], v[34:35], 0, v[120:121]
	v_cvt_pk_bf16_f32 v34, v47, v46
	v_cvt_pk_bf16_f32 v35, v41, v40
	v_cvt_pk_bf16_f32 v36, v43, v42
	v_cvt_pk_bf16_f32 v37, v44, v37
	global_store_dwordx4 v[38:39], v[34:37], off
	s_nop 1
	v_lshl_add_u64 v[34:35], v[148:149], 0, s[4:5]
	v_pk_add_f32 v[26:27], v[26:27], v[204:205]
	v_pk_add_f32 v[30:31], v[30:31], v[200:201]
	v_pk_add_f32 v[32:33], v[32:33], v[202:203]
	v_mul_f32_e32 v30, 0xbfb8aa3b, v30
	v_mul_f32_e32 v31, 0xbfb8aa3b, v31
	v_exp_f32_e32 v30, v30
	v_exp_f32_e32 v31, v31
	v_mul_f32_e32 v26, 0xbfb8aa3b, v26
	v_mul_f32_e32 v27, 0xbfb8aa3b, v27
	v_exp_f32_e32 v26, v26
	v_pk_add_f32 v[30:31], v[30:31], 1.0 op_sel_hi:[1,0]
	v_exp_f32_e32 v27, v27
	v_rcp_f32_e32 v41, v31
	v_pk_add_f32 v[26:27], v[26:27], 1.0 op_sel_hi:[1,0]
	v_pk_add_f32 v[28:29], v[28:29], v[206:207]
	v_fma_f32 v42, -v31, v41, 1.0
	v_fmac_f32_e32 v41, v42, v41
	v_fma_f32 v44, -v31, v41, 1.0
	v_fma_f32 v43, v44, v41, v41
	v_fma_f32 v40, -v31, v43, 1.0
	v_fma_f32 v40, v40, v41, v43
	v_div_fixup_f32 v40, v40, v31, 1.0
	v_rcp_f32_e32 v41, v30
	s_nop 0
	v_fma_f32 v42, -v30, v41, 1.0
	v_fmac_f32_e32 v41, v42, v41
	v_fma_f32 v44, -v30, v41, 1.0
	v_fma_f32 v43, v44, v41, v41
	v_fma_f32 v31, -v30, v43, 1.0
	v_fma_f32 v31, v31, v41, v43
	v_div_fixup_f32 v41, v31, v30, 1.0
	v_mul_f32_e32 v30, 0xbfb8aa3b, v32
	v_mul_f32_e32 v31, 0xbfb8aa3b, v33
	v_exp_f32_e32 v30, v30
	v_exp_f32_e32 v31, v31
	s_nop 0
	v_pk_add_f32 v[30:31], v[30:31], 1.0 op_sel_hi:[1,0]
	s_nop 0
	v_rcp_f32_e32 v33, v31
	s_nop 0
	v_fma_f32 v42, -v31, v33, 1.0
	v_fmac_f32_e32 v33, v42, v33
	v_fma_f32 v44, -v31, v33, 1.0
	v_fma_f32 v43, v44, v33, v33
	v_fma_f32 v32, -v31, v43, 1.0
	v_fma_f32 v32, v32, v33, v43
	v_div_fixup_f32 v32, v32, v31, 1.0
	v_rcp_f32_e32 v33, v30
	s_nop 0
	v_fma_f32 v42, -v30, v33, 1.0
	v_fmac_f32_e32 v33, v42, v33
	v_fma_f32 v44, -v30, v33, 1.0
	v_fma_f32 v43, v44, v33, v33
	v_fma_f32 v31, -v30, v43, 1.0
	v_fma_f32 v31, v31, v33, v43
	v_div_fixup_f32 v33, v31, v30, 1.0
	v_rcp_f32_e32 v31, v27
	s_nop 0
	v_fma_f32 v36, -v27, v31, 1.0
	v_fmac_f32_e32 v31, v36, v31
	v_fma_f32 v38, -v27, v31, 1.0
	v_fma_f32 v37, v38, v31, v31
	v_fma_f32 v30, -v27, v37, 1.0
	v_fma_f32 v30, v30, v31, v37
	v_div_fixup_f32 v36, v30, v27, 1.0
	v_rcp_f32_e32 v30, v26
	s_nop 0
	v_fma_f32 v31, -v26, v30, 1.0
	v_fmac_f32_e32 v30, v31, v30
	v_fma_f32 v38, -v26, v30, 1.0
	v_fma_f32 v37, v38, v30, v30
	v_fma_f32 v27, -v26, v37, 1.0
	v_fma_f32 v27, v27, v30, v37
	v_div_fixup_f32 v37, v27, v26, 1.0
	v_mul_f32_e32 v26, 0xbfb8aa3b, v28
	v_mul_f32_e32 v27, 0xbfb8aa3b, v29
	v_exp_f32_e32 v26, v26
	v_exp_f32_e32 v27, v27
	s_nop 0
	v_pk_add_f32 v[26:27], v[26:27], 1.0 op_sel_hi:[1,0]
	s_nop 0
	v_rcp_f32_e32 v29, v27
	s_nop 0
	v_fma_f32 v30, -v27, v29, 1.0
	v_fmac_f32_e32 v29, v30, v29
	v_fma_f32 v38, -v27, v29, 1.0
	v_fma_f32 v31, v38, v29, v29
	v_fma_f32 v28, -v27, v31, 1.0
	v_fma_f32 v28, v28, v29, v31
	v_div_fixup_f32 v29, v28, v27, 1.0
	v_rcp_f32_e32 v28, v26
	s_nop 0
	v_fma_f32 v30, -v26, v28, 1.0
	v_fmac_f32_e32 v28, v30, v28
	v_fma_f32 v38, -v26, v28, 1.0
	v_fma_f32 v31, v38, v28, v28
	v_fma_f32 v27, -v26, v31, 1.0
	v_fma_f32 v27, v27, v28, v31
	v_div_fixup_f32 v38, v27, v26, 1.0
	v_lshl_add_u64 v[26:27], v[126:127], 0, v[34:35]
	v_lshl_add_u64 v[30:31], v[26:27], 0, v[0:1]
	v_cvt_pk_bf16_f32 v26, v41, v40
	v_cvt_pk_bf16_f32 v27, v33, v32
	v_cvt_pk_bf16_f32 v28, v37, v36
	v_cvt_pk_bf16_f32 v29, v38, v29
	global_store_dwordx4 v[30:31], v[26:29], off
	v_pk_add_f32 v[18:19], v[18:19], v[212:213]
	v_pk_add_f32 v[22:23], v[22:23], v[208:209]
	v_pk_add_f32 v[24:25], v[24:25], v[210:211]
	v_mul_f32_e32 v22, 0xbfb8aa3b, v22
	v_mul_f32_e32 v23, 0xbfb8aa3b, v23
	v_exp_f32_e32 v22, v22
	v_exp_f32_e32 v23, v23
	v_mul_f32_e32 v18, 0xbfb8aa3b, v18
	v_mul_f32_e32 v19, 0xbfb8aa3b, v19
	v_exp_f32_e32 v18, v18
	v_pk_add_f32 v[22:23], v[22:23], 1.0 op_sel_hi:[1,0]
	v_exp_f32_e32 v19, v19
	v_rcp_f32_e32 v31, v23
	v_pk_add_f32 v[18:19], v[18:19], 1.0 op_sel_hi:[1,0]
	v_pk_add_f32 v[20:21], v[20:21], v[214:215]
	v_fma_f32 v32, -v23, v31, 1.0
	v_fmac_f32_e32 v31, v32, v31
	v_fma_f32 v36, -v23, v31, 1.0
	v_fma_f32 v33, v36, v31, v31
	v_fma_f32 v30, -v23, v33, 1.0
; __device__ __forceinline__ u32x4 pack8(f32x4 v0, f32x4 v1) { u32x4 o; o.x = pkbf(v0.x, v0.y); o.y = pkbf(v0.z, v0.w); o.z = pkbf(v1.x, v1.y); o.w = pkbf(v1.z, v1.w); return o; }
; __device__ __forceinline__ f32x4 sig4(f32x4 v) { return (f32x4){sigmoidf_(v.x), sigmoidf_(v.y), sigmoidf_(v.z), sigmoidf_(v.w)}; }
;     __device__ __forceinline__ void operator()(int row, int col, f32x4 v0, f32x4 v1) const { *(u32x4*)(G + (size_t)row * 1024 + col) = pack8(v0, v1); }
;     __device__ __forceinline__ void operator()(const pg8::f32x4 (&acc)[2][2][4][2], const pg8::Unit& u, int wr, int wc, int fr, int fq) const {
;     ...
;         for (int ai = 0; ai < 2; ++ai)
; #pragma unroll
;             for (int m = 0; m < 4; ++m)
; #pragma unroll
;                 for (int bj = 0; bj < 2; ++bj) { op(row0 + ai * 128 + m * 16, col0 + bj * 128, acc[ai][bj][m][0], acc[ai][bj][m][1]); asm volatile("" ::: "memory"); }
;     __device__ __forceinline__ void operator()(int row, int col, f32x4 v0, f32x4 v1) const {
;         const f32x4 b0 = *(const f32x4*)(a0 + col), b1 = *(const f32x4*)(a0 + col + 4);
;         v0 = sig4(v0 + b0); v1 = sig4(v1 + b1);
;         bf16_t* dst = (col < 1024 ? A0 : A1) + (size_t)row * 1024 + (col & 1023);
;         *(u32x4*)dst = pack8(v0, v1);
;     }
	v_fma_f32 v30, v30, v31, v33
	v_div_fixup_f32 v30, v30, v23, 1.0
	v_rcp_f32_e32 v31, v22
	s_nop 0
	v_fma_f32 v32, -v22, v31, 1.0
	v_fmac_f32_e32 v31, v32, v31
	v_fma_f32 v36, -v22, v31, 1.0
	v_fma_f32 v33, v36, v31, v31
	v_fma_f32 v23, -v22, v33, 1.0
	v_fma_f32 v23, v23, v31, v33
	v_div_fixup_f32 v31, v23, v22, 1.0
	v_mul_f32_e32 v22, 0xbfb8aa3b, v24
	v_mul_f32_e32 v23, 0xbfb8aa3b, v25
	v_exp_f32_e32 v22, v22
	v_exp_f32_e32 v23, v23
	s_nop 0
	v_pk_add_f32 v[22:23], v[22:23], 1.0 op_sel_hi:[1,0]
	s_nop 0
	v_rcp_f32_e32 v25, v23
	s_nop 0
	v_fma_f32 v32, -v23, v25, 1.0
	v_fmac_f32_e32 v25, v32, v25
	v_fma_f32 v36, -v23, v25, 1.0
	v_fma_f32 v33, v36, v25, v25
	v_fma_f32 v24, -v23, v33, 1.0
	v_fma_f32 v24, v24, v25, v33
	v_div_fixup_f32 v24, v24, v23, 1.0
	v_rcp_f32_e32 v25, v22
	s_nop 0
	v_fma_f32 v32, -v22, v25, 1.0
	v_fmac_f32_e32 v25, v32, v25
	v_fma_f32 v36, -v22, v25, 1.0
	v_fma_f32 v33, v36, v25, v25
	v_fma_f32 v23, -v22, v33, 1.0
	v_fma_f32 v23, v23, v25, v33
	v_div_fixup_f32 v25, v23, v22, 1.0
	v_rcp_f32_e32 v23, v19
	s_nop 0
	v_fma_f32 v26, -v19, v23, 1.0
	v_fmac_f32_e32 v23, v26, v23
	v_fma_f32 v28, -v19, v23, 1.0
	v_fma_f32 v27, v28, v23, v23
	v_fma_f32 v22, -v19, v27, 1.0
	v_fma_f32 v22, v22, v23, v27
	v_div_fixup_f32 v26, v22, v19, 1.0
	v_rcp_f32_e32 v22, v18
	s_nop 0
	v_fma_f32 v23, -v18, v22, 1.0
	v_fmac_f32_e32 v22, v23, v22
	v_fma_f32 v28, -v18, v22, 1.0
	v_fma_f32 v27, v28, v22, v22
	v_fma_f32 v19, -v18, v27, 1.0
	v_fma_f32 v19, v19, v22, v27
	v_div_fixup_f32 v27, v19, v18, 1.0
	v_mul_f32_e32 v18, 0xbfb8aa3b, v20
	v_mul_f32_e32 v19, 0xbfb8aa3b, v21
	v_exp_f32_e32 v18, v18
	v_exp_f32_e32 v19, v19
	s_nop 0
	v_pk_add_f32 v[18:19], v[18:19], 1.0 op_sel_hi:[1,0]
	s_nop 0
	v_rcp_f32_e32 v21, v19
	s_nop 0
	v_fma_f32 v22, -v19, v21, 1.0
	v_fmac_f32_e32 v21, v22, v21
	v_fma_f32 v28, -v19, v21, 1.0
	v_fma_f32 v23, v28, v21, v21
	v_fma_f32 v20, -v19, v23, 1.0
	v_fma_f32 v20, v20, v21, v23
	v_div_fixup_f32 v21, v20, v19, 1.0
	v_rcp_f32_e32 v20, v18
	s_mov_b64 s[4:5], 0x58000
	v_fma_f32 v22, -v18, v20, 1.0
	v_fmac_f32_e32 v20, v22, v20
	v_fma_f32 v28, -v18, v20, 1.0
	v_fma_f32 v23, v28, v20, v20
	v_fma_f32 v19, -v18, v23, 1.0
	v_fma_f32 v19, v19, v20, v23
	v_div_fixup_f32 v28, v19, v18, 1.0
	v_lshl_add_u64 v[18:19], v[118:119], 0, v[34:35]
	v_lshl_add_u64 v[22:23], v[18:19], 0, v[120:121]
	v_cvt_pk_bf16_f32 v18, v31, v30
	v_cvt_pk_bf16_f32 v19, v25, v24
	v_cvt_pk_bf16_f32 v20, v27, v26
	v_cvt_pk_bf16_f32 v21, v28, v21
	global_store_dwordx4 v[22:23], v[18:21], off
	s_nop 1
	v_lshl_add_u64 v[18:19], v[148:149], 0, s[4:5]
	v_pk_add_f32 v[10:11], v[10:11], v[204:205]
	v_pk_add_f32 v[14:15], v[14:15], v[200:201]
	v_pk_add_f32 v[16:17], v[16:17], v[202:203]
	v_mul_f32_e32 v14, 0xbfb8aa3b, v14
	v_mul_f32_e32 v15, 0xbfb8aa3b, v15
	v_exp_f32_e32 v14, v14
	v_exp_f32_e32 v15, v15
	v_mul_f32_e32 v10, 0xbfb8aa3b, v10
	v_mul_f32_e32 v11, 0xbfb8aa3b, v11
	v_exp_f32_e32 v10, v10
	v_pk_add_f32 v[14:15], v[14:15], 1.0 op_sel_hi:[1,0]
	v_exp_f32_e32 v11, v11
	v_rcp_f32_e32 v25, v15
	v_pk_add_f32 v[10:11], v[10:11], 1.0 op_sel_hi:[1,0]
	v_pk_add_f32 v[12:13], v[12:13], v[206:207]
	v_fma_f32 v26, -v15, v25, 1.0
	v_fmac_f32_e32 v25, v26, v25
	v_fma_f32 v28, -v15, v25, 1.0
	v_fma_f32 v27, v28, v25, v25
	v_fma_f32 v24, -v15, v27, 1.0
	v_fma_f32 v24, v24, v25, v27
	v_div_fixup_f32 v24, v24, v15, 1.0
	v_rcp_f32_e32 v25, v14
	s_nop 0
	v_fma_f32 v26, -v14, v25, 1.0
	v_fmac_f32_e32 v25, v26, v25
	v_fma_f32 v28, -v14, v25, 1.0
	v_fma_f32 v27, v28, v25, v25
	v_fma_f32 v15, -v14, v27, 1.0
	v_fma_f32 v15, v15, v25, v27
	v_div_fixup_f32 v25, v15, v14, 1.0
	v_mul_f32_e32 v14, 0xbfb8aa3b, v16
	v_mul_f32_e32 v15, 0xbfb8aa3b, v17
	v_exp_f32_e32 v14, v14
	v_exp_f32_e32 v15, v15
	s_nop 0
	v_pk_add_f32 v[14:15], v[14:15], 1.0 op_sel_hi:[1,0]
	s_nop 0
	v_rcp_f32_e32 v17, v15
	s_nop 0
	v_fma_f32 v26, -v15, v17, 1.0
	v_fmac_f32_e32 v17, v26, v17
	v_fma_f32 v28, -v15, v17, 1.0
	v_fma_f32 v27, v28, v17, v17
	v_fma_f32 v16, -v15, v27, 1.0
	v_fma_f32 v16, v16, v17, v27
	v_div_fixup_f32 v16, v16, v15, 1.0
	v_rcp_f32_e32 v17, v14
	s_nop 0
	v_fma_f32 v26, -v14, v17, 1.0
	v_fmac_f32_e32 v17, v26, v17
	v_fma_f32 v28, -v14, v17, 1.0
	v_fma_f32 v27, v28, v17, v17
	v_fma_f32 v15, -v14, v27, 1.0
	v_fma_f32 v15, v15, v17, v27
	v_div_fixup_f32 v17, v15, v14, 1.0
	v_rcp_f32_e32 v15, v11
	s_nop 0
	v_fma_f32 v20, -v11, v15, 1.0
	v_fmac_f32_e32 v15, v20, v15
	v_fma_f32 v22, -v11, v15, 1.0
	v_fma_f32 v21, v22, v15, v15
; #define PG8_BAR __builtin_amdgcn_s_barrier()
; __device__ __forceinline__ u32x4 pack8(f32x4 v0, f32x4 v1) { u32x4 o; o.x = pkbf(v0.x, v0.y); o.y = pkbf(v0.z, v0.w); o.z = pkbf(v1.x, v1.y); o.w = pkbf(v1.z, v1.w); return o; }
; __device__ __forceinline__ f32x4 sig4(f32x4 v) { return (f32x4){sigmoidf_(v.x), sigmoidf_(v.y), sigmoidf_(v.z), sigmoidf_(v.w)}; }
;     __device__ __forceinline__ void operator()(int row, int col, f32x4 v0, f32x4 v1) const { *(u32x4*)(G + (size_t)row * 1024 + col) = pack8(v0, v1); }
; template <class Epi, class Sched, bool ALIGN_EPI = false, bool SP2 = false>
; __device__ __forceinline__ void gemm_phase(PG8_LAS unsigned char* lds, const Gemm g, const Sched& S, const Epi& E, const int tid_in) {
;     ...
;         if constexpr (ALIGN_EPI) { if (wr == 0) PG8_BAR; }
;         if constexpr (!Epi::AFTER_DRAIN) { E(acc, cur, wr, wc, fr, fq); S.done(cur); }
;         if (!has_next) break;
; #pragma unroll
;         for (int a = 0; a < 2; ++a)
; #pragma unroll
;             for (int b = 0; b < 2; ++b)
; #pragma unroll
;                 for (int m = 0; m < 4; ++m)
; #pragma unroll
;                     for (int n = 0; n < 2; ++n) acc[a][b][m][n] = (f32x4){0.f, 0.f, 0.f, 0.f};
;         cur = nxt; cA = nA; cB = nB; ++ui;
;         if constexpr (ALIGN_EPI) { if (wr == 1) PG8_BAR; }
;     }
;     __device__ __forceinline__ void operator()(const pg8::f32x4 (&acc)[2][2][4][2], const pg8::Unit& u, int wr, int wc, int fr, int fq) const {
;     ...
;         for (int ai = 0; ai < 2; ++ai)
; #pragma unroll
;             for (int m = 0; m < 4; ++m)
; #pragma unroll
;                 for (int bj = 0; bj < 2; ++bj) { op(row0 + ai * 128 + m * 16, col0 + bj * 128, acc[ai][bj][m][0], acc[ai][bj][m][1]); asm volatile("" ::: "memory"); }
;     __device__ __forceinline__ void operator()(int row, int col, f32x4 v0, f32x4 v1) const {
;         const f32x4 b0 = *(const f32x4*)(a0 + col), b1 = *(const f32x4*)(a0 + col + 4);
;         v0 = sig4(v0 + b0); v1 = sig4(v1 + b1);
;         bf16_t* dst = (col < 1024 ? A0 : A1) + (size_t)row * 1024 + (col & 1023);
;         *(u32x4*)dst = pack8(v0, v1);
;     }
	v_fma_f32 v14, -v11, v21, 1.0
	v_fma_f32 v14, v14, v15, v21
	v_div_fixup_f32 v20, v14, v11, 1.0
	v_rcp_f32_e32 v14, v10
	s_nop 0
	v_fma_f32 v15, -v10, v14, 1.0
	v_fmac_f32_e32 v14, v15, v14
	v_fma_f32 v22, -v10, v14, 1.0
	v_fma_f32 v21, v22, v14, v14
	v_fma_f32 v11, -v10, v21, 1.0
	v_fma_f32 v11, v11, v14, v21
	v_div_fixup_f32 v21, v11, v10, 1.0
	v_mul_f32_e32 v10, 0xbfb8aa3b, v12
	v_mul_f32_e32 v11, 0xbfb8aa3b, v13
	v_exp_f32_e32 v10, v10
	v_exp_f32_e32 v11, v11
	s_nop 0
	v_pk_add_f32 v[10:11], v[10:11], 1.0 op_sel_hi:[1,0]
	s_nop 0
	v_rcp_f32_e32 v13, v11
	s_nop 0
	v_fma_f32 v14, -v11, v13, 1.0
	v_fmac_f32_e32 v13, v14, v13
	v_fma_f32 v22, -v11, v13, 1.0
	v_fma_f32 v15, v22, v13, v13
	v_fma_f32 v12, -v11, v15, 1.0
	v_fma_f32 v12, v12, v13, v15
	v_div_fixup_f32 v13, v12, v11, 1.0
	v_rcp_f32_e32 v12, v10
	s_nop 0
	v_fma_f32 v14, -v10, v12, 1.0
	v_fmac_f32_e32 v12, v14, v12
	v_fma_f32 v22, -v10, v12, 1.0
	v_fma_f32 v15, v22, v12, v12
	v_fma_f32 v11, -v10, v15, 1.0
	v_fma_f32 v11, v11, v12, v15
	v_div_fixup_f32 v22, v11, v10, 1.0
	v_lshl_add_u64 v[10:11], v[126:127], 0, v[18:19]
	v_lshl_add_u64 v[14:15], v[10:11], 0, v[0:1]
	v_cvt_pk_bf16_f32 v10, v25, v24
	v_cvt_pk_bf16_f32 v11, v17, v16
	v_cvt_pk_bf16_f32 v12, v21, v20
	v_cvt_pk_bf16_f32 v13, v22, v13
	global_store_dwordx4 v[14:15], v[10:13], off
	v_pk_add_f32 v[2:3], v[2:3], v[212:213]
	v_pk_add_f32 v[6:7], v[6:7], v[208:209]
	v_pk_add_f32 v[8:9], v[8:9], v[210:211]
	v_mul_f32_e32 v0, 0xbfb8aa3b, v6
	v_exp_f32_e32 v6, v0
	v_mul_f32_e32 v0, 0xbfb8aa3b, v7
	v_exp_f32_e32 v7, v0
	v_mul_f32_e32 v2, 0xbfb8aa3b, v2
	v_mul_f32_e32 v3, 0xbfb8aa3b, v3
	v_exp_f32_e32 v2, v2
	v_pk_add_f32 v[6:7], v[6:7], 1.0 op_sel_hi:[1,0]
	v_exp_f32_e32 v3, v3
	v_rcp_f32_e32 v14, v7
	v_pk_add_f32 v[2:3], v[2:3], 1.0 op_sel_hi:[1,0]
	v_pk_add_f32 v[4:5], v[4:5], v[214:215]
	v_fma_f32 v15, -v7, v14, 1.0
	v_fmac_f32_e32 v14, v15, v14
	v_fma_f32 v17, -v7, v14, 1.0
	v_fma_f32 v16, v17, v14, v14
	v_fma_f32 v0, -v7, v16, 1.0
	v_fma_f32 v0, v0, v14, v16
	v_div_fixup_f32 v0, v0, v7, 1.0
	v_rcp_f32_e32 v14, v6
	s_nop 0
	v_fma_f32 v15, -v6, v14, 1.0
	v_fmac_f32_e32 v14, v15, v14
	v_fma_f32 v17, -v6, v14, 1.0
	v_fma_f32 v16, v17, v14, v14
	v_fma_f32 v7, -v6, v16, 1.0
	v_fma_f32 v7, v7, v14, v16
	v_div_fixup_f32 v14, v7, v6, 1.0
	v_mul_f32_e32 v6, 0xbfb8aa3b, v8
	v_mul_f32_e32 v7, 0xbfb8aa3b, v9
	v_exp_f32_e32 v6, v6
	v_exp_f32_e32 v7, v7
	s_nop 0
	v_pk_add_f32 v[6:7], v[6:7], 1.0 op_sel_hi:[1,0]
	s_nop 0
	v_rcp_f32_e32 v9, v7
	s_nop 0
	v_fma_f32 v15, -v7, v9, 1.0
	v_fmac_f32_e32 v9, v15, v9
	v_fma_f32 v17, -v7, v9, 1.0
	v_fma_f32 v16, v17, v9, v9
	v_fma_f32 v8, -v7, v16, 1.0
	v_fma_f32 v8, v8, v9, v16
	v_div_fixup_f32 v8, v8, v7, 1.0
	v_rcp_f32_e32 v9, v6
	s_nop 0
	v_fma_f32 v15, -v6, v9, 1.0
	v_fmac_f32_e32 v9, v15, v9
	v_fma_f32 v17, -v6, v9, 1.0
	v_fma_f32 v16, v17, v9, v9
	v_fma_f32 v7, -v6, v16, 1.0
	v_fma_f32 v7, v7, v9, v16
	v_div_fixup_f32 v9, v7, v6, 1.0
	v_rcp_f32_e32 v7, v3
	s_nop 0
	v_fma_f32 v10, -v3, v7, 1.0
	v_fmac_f32_e32 v7, v10, v7
	v_fma_f32 v12, -v3, v7, 1.0
	v_fma_f32 v11, v12, v7, v7
	v_fma_f32 v6, -v3, v11, 1.0
	v_fma_f32 v6, v6, v7, v11
	v_div_fixup_f32 v10, v6, v3, 1.0
	v_rcp_f32_e32 v6, v2
	s_nop 0
	v_fma_f32 v7, -v2, v6, 1.0
	v_fmac_f32_e32 v6, v7, v6
	v_fma_f32 v12, -v2, v6, 1.0
	v_fma_f32 v11, v12, v6, v6
	v_fma_f32 v3, -v2, v11, 1.0
	v_fma_f32 v3, v3, v6, v11
	v_div_fixup_f32 v11, v3, v2, 1.0
	v_mul_f32_e32 v2, 0xbfb8aa3b, v4
	v_mul_f32_e32 v3, 0xbfb8aa3b, v5
	v_exp_f32_e32 v2, v2
	v_exp_f32_e32 v3, v3
	s_nop 0
	v_pk_add_f32 v[2:3], v[2:3], 1.0 op_sel_hi:[1,0]
	s_nop 0
	v_rcp_f32_e32 v5, v3
	s_nop 0
	v_fma_f32 v6, -v3, v5, 1.0
	v_fmac_f32_e32 v5, v6, v5
	v_fma_f32 v12, -v3, v5, 1.0
	v_fma_f32 v7, v12, v5, v5
	v_fma_f32 v4, -v3, v7, 1.0
	v_fma_f32 v4, v4, v5, v7
	v_div_fixup_f32 v5, v4, v3, 1.0
	v_rcp_f32_e32 v4, v2
	s_mov_b64 s[4:5], -1
	v_fma_f32 v6, -v2, v4, 1.0
	v_fmac_f32_e32 v4, v6, v4
	v_fma_f32 v12, -v2, v4, 1.0
	v_fma_f32 v7, v12, v4, v4
	v_fma_f32 v3, -v2, v7, 1.0
	v_fma_f32 v3, v3, v4, v7
	v_div_fixup_f32 v12, v3, v2, 1.0
	v_lshl_add_u64 v[2:3], v[118:119], 0, v[18:19]
	v_lshl_add_u64 v[6:7], v[2:3], 0, v[120:121]
	v_cvt_pk_bf16_f32 v2, v14, v0
	v_cvt_pk_bf16_f32 v3, v9, v8
	v_cvt_pk_bf16_f32 v4, v11, v10
	v_cvt_pk_bf16_f32 v5, v12, v5
	global_store_dwordx4 v[6:7], v[2:5], off
	s_and_b64 vcc, exec, s[40:41]
	s_cbranch_vccnz .LBB0_393
	s_andn2_b64 vcc, exec, s[50:51]
	s_cbranch_vccnz .LBB0_392
	s_barrier
	s_branch .LBB0_392
